# v30 + GEMM K-loops: the back-to-back s_setprio 0 / s_setprio 1 pair in the middle of each 32-MFMA compute segment deleted
# baseline (speedup 1.0000x reference)
.LBB0_161:
	s_ashr_i32 s23, s22, 31
	s_lshl_b64 s[8:9], s[22:23], 20
	v_readlane_b32 s20, v254, 38
	v_readlane_b32 s21, v254, 39
	s_add_u32 s8, s20, s8
	s_addc_u32 s9, s21, s9
	s_and_b64 s[20:21], s[40:41], exec
	s_cselect_b32 s13, s9, s43
	s_cselect_b32 s20, s8, s42
	s_ashr_i32 s19, s18, 31
	s_lshl_b64 s[28:29], s[18:19], 20
	v_readlane_b32 s30, v254, 22
	v_readlane_b32 s31, v254, 23
	s_add_u32 s28, s30, s28
	s_addc_u32 s29, s31, s29
	s_and_b64 s[30:31], s[40:41], exec
	s_cselect_b32 s19, s29, s45
	s_cselect_b32 s21, s28, s44
	s_add_u32 s42, s42, 0x80080
	s_addc_u32 s43, s43, 0
	s_add_u32 s23, s44, 0x100
	s_addc_u32 s25, s45, 0
	s_mov_b32 s30, -2
	v_readlane_b32 s52, v255, 20
	v_readlane_b32 s53, v255, 21
	v_readlane_b32 s72, v255, 22
	v_readlane_b32 s73, v255, 23
	s_mov_b64 s[74:75], 0x80
	s_add_u32 s31, s42, 0xfff80080
	s_addc_u32 s44, s43, -1
	s_add_i32 s47, 0, 0x10000
	s_cmp_eq_u32 s30, 28
	s_cselect_b32 s49, s13, s44
	s_cselect_b32 s48, s20, s31
	ds_read_b128 v[144:147], v1
	ds_read_b128 v[148:151], v141
	s_cselect_b32 s45, s19, s25
	s_cselect_b32 s44, s21, s23
	s_add_i32 s31, 0, 0x14000
	ds_read_b128 v[152:155], v1 offset:2048
	ds_read_b128 v[156:159], v141 offset:2048
	ds_read_b128 v[160:163], v1 offset:16384
	ds_read_b128 v[164:167], v141 offset:16384
	ds_read_b128 v[168:171], v1 offset:18432
	ds_read_b128 v[172:175], v141 offset:18432
	s_add_i32 m0, s34, 0xc000
	ds_read_b128 v[176:179], v142
	ds_read_b128 v[184:187], v142 offset:2048
	ds_read_b128 v[188:191], v143
	ds_read_b128 v[192:195], v143 offset:2048
	ds_read_b128 v[196:199], v142 offset:4096
	ds_read_b128 v[200:203], v142 offset:6144
	ds_read_b128 v[204:207], v143 offset:4096
	ds_read_b128 v[208:211], v143 offset:6144
	global_load_lds_dwordx4 v138, s[42:43]
	s_add_i32 m0, s34, 0xe000
	s_nop 0
	global_load_lds_dwordx4 v134, s[42:43]
	s_waitcnt vmcnt(8)
	s_waitcnt lgkmcnt(0)
	s_barrier
	s_setprio 1
	v_mfma_f32_16x16x32_bf16 v[128:131], v[144:147], v[176:179], 0
	v_mfma_f32_16x16x32_bf16 v[124:127], v[152:155], v[176:179], 0
	v_mfma_f32_16x16x32_bf16 v[112:115], v[144:147], v[184:187], 0
	v_mfma_f32_16x16x32_bf16 v[108:111], v[152:155], v[184:187], 0
	v_mfma_f32_16x16x32_bf16 v[96:99], v[144:147], v[196:199], 0
	v_mfma_f32_16x16x32_bf16 v[92:95], v[152:155], v[196:199], 0
	v_mfma_f32_16x16x32_bf16 v[80:83], v[144:147], v[200:203], 0
	v_mfma_f32_16x16x32_bf16 v[76:79], v[152:155], v[200:203], 0
	v_mfma_f32_16x16x32_bf16 v[128:131], v[148:151], v[188:191], v[128:131]
	v_mfma_f32_16x16x32_bf16 v[124:127], v[156:159], v[188:191], v[124:127]
	v_mfma_f32_16x16x32_bf16 v[112:115], v[148:151], v[192:195], v[112:115]
	v_mfma_f32_16x16x32_bf16 v[108:111], v[156:159], v[192:195], v[108:111]
	v_mfma_f32_16x16x32_bf16 v[96:99], v[148:151], v[204:207], v[96:99]
	v_mfma_f32_16x16x32_bf16 v[92:95], v[156:159], v[204:207], v[92:95]
	v_mfma_f32_16x16x32_bf16 v[80:83], v[148:151], v[208:211], v[80:83]
	v_mfma_f32_16x16x32_bf16 v[76:79], v[156:159], v[208:211], v[76:79]
	v_mfma_f32_16x16x32_bf16 v[120:123], v[160:163], v[176:179], 0
	v_mfma_f32_16x16x32_bf16 v[116:119], v[168:171], v[176:179], 0
	v_mfma_f32_16x16x32_bf16 v[104:107], v[160:163], v[184:187], 0
	v_mfma_f32_16x16x32_bf16 v[100:103], v[168:171], v[184:187], 0
	v_mfma_f32_16x16x32_bf16 v[88:91], v[160:163], v[196:199], 0
	v_mfma_f32_16x16x32_bf16 v[84:87], v[168:171], v[196:199], 0
	v_mfma_f32_16x16x32_bf16 v[72:75], v[160:163], v[200:203], 0
	v_mfma_f32_16x16x32_bf16 v[68:71], v[168:171], v[200:203], 0
	v_mfma_f32_16x16x32_bf16 v[120:123], v[164:167], v[188:191], v[120:123]
	v_mfma_f32_16x16x32_bf16 v[116:119], v[172:175], v[188:191], v[116:119]
	v_mfma_f32_16x16x32_bf16 v[104:107], v[164:167], v[192:195], v[104:107]
	v_mfma_f32_16x16x32_bf16 v[100:103], v[172:175], v[192:195], v[100:103]
	v_mfma_f32_16x16x32_bf16 v[88:91], v[164:167], v[204:207], v[88:91]
	v_mfma_f32_16x16x32_bf16 v[84:87], v[172:175], v[204:207], v[84:87]
	v_mfma_f32_16x16x32_bf16 v[72:75], v[164:167], v[208:211], v[72:75]
	v_mfma_f32_16x16x32_bf16 v[68:71], v[172:175], v[208:211], v[68:71]
	s_setprio 0
	s_barrier
	s_add_i32 s47, s47, s33
	s_mov_b32 m0, s47
	ds_read_b128 v[176:179], v142 offset:16384
	ds_read_b128 v[184:187], v142 offset:18432
	ds_read_b128 v[188:191], v143 offset:16384
	ds_read_b128 v[192:195], v143 offset:18432
	ds_read_b128 v[196:199], v142 offset:20480
	ds_read_b128 v[200:203], v142 offset:22528
	ds_read_b128 v[204:207], v143 offset:20480
	ds_read_b128 v[208:211], v143 offset:22528
	global_load_lds_dwordx4 v136, s[44:45]
	s_add_i32 m0, s47, 0x2000
	s_add_u32 s50, s44, 0x80000
	s_addc_u32 s51, s45, 0
	s_add_i32 s31, s31, s33
	global_load_lds_dwordx4 v132, s[44:45]
	s_mov_b32 m0, s31
	s_nop 0
	global_load_lds_dwordx4 v136, s[50:51]
	s_add_i32 m0, s31, 0x2000
	s_nop 0
	global_load_lds_dwordx4 v132, s[50:51]
	s_mov_b32 m0, s34
	s_nop 0
	global_load_lds_dwordx4 v138, s[48:49]
	s_mov_b32 m0, s35
	s_nop 0
	global_load_lds_dwordx4 v134, s[48:49]
	s_waitcnt vmcnt(8)
	s_waitcnt lgkmcnt(0)
	s_barrier
	s_setprio 1
	v_mfma_f32_16x16x32_bf16 v[64:67], v[144:147], v[176:179], 0
	v_mfma_f32_16x16x32_bf16 v[60:63], v[152:155], v[176:179], 0
	v_mfma_f32_16x16x32_bf16 v[48:51], v[144:147], v[184:187], 0
	v_mfma_f32_16x16x32_bf16 v[44:47], v[152:155], v[184:187], 0
	v_mfma_f32_16x16x32_bf16 v[30:33], v[144:147], v[196:199], 0
	v_mfma_f32_16x16x32_bf16 v[26:29], v[152:155], v[196:199], 0
	v_mfma_f32_16x16x32_bf16 v[14:17], v[144:147], v[200:203], 0
	v_mfma_f32_16x16x32_bf16 v[10:13], v[152:155], v[200:203], 0
	v_mfma_f32_16x16x32_bf16 v[64:67], v[148:151], v[188:191], v[64:67]
	v_mfma_f32_16x16x32_bf16 v[60:63], v[156:159], v[188:191], v[60:63]
	v_mfma_f32_16x16x32_bf16 v[48:51], v[148:151], v[192:195], v[48:51]
	v_mfma_f32_16x16x32_bf16 v[44:47], v[156:159], v[192:195], v[44:47]
	v_mfma_f32_16x16x32_bf16 v[30:33], v[148:151], v[204:207], v[30:33]
	v_mfma_f32_16x16x32_bf16 v[26:29], v[156:159], v[204:207], v[26:29]
	v_mfma_f32_16x16x32_bf16 v[14:17], v[148:151], v[208:211], v[14:17]
	v_mfma_f32_16x16x32_bf16 v[10:13], v[156:159], v[208:211], v[10:13]
	v_mfma_f32_16x16x32_bf16 v[56:59], v[160:163], v[176:179], 0
	v_mfma_f32_16x16x32_bf16 v[52:55], v[168:171], v[176:179], 0
	v_mfma_f32_16x16x32_bf16 v[40:43], v[160:163], v[184:187], 0
	v_mfma_f32_16x16x32_bf16 v[36:39], v[168:171], v[184:187], 0
	v_mfma_f32_16x16x32_bf16 v[22:25], v[160:163], v[196:199], 0
	v_mfma_f32_16x16x32_bf16 v[18:21], v[168:171], v[196:199], 0
	v_mfma_f32_16x16x32_bf16 v[6:9], v[160:163], v[200:203], 0
	v_mfma_f32_16x16x32_bf16 v[2:5], v[168:171], v[200:203], 0
	v_mfma_f32_16x16x32_bf16 v[56:59], v[164:167], v[188:191], v[56:59]
	v_mfma_f32_16x16x32_bf16 v[52:55], v[172:175], v[188:191], v[52:55]
	v_mfma_f32_16x16x32_bf16 v[40:43], v[164:167], v[192:195], v[40:43]
	v_mfma_f32_16x16x32_bf16 v[36:39], v[172:175], v[192:195], v[36:39]
	v_mfma_f32_16x16x32_bf16 v[22:25], v[164:167], v[204:207], v[22:25]
	v_mfma_f32_16x16x32_bf16 v[18:21], v[172:175], v[204:207], v[18:21]
	v_mfma_f32_16x16x32_bf16 v[6:9], v[164:167], v[208:211], v[6:9]
	v_mfma_f32_16x16x32_bf16 v[2:5], v[172:175], v[208:211], v[2:5]
	s_setprio 0
	s_barrier
	s_add_i32 s31, 0, 0x18000
	ds_read_b128 v[144:147], v1 offset:32768
	ds_read_b128 v[148:151], v141 offset:32768
	s_add_i32 s47, 0, 0x1c000
	ds_read_b128 v[152:155], v1 offset:34816
	ds_read_b128 v[156:159], v141 offset:34816
	ds_read_b128 v[160:163], v1 offset:49152
	ds_read_b128 v[164:167], v141 offset:49152
	ds_read_b128 v[168:171], v1 offset:51200
	ds_read_b128 v[172:175], v141 offset:51200
	s_mov_b64 s[100:101], s[48:49]
	s_add_u32 s48, s48, 0x80000
	s_addc_u32 s49, s49, 0
	s_mov_b32 m0, s54
	ds_read_b128 v[176:179], v142 offset:32768
	ds_read_b128 v[184:187], v142 offset:34816
	ds_read_b128 v[188:191], v143 offset:32768
	ds_read_b128 v[192:195], v143 offset:34816
	ds_read_b128 v[196:199], v142 offset:36864
	ds_read_b128 v[200:203], v142 offset:38912
	ds_read_b128 v[204:207], v143 offset:36864
	ds_read_b128 v[208:211], v143 offset:38912
	global_load_lds_dwordx4 v138, s[48:49]
	s_mov_b32 m0, s55
	s_nop 0
	global_load_lds_dwordx4 v134, s[48:49]
	s_waitcnt vmcnt(8)
	s_waitcnt lgkmcnt(0)
	s_barrier
	s_setprio 1
	v_mfma_f32_16x16x32_bf16 v[128:131], v[144:147], v[176:179], v[128:131]
	v_mfma_f32_16x16x32_bf16 v[124:127], v[152:155], v[176:179], v[124:127]
	v_mfma_f32_16x16x32_bf16 v[112:115], v[144:147], v[184:187], v[112:115]
	v_mfma_f32_16x16x32_bf16 v[108:111], v[152:155], v[184:187], v[108:111]
	v_mfma_f32_16x16x32_bf16 v[96:99], v[144:147], v[196:199], v[96:99]
	v_mfma_f32_16x16x32_bf16 v[92:95], v[152:155], v[196:199], v[92:95]
	v_mfma_f32_16x16x32_bf16 v[80:83], v[144:147], v[200:203], v[80:83]
	v_mfma_f32_16x16x32_bf16 v[76:79], v[152:155], v[200:203], v[76:79]
	v_mfma_f32_16x16x32_bf16 v[128:131], v[148:151], v[188:191], v[128:131]
	v_mfma_f32_16x16x32_bf16 v[124:127], v[156:159], v[188:191], v[124:127]
	v_mfma_f32_16x16x32_bf16 v[112:115], v[148:151], v[192:195], v[112:115]
	v_mfma_f32_16x16x32_bf16 v[108:111], v[156:159], v[192:195], v[108:111]
	v_mfma_f32_16x16x32_bf16 v[96:99], v[148:151], v[204:207], v[96:99]
	v_mfma_f32_16x16x32_bf16 v[92:95], v[156:159], v[204:207], v[92:95]
	v_mfma_f32_16x16x32_bf16 v[80:83], v[148:151], v[208:211], v[80:83]
	v_mfma_f32_16x16x32_bf16 v[76:79], v[156:159], v[208:211], v[76:79]
	v_mfma_f32_16x16x32_bf16 v[120:123], v[160:163], v[176:179], v[120:123]
	v_mfma_f32_16x16x32_bf16 v[116:119], v[168:171], v[176:179], v[116:119]
	v_mfma_f32_16x16x32_bf16 v[104:107], v[160:163], v[184:187], v[104:107]
	v_mfma_f32_16x16x32_bf16 v[100:103], v[168:171], v[184:187], v[100:103]
	v_mfma_f32_16x16x32_bf16 v[88:91], v[160:163], v[196:199], v[88:91]
	v_mfma_f32_16x16x32_bf16 v[84:87], v[168:171], v[196:199], v[84:87]
	v_mfma_f32_16x16x32_bf16 v[72:75], v[160:163], v[200:203], v[72:75]
	v_mfma_f32_16x16x32_bf16 v[68:71], v[168:171], v[200:203], v[68:71]
	v_mfma_f32_16x16x32_bf16 v[120:123], v[164:167], v[188:191], v[120:123]
	v_mfma_f32_16x16x32_bf16 v[116:119], v[172:175], v[188:191], v[116:119]
	v_mfma_f32_16x16x32_bf16 v[104:107], v[164:167], v[192:195], v[104:107]
	v_mfma_f32_16x16x32_bf16 v[100:103], v[172:175], v[192:195], v[100:103]
	v_mfma_f32_16x16x32_bf16 v[88:91], v[164:167], v[204:207], v[88:91]
	v_mfma_f32_16x16x32_bf16 v[84:87], v[172:175], v[204:207], v[84:87]
	v_mfma_f32_16x16x32_bf16 v[72:75], v[164:167], v[208:211], v[72:75]
	v_mfma_f32_16x16x32_bf16 v[68:71], v[172:175], v[208:211], v[68:71]
	s_setprio 0
	s_barrier
	s_add_i32 s31, s31, s33
	s_add_i32 m0, s31, 0xffffff80
	ds_read_b128 v[176:179], v142 offset:49152
	ds_read_b128 v[184:187], v142 offset:51200
	ds_read_b128 v[188:191], v143 offset:49152
	ds_read_b128 v[192:195], v143 offset:51200
	ds_read_b128 v[196:199], v142 offset:53248
	ds_read_b128 v[200:203], v142 offset:55296
	ds_read_b128 v[204:207], v143 offset:53248
	ds_read_b128 v[208:211], v143 offset:55296
	global_load_lds_dwordx4 v136, s[44:45] offset:128
	s_add_i32 m0, s31, 0x1f80
	s_mov_b64 s[98:99], s[44:45]
	s_add_u32 s44, s44, 0x80080
	s_addc_u32 s45, s45, 0
	s_add_i32 s31, s47, s33
	global_load_lds_dwordx4 v132, s[98:99] offset:128
	s_mov_b32 m0, s31
	s_nop 0
	global_load_lds_dwordx4 v136, s[44:45]
	s_add_i32 m0, s31, 0x2000
	s_nop 0
	global_load_lds_dwordx4 v132, s[44:45]
	s_add_i32 m0, s56, 0xffffff80
	s_nop 0
	global_load_lds_dwordx4 v138, s[100:101] offset:128
	s_add_i32 m0, s57, 0xffffff80
	s_nop 0
	global_load_lds_dwordx4 v134, s[100:101] offset:128
	s_waitcnt vmcnt(8)
	s_waitcnt lgkmcnt(0)
	s_barrier
	s_setprio 1
	v_mfma_f32_16x16x32_bf16 v[64:67], v[144:147], v[176:179], v[64:67]
	v_mfma_f32_16x16x32_bf16 v[60:63], v[152:155], v[176:179], v[60:63]
	v_mfma_f32_16x16x32_bf16 v[48:51], v[144:147], v[184:187], v[48:51]
	v_mfma_f32_16x16x32_bf16 v[44:47], v[152:155], v[184:187], v[44:47]
	v_mfma_f32_16x16x32_bf16 v[30:33], v[144:147], v[196:199], v[30:33]
	v_mfma_f32_16x16x32_bf16 v[26:29], v[152:155], v[196:199], v[26:29]
	v_mfma_f32_16x16x32_bf16 v[14:17], v[144:147], v[200:203], v[14:17]
	v_mfma_f32_16x16x32_bf16 v[10:13], v[152:155], v[200:203], v[10:13]
	v_mfma_f32_16x16x32_bf16 v[64:67], v[148:151], v[188:191], v[64:67]
	v_mfma_f32_16x16x32_bf16 v[60:63], v[156:159], v[188:191], v[60:63]
	v_mfma_f32_16x16x32_bf16 v[48:51], v[148:151], v[192:195], v[48:51]
	v_mfma_f32_16x16x32_bf16 v[44:47], v[156:159], v[192:195], v[44:47]
	v_mfma_f32_16x16x32_bf16 v[30:33], v[148:151], v[204:207], v[30:33]
	v_mfma_f32_16x16x32_bf16 v[26:29], v[156:159], v[204:207], v[26:29]
	v_mfma_f32_16x16x32_bf16 v[14:17], v[148:151], v[208:211], v[14:17]
	v_mfma_f32_16x16x32_bf16 v[10:13], v[156:159], v[208:211], v[10:13]
	v_mfma_f32_16x16x32_bf16 v[56:59], v[160:163], v[176:179], v[56:59]
	v_mfma_f32_16x16x32_bf16 v[52:55], v[168:171], v[176:179], v[52:55]
	v_mfma_f32_16x16x32_bf16 v[40:43], v[160:163], v[184:187], v[40:43]
	v_mfma_f32_16x16x32_bf16 v[36:39], v[168:171], v[184:187], v[36:39]
	v_mfma_f32_16x16x32_bf16 v[22:25], v[160:163], v[196:199], v[22:25]
	v_mfma_f32_16x16x32_bf16 v[18:21], v[168:171], v[196:199], v[18:21]
	v_mfma_f32_16x16x32_bf16 v[6:9], v[160:163], v[200:203], v[6:9]
	v_mfma_f32_16x16x32_bf16 v[2:5], v[168:171], v[200:203], v[2:5]
	v_mfma_f32_16x16x32_bf16 v[56:59], v[164:167], v[188:191], v[56:59]
	v_mfma_f32_16x16x32_bf16 v[52:55], v[172:175], v[188:191], v[52:55]
	v_mfma_f32_16x16x32_bf16 v[40:43], v[164:167], v[192:195], v[40:43]
	v_mfma_f32_16x16x32_bf16 v[36:39], v[172:175], v[192:195], v[36:39]
	v_mfma_f32_16x16x32_bf16 v[22:25], v[164:167], v[204:207], v[22:25]
	v_mfma_f32_16x16x32_bf16 v[18:21], v[172:175], v[204:207], v[18:21]
	v_mfma_f32_16x16x32_bf16 v[6:9], v[164:167], v[208:211], v[6:9]
	v_mfma_f32_16x16x32_bf16 v[2:5], v[172:175], v[208:211], v[2:5]
	s_setprio 0
	s_barrier
	s_add_i32 s30, s30, 2
	s_add_u32 s42, s42, 0x100
	s_addc_u32 s43, s43, 0
	s_add_u32 s23, s23, 0x100
	s_addc_u32 s25, s25, 0
	s_cmp_gt_u32 s30, 29
	s_cbranch_scc1 .Lpeel_done_P1
.LBB0_162:
	s_add_u32 s31, s42, 0xfff80080
	s_addc_u32 s44, s43, -1
	s_add_i32 s47, 0, 0x10000
	s_cmp_eq_u32 s30, 28
	s_cselect_b32 s49, s13, s44
	s_cselect_b32 s48, s20, s31
	ds_read_b128 v[144:147], v1
	ds_read_b128 v[148:151], v141
	s_cselect_b32 s45, s19, s25
	s_cselect_b32 s44, s21, s23
	s_add_i32 s31, 0, 0x14000
	ds_read_b128 v[152:155], v1 offset:2048
	ds_read_b128 v[156:159], v141 offset:2048
	ds_read_b128 v[160:163], v1 offset:16384
	ds_read_b128 v[164:167], v141 offset:16384
	ds_read_b128 v[168:171], v1 offset:18432
	ds_read_b128 v[172:175], v141 offset:18432
	s_add_i32 m0, s34, 0xc000
	ds_read_b128 v[176:179], v142
	ds_read_b128 v[184:187], v142 offset:2048
	ds_read_b128 v[188:191], v143
	ds_read_b128 v[192:195], v143 offset:2048
	ds_read_b128 v[196:199], v142 offset:4096
	ds_read_b128 v[200:203], v142 offset:6144
	ds_read_b128 v[204:207], v143 offset:4096
	ds_read_b128 v[208:211], v143 offset:6144
	global_load_lds_dwordx4 v138, s[42:43]
	s_add_i32 m0, s34, 0xe000
	s_nop 0
	global_load_lds_dwordx4 v134, s[42:43]
	s_waitcnt vmcnt(8)
	s_waitcnt lgkmcnt(0)
	s_barrier
	s_setprio 1
	v_mfma_f32_16x16x32_bf16 v[128:131], v[144:147], v[176:179], v[128:131]
	v_mfma_f32_16x16x32_bf16 v[124:127], v[152:155], v[176:179], v[124:127]
	v_mfma_f32_16x16x32_bf16 v[112:115], v[144:147], v[184:187], v[112:115]
	v_mfma_f32_16x16x32_bf16 v[108:111], v[152:155], v[184:187], v[108:111]
	v_mfma_f32_16x16x32_bf16 v[96:99], v[144:147], v[196:199], v[96:99]
	v_mfma_f32_16x16x32_bf16 v[92:95], v[152:155], v[196:199], v[92:95]
	v_mfma_f32_16x16x32_bf16 v[80:83], v[144:147], v[200:203], v[80:83]
	v_mfma_f32_16x16x32_bf16 v[76:79], v[152:155], v[200:203], v[76:79]
	v_mfma_f32_16x16x32_bf16 v[128:131], v[148:151], v[188:191], v[128:131]
	v_mfma_f32_16x16x32_bf16 v[124:127], v[156:159], v[188:191], v[124:127]
	v_mfma_f32_16x16x32_bf16 v[112:115], v[148:151], v[192:195], v[112:115]
	v_mfma_f32_16x16x32_bf16 v[108:111], v[156:159], v[192:195], v[108:111]
	v_mfma_f32_16x16x32_bf16 v[96:99], v[148:151], v[204:207], v[96:99]
	v_mfma_f32_16x16x32_bf16 v[92:95], v[156:159], v[204:207], v[92:95]
	v_mfma_f32_16x16x32_bf16 v[80:83], v[148:151], v[208:211], v[80:83]
	v_mfma_f32_16x16x32_bf16 v[76:79], v[156:159], v[208:211], v[76:79]
	v_mfma_f32_16x16x32_bf16 v[120:123], v[160:163], v[176:179], v[120:123]
	v_mfma_f32_16x16x32_bf16 v[116:119], v[168:171], v[176:179], v[116:119]
	v_mfma_f32_16x16x32_bf16 v[104:107], v[160:163], v[184:187], v[104:107]
	v_mfma_f32_16x16x32_bf16 v[100:103], v[168:171], v[184:187], v[100:103]
	v_mfma_f32_16x16x32_bf16 v[88:91], v[160:163], v[196:199], v[88:91]
	v_mfma_f32_16x16x32_bf16 v[84:87], v[168:171], v[196:199], v[84:87]
	v_mfma_f32_16x16x32_bf16 v[72:75], v[160:163], v[200:203], v[72:75]
	v_mfma_f32_16x16x32_bf16 v[68:71], v[168:171], v[200:203], v[68:71]
	v_mfma_f32_16x16x32_bf16 v[120:123], v[164:167], v[188:191], v[120:123]
	v_mfma_f32_16x16x32_bf16 v[116:119], v[172:175], v[188:191], v[116:119]
	v_mfma_f32_16x16x32_bf16 v[104:107], v[164:167], v[192:195], v[104:107]
	v_mfma_f32_16x16x32_bf16 v[100:103], v[172:175], v[192:195], v[100:103]
	v_mfma_f32_16x16x32_bf16 v[88:91], v[164:167], v[204:207], v[88:91]
	v_mfma_f32_16x16x32_bf16 v[84:87], v[172:175], v[204:207], v[84:87]
	v_mfma_f32_16x16x32_bf16 v[72:75], v[164:167], v[208:211], v[72:75]
	v_mfma_f32_16x16x32_bf16 v[68:71], v[172:175], v[208:211], v[68:71]
	s_setprio 0
	s_barrier
	s_add_i32 s47, s47, s33
	s_mov_b32 m0, s47
	ds_read_b128 v[176:179], v142 offset:16384
	ds_read_b128 v[184:187], v142 offset:18432
	ds_read_b128 v[188:191], v143 offset:16384
	ds_read_b128 v[192:195], v143 offset:18432
	ds_read_b128 v[196:199], v142 offset:20480
	ds_read_b128 v[200:203], v142 offset:22528
	ds_read_b128 v[204:207], v143 offset:20480
	ds_read_b128 v[208:211], v143 offset:22528
	global_load_lds_dwordx4 v136, s[44:45]
	s_add_i32 m0, s47, 0x2000
	s_add_u32 s50, s44, 0x80000
	s_addc_u32 s51, s45, 0
	s_add_i32 s31, s31, s33
	global_load_lds_dwordx4 v132, s[44:45]
	s_mov_b32 m0, s31
	s_nop 0
	global_load_lds_dwordx4 v136, s[50:51]
	s_add_i32 m0, s31, 0x2000
	s_nop 0
	global_load_lds_dwordx4 v132, s[50:51]
	s_mov_b32 m0, s34
	s_nop 0
	global_load_lds_dwordx4 v138, s[48:49]
	s_mov_b32 m0, s35
	s_nop 0
	global_load_lds_dwordx4 v134, s[48:49]
	s_waitcnt vmcnt(8)
	s_waitcnt lgkmcnt(0)
	s_barrier
	s_setprio 1
	v_mfma_f32_16x16x32_bf16 v[64:67], v[144:147], v[176:179], v[64:67]
	v_mfma_f32_16x16x32_bf16 v[60:63], v[152:155], v[176:179], v[60:63]
	v_mfma_f32_16x16x32_bf16 v[48:51], v[144:147], v[184:187], v[48:51]
	v_mfma_f32_16x16x32_bf16 v[44:47], v[152:155], v[184:187], v[44:47]
	v_mfma_f32_16x16x32_bf16 v[30:33], v[144:147], v[196:199], v[30:33]
	v_mfma_f32_16x16x32_bf16 v[26:29], v[152:155], v[196:199], v[26:29]
	v_mfma_f32_16x16x32_bf16 v[14:17], v[144:147], v[200:203], v[14:17]
	v_mfma_f32_16x16x32_bf16 v[10:13], v[152:155], v[200:203], v[10:13]
	v_mfma_f32_16x16x32_bf16 v[64:67], v[148:151], v[188:191], v[64:67]
	v_mfma_f32_16x16x32_bf16 v[60:63], v[156:159], v[188:191], v[60:63]
	v_mfma_f32_16x16x32_bf16 v[48:51], v[148:151], v[192:195], v[48:51]
	v_mfma_f32_16x16x32_bf16 v[44:47], v[156:159], v[192:195], v[44:47]
	v_mfma_f32_16x16x32_bf16 v[30:33], v[148:151], v[204:207], v[30:33]
	v_mfma_f32_16x16x32_bf16 v[26:29], v[156:159], v[204:207], v[26:29]
	v_mfma_f32_16x16x32_bf16 v[14:17], v[148:151], v[208:211], v[14:17]
	v_mfma_f32_16x16x32_bf16 v[10:13], v[156:159], v[208:211], v[10:13]
	v_mfma_f32_16x16x32_bf16 v[56:59], v[160:163], v[176:179], v[56:59]
	v_mfma_f32_16x16x32_bf16 v[52:55], v[168:171], v[176:179], v[52:55]
	v_mfma_f32_16x16x32_bf16 v[40:43], v[160:163], v[184:187], v[40:43]
	v_mfma_f32_16x16x32_bf16 v[36:39], v[168:171], v[184:187], v[36:39]
	v_mfma_f32_16x16x32_bf16 v[22:25], v[160:163], v[196:199], v[22:25]
	v_mfma_f32_16x16x32_bf16 v[18:21], v[168:171], v[196:199], v[18:21]
	v_mfma_f32_16x16x32_bf16 v[6:9], v[160:163], v[200:203], v[6:9]
	v_mfma_f32_16x16x32_bf16 v[2:5], v[168:171], v[200:203], v[2:5]
	v_mfma_f32_16x16x32_bf16 v[56:59], v[164:167], v[188:191], v[56:59]
	v_mfma_f32_16x16x32_bf16 v[52:55], v[172:175], v[188:191], v[52:55]
	v_mfma_f32_16x16x32_bf16 v[40:43], v[164:167], v[192:195], v[40:43]
	v_mfma_f32_16x16x32_bf16 v[36:39], v[172:175], v[192:195], v[36:39]
	v_mfma_f32_16x16x32_bf16 v[22:25], v[164:167], v[204:207], v[22:25]
	v_mfma_f32_16x16x32_bf16 v[18:21], v[172:175], v[204:207], v[18:21]
	v_mfma_f32_16x16x32_bf16 v[6:9], v[164:167], v[208:211], v[6:9]
	v_mfma_f32_16x16x32_bf16 v[2:5], v[172:175], v[208:211], v[2:5]
	s_setprio 0
	s_barrier
	s_add_i32 s31, 0, 0x18000
	ds_read_b128 v[144:147], v1 offset:32768
	ds_read_b128 v[148:151], v141 offset:32768
	s_add_i32 s47, 0, 0x1c000
	ds_read_b128 v[152:155], v1 offset:34816
	ds_read_b128 v[156:159], v141 offset:34816
	ds_read_b128 v[160:163], v1 offset:49152
	ds_read_b128 v[164:167], v141 offset:49152
	ds_read_b128 v[168:171], v1 offset:51200
	ds_read_b128 v[172:175], v141 offset:51200
	s_mov_b64 s[100:101], s[48:49]
	s_add_u32 s48, s48, 0x80000
	s_addc_u32 s49, s49, 0
	s_mov_b32 m0, s54
	ds_read_b128 v[176:179], v142 offset:32768
	ds_read_b128 v[184:187], v142 offset:34816
	ds_read_b128 v[188:191], v143 offset:32768
	ds_read_b128 v[192:195], v143 offset:34816
	ds_read_b128 v[196:199], v142 offset:36864
	ds_read_b128 v[200:203], v142 offset:38912
	ds_read_b128 v[204:207], v143 offset:36864
	ds_read_b128 v[208:211], v143 offset:38912
	global_load_lds_dwordx4 v138, s[48:49]
	s_mov_b32 m0, s55
	s_nop 0
	global_load_lds_dwordx4 v134, s[48:49]
	s_waitcnt vmcnt(8)
	s_waitcnt lgkmcnt(0)
	s_barrier
	s_setprio 1
	v_mfma_f32_16x16x32_bf16 v[128:131], v[144:147], v[176:179], v[128:131]
	v_mfma_f32_16x16x32_bf16 v[124:127], v[152:155], v[176:179], v[124:127]
	v_mfma_f32_16x16x32_bf16 v[112:115], v[144:147], v[184:187], v[112:115]
	v_mfma_f32_16x16x32_bf16 v[108:111], v[152:155], v[184:187], v[108:111]
	v_mfma_f32_16x16x32_bf16 v[96:99], v[144:147], v[196:199], v[96:99]
	v_mfma_f32_16x16x32_bf16 v[92:95], v[152:155], v[196:199], v[92:95]
	v_mfma_f32_16x16x32_bf16 v[80:83], v[144:147], v[200:203], v[80:83]
	v_mfma_f32_16x16x32_bf16 v[76:79], v[152:155], v[200:203], v[76:79]
	v_mfma_f32_16x16x32_bf16 v[128:131], v[148:151], v[188:191], v[128:131]
	v_mfma_f32_16x16x32_bf16 v[124:127], v[156:159], v[188:191], v[124:127]
	v_mfma_f32_16x16x32_bf16 v[112:115], v[148:151], v[192:195], v[112:115]
	v_mfma_f32_16x16x32_bf16 v[108:111], v[156:159], v[192:195], v[108:111]
	v_mfma_f32_16x16x32_bf16 v[96:99], v[148:151], v[204:207], v[96:99]
	v_mfma_f32_16x16x32_bf16 v[92:95], v[156:159], v[204:207], v[92:95]
	v_mfma_f32_16x16x32_bf16 v[80:83], v[148:151], v[208:211], v[80:83]
	v_mfma_f32_16x16x32_bf16 v[76:79], v[156:159], v[208:211], v[76:79]
	v_mfma_f32_16x16x32_bf16 v[120:123], v[160:163], v[176:179], v[120:123]
	v_mfma_f32_16x16x32_bf16 v[116:119], v[168:171], v[176:179], v[116:119]
	v_mfma_f32_16x16x32_bf16 v[104:107], v[160:163], v[184:187], v[104:107]
	v_mfma_f32_16x16x32_bf16 v[100:103], v[168:171], v[184:187], v[100:103]
	v_mfma_f32_16x16x32_bf16 v[88:91], v[160:163], v[196:199], v[88:91]
	v_mfma_f32_16x16x32_bf16 v[84:87], v[168:171], v[196:199], v[84:87]
	v_mfma_f32_16x16x32_bf16 v[72:75], v[160:163], v[200:203], v[72:75]
	v_mfma_f32_16x16x32_bf16 v[68:71], v[168:171], v[200:203], v[68:71]
	v_mfma_f32_16x16x32_bf16 v[120:123], v[164:167], v[188:191], v[120:123]
	v_mfma_f32_16x16x32_bf16 v[116:119], v[172:175], v[188:191], v[116:119]
	v_mfma_f32_16x16x32_bf16 v[104:107], v[164:167], v[192:195], v[104:107]
	v_mfma_f32_16x16x32_bf16 v[100:103], v[172:175], v[192:195], v[100:103]
	v_mfma_f32_16x16x32_bf16 v[88:91], v[164:167], v[204:207], v[88:91]
	v_mfma_f32_16x16x32_bf16 v[84:87], v[172:175], v[204:207], v[84:87]
	v_mfma_f32_16x16x32_bf16 v[72:75], v[164:167], v[208:211], v[72:75]
	v_mfma_f32_16x16x32_bf16 v[68:71], v[172:175], v[208:211], v[68:71]
	s_setprio 0
	s_barrier
	s_add_i32 s31, s31, s33
	s_add_i32 m0, s31, 0xffffff80
	ds_read_b128 v[176:179], v142 offset:49152
	ds_read_b128 v[184:187], v142 offset:51200
	ds_read_b128 v[188:191], v143 offset:49152
	ds_read_b128 v[192:195], v143 offset:51200
	ds_read_b128 v[196:199], v142 offset:53248
	ds_read_b128 v[200:203], v142 offset:55296
	ds_read_b128 v[204:207], v143 offset:53248
	ds_read_b128 v[208:211], v143 offset:55296
	global_load_lds_dwordx4 v136, s[44:45] offset:128
	s_add_i32 m0, s31, 0x1f80
	s_mov_b64 s[98:99], s[44:45]
	s_add_u32 s44, s44, 0x80080
	s_addc_u32 s45, s45, 0
	s_add_i32 s31, s47, s33
	global_load_lds_dwordx4 v132, s[98:99] offset:128
	s_mov_b32 m0, s31
	s_nop 0
	global_load_lds_dwordx4 v136, s[44:45]
	s_add_i32 m0, s31, 0x2000
	s_nop 0
	global_load_lds_dwordx4 v132, s[44:45]
	s_add_i32 m0, s56, 0xffffff80
	s_nop 0
	global_load_lds_dwordx4 v138, s[100:101] offset:128
	s_add_i32 m0, s57, 0xffffff80
	s_nop 0
	global_load_lds_dwordx4 v134, s[100:101] offset:128
	s_waitcnt vmcnt(8)
	s_waitcnt lgkmcnt(0)
	s_barrier
	s_setprio 1
	v_mfma_f32_16x16x32_bf16 v[64:67], v[144:147], v[176:179], v[64:67]
	v_mfma_f32_16x16x32_bf16 v[60:63], v[152:155], v[176:179], v[60:63]
	v_mfma_f32_16x16x32_bf16 v[48:51], v[144:147], v[184:187], v[48:51]
	v_mfma_f32_16x16x32_bf16 v[44:47], v[152:155], v[184:187], v[44:47]
	v_mfma_f32_16x16x32_bf16 v[30:33], v[144:147], v[196:199], v[30:33]
	v_mfma_f32_16x16x32_bf16 v[26:29], v[152:155], v[196:199], v[26:29]
	v_mfma_f32_16x16x32_bf16 v[14:17], v[144:147], v[200:203], v[14:17]
	v_mfma_f32_16x16x32_bf16 v[10:13], v[152:155], v[200:203], v[10:13]
	v_mfma_f32_16x16x32_bf16 v[64:67], v[148:151], v[188:191], v[64:67]
	v_mfma_f32_16x16x32_bf16 v[60:63], v[156:159], v[188:191], v[60:63]
	v_mfma_f32_16x16x32_bf16 v[48:51], v[148:151], v[192:195], v[48:51]
	v_mfma_f32_16x16x32_bf16 v[44:47], v[156:159], v[192:195], v[44:47]
	v_mfma_f32_16x16x32_bf16 v[30:33], v[148:151], v[204:207], v[30:33]
	v_mfma_f32_16x16x32_bf16 v[26:29], v[156:159], v[204:207], v[26:29]
	v_mfma_f32_16x16x32_bf16 v[14:17], v[148:151], v[208:211], v[14:17]
	v_mfma_f32_16x16x32_bf16 v[10:13], v[156:159], v[208:211], v[10:13]
	v_mfma_f32_16x16x32_bf16 v[56:59], v[160:163], v[176:179], v[56:59]
	v_mfma_f32_16x16x32_bf16 v[52:55], v[168:171], v[176:179], v[52:55]
	v_mfma_f32_16x16x32_bf16 v[40:43], v[160:163], v[184:187], v[40:43]
	v_mfma_f32_16x16x32_bf16 v[36:39], v[168:171], v[184:187], v[36:39]
	v_mfma_f32_16x16x32_bf16 v[22:25], v[160:163], v[196:199], v[22:25]
	v_mfma_f32_16x16x32_bf16 v[18:21], v[168:171], v[196:199], v[18:21]
	v_mfma_f32_16x16x32_bf16 v[6:9], v[160:163], v[200:203], v[6:9]
	v_mfma_f32_16x16x32_bf16 v[2:5], v[168:171], v[200:203], v[2:5]
	v_mfma_f32_16x16x32_bf16 v[56:59], v[164:167], v[188:191], v[56:59]
	v_mfma_f32_16x16x32_bf16 v[52:55], v[172:175], v[188:191], v[52:55]
	v_mfma_f32_16x16x32_bf16 v[40:43], v[164:167], v[192:195], v[40:43]
	v_mfma_f32_16x16x32_bf16 v[36:39], v[172:175], v[192:195], v[36:39]
	v_mfma_f32_16x16x32_bf16 v[22:25], v[164:167], v[204:207], v[22:25]
	v_mfma_f32_16x16x32_bf16 v[18:21], v[172:175], v[204:207], v[18:21]
	v_mfma_f32_16x16x32_bf16 v[6:9], v[164:167], v[208:211], v[6:9]
	v_mfma_f32_16x16x32_bf16 v[2:5], v[172:175], v[208:211], v[2:5]
	s_setprio 0
	s_barrier
	s_add_i32 s30, s30, 2
	s_add_u32 s42, s42, 0x100
	s_addc_u32 s43, s43, 0
	s_add_u32 s23, s23, 0x100
	s_addc_u32 s25, s25, 0
	s_cmp_gt_u32 s30, 29
	s_cbranch_scc0 .LBB0_162

.LBB0_907:
	s_and_b32 s9, 1, s12
	s_cmp_gt_i32 s12, 1
	s_cselect_b32 s24, 10, 12
	s_cmp_eq_u32 s9, 1
	s_cselect_b64 s[18:19], -1, 0
	s_and_b64 s[20:21], s[18:19], exec
	s_cselect_b32 s9, s24, 32
	s_add_i32 s20, s9, -2
	s_add_u32 s22, s22, 0x80080
	s_addc_u32 s23, s23, 0
	s_add_u32 s21, s28, 0x100
	s_addc_u32 s24, s29, 0
	s_mov_b32 s25, 0
	s_waitcnt vmcnt(0)
	v_readlane_b32 s43, v255, 20
	v_readlane_b32 s45, v255, 21
	v_readlane_b32 s66, v255, 22
	v_readlane_b32 s67, v255, 23
	s_mov_b64 s[68:69], 0x80
	s_add_i32 s30, s25, 2
	s_add_u32 s28, s22, 0xfff80080
	s_addc_u32 s29, s23, -1
	s_add_i32 s31, 0, 0x10000
	s_cmp_eq_u32 s20, s25
	s_cselect_b32 s41, s47, s29
	s_cselect_b32 s40, s46, s28
	s_cselect_b32 s29, s49, s24
	s_cselect_b32 s28, s48, s21
	s_add_i32 s25, 0, 0x14000
	ds_read_b128 v[132:135], v1
	ds_read_b128 v[136:139], v204
	ds_read_b128 v[140:143], v1 offset:2048
	ds_read_b128 v[144:147], v204 offset:2048
	ds_read_b128 v[148:151], v1 offset:16384
	ds_read_b128 v[152:155], v204 offset:16384
	ds_read_b128 v[156:159], v1 offset:18432
	ds_read_b128 v[160:163], v204 offset:18432
	s_add_i32 m0, s50, 0xc000
	ds_read_b128 v[164:167], v205
	ds_read_b128 v[168:171], v205 offset:2048
	ds_read_b128 v[172:175], v206
	ds_read_b128 v[176:179], v206 offset:2048
	ds_read_b128 v[190:193], v205 offset:4096
	ds_read_b128 v[194:197], v205 offset:6144
	ds_read_b128 v[198:201], v206 offset:4096
	ds_read_b128 v[232:235], v206 offset:6144
	global_load_lds_dwordx4 v188, s[22:23]
	s_add_i32 m0, s50, 0xe000
	s_nop 0
	global_load_lds_dwordx4 v186, s[22:23]
	s_waitcnt vmcnt(8)
	s_waitcnt lgkmcnt(0)
	s_barrier
	s_setprio 1
	v_mfma_f32_16x16x32_bf16 v[68:71], v[132:135], v[164:167], 0
	v_mfma_f32_16x16x32_bf16 v[72:75], v[140:143], v[164:167], 0
	v_mfma_f32_16x16x32_bf16 v[84:87], v[132:135], v[168:171], 0
	v_mfma_f32_16x16x32_bf16 v[88:91], v[140:143], v[168:171], 0
	v_mfma_f32_16x16x32_bf16 v[100:103], v[132:135], v[190:193], 0
	v_mfma_f32_16x16x32_bf16 v[104:107], v[140:143], v[190:193], 0
	v_mfma_f32_16x16x32_bf16 v[116:119], v[132:135], v[194:197], 0
	v_mfma_f32_16x16x32_bf16 v[120:123], v[140:143], v[194:197], 0
	v_mfma_f32_16x16x32_bf16 v[68:71], v[136:139], v[172:175], v[68:71]
	v_mfma_f32_16x16x32_bf16 v[72:75], v[144:147], v[172:175], v[72:75]
	v_mfma_f32_16x16x32_bf16 v[84:87], v[136:139], v[176:179], v[84:87]
	v_mfma_f32_16x16x32_bf16 v[88:91], v[144:147], v[176:179], v[88:91]
	v_mfma_f32_16x16x32_bf16 v[100:103], v[136:139], v[198:201], v[100:103]
	v_mfma_f32_16x16x32_bf16 v[104:107], v[144:147], v[198:201], v[104:107]
	v_mfma_f32_16x16x32_bf16 v[116:119], v[136:139], v[232:235], v[116:119]
	v_mfma_f32_16x16x32_bf16 v[120:123], v[144:147], v[232:235], v[120:123]
	v_mfma_f32_16x16x32_bf16 v[76:79], v[148:151], v[164:167], 0
	v_mfma_f32_16x16x32_bf16 v[80:83], v[156:159], v[164:167], 0
	v_mfma_f32_16x16x32_bf16 v[92:95], v[148:151], v[168:171], 0
	v_mfma_f32_16x16x32_bf16 v[96:99], v[156:159], v[168:171], 0
	v_mfma_f32_16x16x32_bf16 v[108:111], v[148:151], v[190:193], 0
	v_mfma_f32_16x16x32_bf16 v[112:115], v[156:159], v[190:193], 0
	v_mfma_f32_16x16x32_bf16 v[124:127], v[148:151], v[194:197], 0
	v_mfma_f32_16x16x32_bf16 v[128:131], v[156:159], v[194:197], 0
	v_mfma_f32_16x16x32_bf16 v[76:79], v[152:155], v[172:175], v[76:79]
	v_mfma_f32_16x16x32_bf16 v[80:83], v[160:163], v[172:175], v[80:83]
	v_mfma_f32_16x16x32_bf16 v[92:95], v[152:155], v[176:179], v[92:95]
	v_mfma_f32_16x16x32_bf16 v[96:99], v[160:163], v[176:179], v[96:99]
	v_mfma_f32_16x16x32_bf16 v[108:111], v[152:155], v[198:201], v[108:111]
	v_mfma_f32_16x16x32_bf16 v[112:115], v[160:163], v[198:201], v[112:115]
	v_mfma_f32_16x16x32_bf16 v[124:127], v[152:155], v[232:235], v[124:127]
	v_mfma_f32_16x16x32_bf16 v[128:131], v[160:163], v[232:235], v[128:131]
	s_setprio 0
	s_barrier
	s_add_i32 s31, s31, s33
	s_mov_b32 m0, s31
	ds_read_b128 v[164:167], v205 offset:16384
	ds_read_b128 v[168:171], v205 offset:18432
	ds_read_b128 v[172:175], v206 offset:16384
	ds_read_b128 v[176:179], v206 offset:18432
	ds_read_b128 v[190:193], v205 offset:20480
	ds_read_b128 v[194:197], v205 offset:22528
	ds_read_b128 v[198:201], v206 offset:20480
	ds_read_b128 v[232:235], v206 offset:22528
	global_load_lds_dwordx4 v34, s[28:29]
	s_add_i32 m0, s31, 0x2000
	s_add_u32 s34, s28, 0x80000
	s_addc_u32 s35, s29, 0
	s_add_i32 s25, s25, s33
	global_load_lds_dwordx4 v184, s[28:29]
	s_mov_b32 m0, s25
	s_nop 0
	global_load_lds_dwordx4 v34, s[34:35]
	s_add_i32 m0, s25, 0x2000
	s_nop 0
	global_load_lds_dwordx4 v184, s[34:35]
	s_mov_b32 m0, s50
	s_nop 0
	global_load_lds_dwordx4 v188, s[40:41]
	s_mov_b32 m0, s51
	s_nop 0
	global_load_lds_dwordx4 v186, s[40:41]
	s_waitcnt vmcnt(8)
	s_waitcnt lgkmcnt(0)
	s_barrier
	s_setprio 1
	v_mfma_f32_16x16x32_bf16 v[2:5], v[132:135], v[164:167], 0
	v_mfma_f32_16x16x32_bf16 v[6:9], v[140:143], v[164:167], 0
	v_mfma_f32_16x16x32_bf16 v[18:21], v[132:135], v[168:171], 0
	v_mfma_f32_16x16x32_bf16 v[22:25], v[140:143], v[168:171], 0
	v_mfma_f32_16x16x32_bf16 v[36:39], v[132:135], v[190:193], 0
	v_mfma_f32_16x16x32_bf16 v[40:43], v[140:143], v[190:193], 0
	v_mfma_f32_16x16x32_bf16 v[52:55], v[132:135], v[194:197], 0
	v_mfma_f32_16x16x32_bf16 v[56:59], v[140:143], v[194:197], 0
	v_mfma_f32_16x16x32_bf16 v[2:5], v[136:139], v[172:175], v[2:5]
	v_mfma_f32_16x16x32_bf16 v[6:9], v[144:147], v[172:175], v[6:9]
	v_mfma_f32_16x16x32_bf16 v[18:21], v[136:139], v[176:179], v[18:21]
	v_mfma_f32_16x16x32_bf16 v[22:25], v[144:147], v[176:179], v[22:25]
	v_mfma_f32_16x16x32_bf16 v[36:39], v[136:139], v[198:201], v[36:39]
	v_mfma_f32_16x16x32_bf16 v[40:43], v[144:147], v[198:201], v[40:43]
	v_mfma_f32_16x16x32_bf16 v[52:55], v[136:139], v[232:235], v[52:55]
	v_mfma_f32_16x16x32_bf16 v[56:59], v[144:147], v[232:235], v[56:59]
	v_mfma_f32_16x16x32_bf16 v[10:13], v[148:151], v[164:167], 0
	v_mfma_f32_16x16x32_bf16 v[14:17], v[156:159], v[164:167], 0
	v_mfma_f32_16x16x32_bf16 v[26:29], v[148:151], v[168:171], 0
	v_mfma_f32_16x16x32_bf16 v[30:33], v[156:159], v[168:171], 0
	v_mfma_f32_16x16x32_bf16 v[44:47], v[148:151], v[190:193], 0
	v_mfma_f32_16x16x32_bf16 v[48:51], v[156:159], v[190:193], 0
	v_mfma_f32_16x16x32_bf16 v[60:63], v[148:151], v[194:197], 0
	v_mfma_f32_16x16x32_bf16 v[64:67], v[156:159], v[194:197], 0
	v_mfma_f32_16x16x32_bf16 v[10:13], v[152:155], v[172:175], v[10:13]
	v_mfma_f32_16x16x32_bf16 v[14:17], v[160:163], v[172:175], v[14:17]
	v_mfma_f32_16x16x32_bf16 v[26:29], v[152:155], v[176:179], v[26:29]
	v_mfma_f32_16x16x32_bf16 v[30:33], v[160:163], v[176:179], v[30:33]
	v_mfma_f32_16x16x32_bf16 v[44:47], v[152:155], v[198:201], v[44:47]
	v_mfma_f32_16x16x32_bf16 v[48:51], v[160:163], v[198:201], v[48:51]
	v_mfma_f32_16x16x32_bf16 v[60:63], v[152:155], v[232:235], v[60:63]
	v_mfma_f32_16x16x32_bf16 v[64:67], v[160:163], v[232:235], v[64:67]
	s_setprio 0
	s_barrier
	s_add_i32 s25, 0, 0x18000
	s_add_i32 s31, 0, 0x1c000
	ds_read_b128 v[132:135], v1 offset:32768
	ds_read_b128 v[136:139], v204 offset:32768
	ds_read_b128 v[140:143], v1 offset:34816
	ds_read_b128 v[144:147], v204 offset:34816
	ds_read_b128 v[148:151], v1 offset:49152
	ds_read_b128 v[152:155], v204 offset:49152
	ds_read_b128 v[156:159], v1 offset:51200
	ds_read_b128 v[160:163], v204 offset:51200
	s_add_u32 s34, s40, 0x80000
	s_addc_u32 s35, s41, 0
	s_mov_b32 m0, s52
	ds_read_b128 v[164:167], v205 offset:32768
	ds_read_b128 v[168:171], v205 offset:34816
	ds_read_b128 v[172:175], v206 offset:32768
	ds_read_b128 v[176:179], v206 offset:34816
	ds_read_b128 v[190:193], v205 offset:36864
	ds_read_b128 v[194:197], v205 offset:38912
	ds_read_b128 v[198:201], v206 offset:36864
	ds_read_b128 v[232:235], v206 offset:38912
	global_load_lds_dwordx4 v188, s[34:35]
	s_mov_b32 m0, s53
	s_nop 0
	global_load_lds_dwordx4 v186, s[34:35]
	s_waitcnt vmcnt(8)
	s_waitcnt lgkmcnt(0)
	s_barrier
	s_setprio 1
	v_mfma_f32_16x16x32_bf16 v[68:71], v[132:135], v[164:167], v[68:71]
	v_mfma_f32_16x16x32_bf16 v[72:75], v[140:143], v[164:167], v[72:75]
	v_mfma_f32_16x16x32_bf16 v[84:87], v[132:135], v[168:171], v[84:87]
	v_mfma_f32_16x16x32_bf16 v[88:91], v[140:143], v[168:171], v[88:91]
	v_mfma_f32_16x16x32_bf16 v[100:103], v[132:135], v[190:193], v[100:103]
	v_mfma_f32_16x16x32_bf16 v[104:107], v[140:143], v[190:193], v[104:107]
	v_mfma_f32_16x16x32_bf16 v[116:119], v[132:135], v[194:197], v[116:119]
	v_mfma_f32_16x16x32_bf16 v[120:123], v[140:143], v[194:197], v[120:123]
	v_mfma_f32_16x16x32_bf16 v[68:71], v[136:139], v[172:175], v[68:71]
	v_mfma_f32_16x16x32_bf16 v[72:75], v[144:147], v[172:175], v[72:75]
	v_mfma_f32_16x16x32_bf16 v[84:87], v[136:139], v[176:179], v[84:87]
	v_mfma_f32_16x16x32_bf16 v[88:91], v[144:147], v[176:179], v[88:91]
	v_mfma_f32_16x16x32_bf16 v[100:103], v[136:139], v[198:201], v[100:103]
	v_mfma_f32_16x16x32_bf16 v[104:107], v[144:147], v[198:201], v[104:107]
	v_mfma_f32_16x16x32_bf16 v[116:119], v[136:139], v[232:235], v[116:119]
	v_mfma_f32_16x16x32_bf16 v[120:123], v[144:147], v[232:235], v[120:123]
	v_mfma_f32_16x16x32_bf16 v[76:79], v[148:151], v[164:167], v[76:79]
	v_mfma_f32_16x16x32_bf16 v[80:83], v[156:159], v[164:167], v[80:83]
	v_mfma_f32_16x16x32_bf16 v[92:95], v[148:151], v[168:171], v[92:95]
	v_mfma_f32_16x16x32_bf16 v[96:99], v[156:159], v[168:171], v[96:99]
	v_mfma_f32_16x16x32_bf16 v[108:111], v[148:151], v[190:193], v[108:111]
	v_mfma_f32_16x16x32_bf16 v[112:115], v[156:159], v[190:193], v[112:115]
	v_mfma_f32_16x16x32_bf16 v[124:127], v[148:151], v[194:197], v[124:127]
	v_mfma_f32_16x16x32_bf16 v[128:131], v[156:159], v[194:197], v[128:131]
	v_mfma_f32_16x16x32_bf16 v[76:79], v[152:155], v[172:175], v[76:79]
	v_mfma_f32_16x16x32_bf16 v[80:83], v[160:163], v[172:175], v[80:83]
	v_mfma_f32_16x16x32_bf16 v[92:95], v[152:155], v[176:179], v[92:95]
	v_mfma_f32_16x16x32_bf16 v[96:99], v[160:163], v[176:179], v[96:99]
	v_mfma_f32_16x16x32_bf16 v[108:111], v[152:155], v[198:201], v[108:111]
	v_mfma_f32_16x16x32_bf16 v[112:115], v[160:163], v[198:201], v[112:115]
	v_mfma_f32_16x16x32_bf16 v[124:127], v[152:155], v[232:235], v[124:127]
	v_mfma_f32_16x16x32_bf16 v[128:131], v[160:163], v[232:235], v[128:131]
	s_setprio 0
	s_barrier
	s_add_i32 s25, s25, s33
	s_add_i32 m0, s25, 0xffffff80
	ds_read_b128 v[164:167], v205 offset:49152
	ds_read_b128 v[168:171], v205 offset:51200
	ds_read_b128 v[172:175], v206 offset:49152
	ds_read_b128 v[176:179], v206 offset:51200
	ds_read_b128 v[190:193], v205 offset:53248
	ds_read_b128 v[194:197], v205 offset:55296
	ds_read_b128 v[198:201], v206 offset:53248
	ds_read_b128 v[232:235], v206 offset:55296
	global_load_lds_dwordx4 v34, s[28:29] offset:128
	s_add_i32 m0, s25, 0x1f80
	s_mov_b64 s[98:99], s[28:29]
	s_add_u32 s28, s28, 0x80080
	s_addc_u32 s29, s29, 0
	s_add_i32 s25, s31, s33
	global_load_lds_dwordx4 v184, s[98:99] offset:128
	s_mov_b32 m0, s25
	s_nop 0
	global_load_lds_dwordx4 v34, s[28:29]
	s_add_i32 m0, s25, 0x2000
	s_nop 0
	global_load_lds_dwordx4 v184, s[28:29]
	s_add_i32 m0, s54, 0xffffff80
	s_nop 0
	global_load_lds_dwordx4 v188, s[40:41] offset:128
	s_add_i32 m0, s55, 0xffffff80
	s_nop 0
	global_load_lds_dwordx4 v186, s[40:41] offset:128
	s_waitcnt vmcnt(8)
	s_waitcnt lgkmcnt(0)
	s_barrier
	s_setprio 1
	v_mfma_f32_16x16x32_bf16 v[2:5], v[132:135], v[164:167], v[2:5]
	v_mfma_f32_16x16x32_bf16 v[6:9], v[140:143], v[164:167], v[6:9]
	v_mfma_f32_16x16x32_bf16 v[18:21], v[132:135], v[168:171], v[18:21]
	v_mfma_f32_16x16x32_bf16 v[22:25], v[140:143], v[168:171], v[22:25]
	v_mfma_f32_16x16x32_bf16 v[36:39], v[132:135], v[190:193], v[36:39]
	v_mfma_f32_16x16x32_bf16 v[40:43], v[140:143], v[190:193], v[40:43]
	v_mfma_f32_16x16x32_bf16 v[52:55], v[132:135], v[194:197], v[52:55]
	v_mfma_f32_16x16x32_bf16 v[56:59], v[140:143], v[194:197], v[56:59]
	v_mfma_f32_16x16x32_bf16 v[2:5], v[136:139], v[172:175], v[2:5]
	v_mfma_f32_16x16x32_bf16 v[6:9], v[144:147], v[172:175], v[6:9]
	v_mfma_f32_16x16x32_bf16 v[18:21], v[136:139], v[176:179], v[18:21]
	v_mfma_f32_16x16x32_bf16 v[22:25], v[144:147], v[176:179], v[22:25]
	v_mfma_f32_16x16x32_bf16 v[36:39], v[136:139], v[198:201], v[36:39]
	v_mfma_f32_16x16x32_bf16 v[40:43], v[144:147], v[198:201], v[40:43]
	v_mfma_f32_16x16x32_bf16 v[52:55], v[136:139], v[232:235], v[52:55]
	v_mfma_f32_16x16x32_bf16 v[56:59], v[144:147], v[232:235], v[56:59]
	v_mfma_f32_16x16x32_bf16 v[10:13], v[148:151], v[164:167], v[10:13]
	v_mfma_f32_16x16x32_bf16 v[14:17], v[156:159], v[164:167], v[14:17]
	v_mfma_f32_16x16x32_bf16 v[26:29], v[148:151], v[168:171], v[26:29]
	v_mfma_f32_16x16x32_bf16 v[30:33], v[156:159], v[168:171], v[30:33]
	v_mfma_f32_16x16x32_bf16 v[44:47], v[148:151], v[190:193], v[44:47]
	v_mfma_f32_16x16x32_bf16 v[48:51], v[156:159], v[190:193], v[48:51]
	v_mfma_f32_16x16x32_bf16 v[60:63], v[148:151], v[194:197], v[60:63]
	v_mfma_f32_16x16x32_bf16 v[64:67], v[156:159], v[194:197], v[64:67]
	v_mfma_f32_16x16x32_bf16 v[10:13], v[152:155], v[172:175], v[10:13]
	v_mfma_f32_16x16x32_bf16 v[14:17], v[160:163], v[172:175], v[14:17]
	v_mfma_f32_16x16x32_bf16 v[26:29], v[152:155], v[176:179], v[26:29]
	v_mfma_f32_16x16x32_bf16 v[30:33], v[160:163], v[176:179], v[30:33]
	v_mfma_f32_16x16x32_bf16 v[44:47], v[152:155], v[198:201], v[44:47]
	v_mfma_f32_16x16x32_bf16 v[48:51], v[160:163], v[198:201], v[48:51]
	v_mfma_f32_16x16x32_bf16 v[60:63], v[152:155], v[232:235], v[60:63]
	v_mfma_f32_16x16x32_bf16 v[64:67], v[160:163], v[232:235], v[64:67]
	s_setprio 0
	s_barrier
	s_add_u32 s22, s22, 0x100
	s_addc_u32 s23, s23, 0
	s_add_u32 s21, s21, 0x100
	s_addc_u32 s24, s24, 0
	s_cmp_ge_u32 s30, s9
	s_mov_b32 s25, s30
	s_cbranch_scc1 .Lpeel_done_P3
.LBB0_908:
	s_add_i32 s30, s25, 2
	s_add_u32 s28, s22, 0xfff80080
	s_addc_u32 s29, s23, -1
	s_add_i32 s31, 0, 0x10000
	s_cmp_eq_u32 s20, s25
	s_cselect_b32 s41, s47, s29
	s_cselect_b32 s40, s46, s28
	s_cselect_b32 s29, s49, s24
	s_cselect_b32 s28, s48, s21
	s_add_i32 s25, 0, 0x14000
	ds_read_b128 v[132:135], v1
	ds_read_b128 v[136:139], v204
	ds_read_b128 v[140:143], v1 offset:2048
	ds_read_b128 v[144:147], v204 offset:2048
	ds_read_b128 v[148:151], v1 offset:16384
	ds_read_b128 v[152:155], v204 offset:16384
	ds_read_b128 v[156:159], v1 offset:18432
	ds_read_b128 v[160:163], v204 offset:18432
	s_add_i32 m0, s50, 0xc000
	ds_read_b128 v[164:167], v205
	ds_read_b128 v[168:171], v205 offset:2048
	ds_read_b128 v[172:175], v206
	ds_read_b128 v[176:179], v206 offset:2048
	ds_read_b128 v[190:193], v205 offset:4096
	ds_read_b128 v[194:197], v205 offset:6144
	ds_read_b128 v[198:201], v206 offset:4096
	ds_read_b128 v[232:235], v206 offset:6144
	global_load_lds_dwordx4 v188, s[22:23]
	s_add_i32 m0, s50, 0xe000
	s_nop 0
	global_load_lds_dwordx4 v186, s[22:23]
	s_waitcnt vmcnt(8)
	s_waitcnt lgkmcnt(0)
	s_barrier
	s_setprio 1
	v_mfma_f32_16x16x32_bf16 v[68:71], v[132:135], v[164:167], v[68:71]
	v_mfma_f32_16x16x32_bf16 v[72:75], v[140:143], v[164:167], v[72:75]
	v_mfma_f32_16x16x32_bf16 v[84:87], v[132:135], v[168:171], v[84:87]
	v_mfma_f32_16x16x32_bf16 v[88:91], v[140:143], v[168:171], v[88:91]
	v_mfma_f32_16x16x32_bf16 v[100:103], v[132:135], v[190:193], v[100:103]
	v_mfma_f32_16x16x32_bf16 v[104:107], v[140:143], v[190:193], v[104:107]
	v_mfma_f32_16x16x32_bf16 v[116:119], v[132:135], v[194:197], v[116:119]
	v_mfma_f32_16x16x32_bf16 v[120:123], v[140:143], v[194:197], v[120:123]
	v_mfma_f32_16x16x32_bf16 v[68:71], v[136:139], v[172:175], v[68:71]
	v_mfma_f32_16x16x32_bf16 v[72:75], v[144:147], v[172:175], v[72:75]
	v_mfma_f32_16x16x32_bf16 v[84:87], v[136:139], v[176:179], v[84:87]
	v_mfma_f32_16x16x32_bf16 v[88:91], v[144:147], v[176:179], v[88:91]
	v_mfma_f32_16x16x32_bf16 v[100:103], v[136:139], v[198:201], v[100:103]
	v_mfma_f32_16x16x32_bf16 v[104:107], v[144:147], v[198:201], v[104:107]
	v_mfma_f32_16x16x32_bf16 v[116:119], v[136:139], v[232:235], v[116:119]
	v_mfma_f32_16x16x32_bf16 v[120:123], v[144:147], v[232:235], v[120:123]
	v_mfma_f32_16x16x32_bf16 v[76:79], v[148:151], v[164:167], v[76:79]
	v_mfma_f32_16x16x32_bf16 v[80:83], v[156:159], v[164:167], v[80:83]
	v_mfma_f32_16x16x32_bf16 v[92:95], v[148:151], v[168:171], v[92:95]
	v_mfma_f32_16x16x32_bf16 v[96:99], v[156:159], v[168:171], v[96:99]
	v_mfma_f32_16x16x32_bf16 v[108:111], v[148:151], v[190:193], v[108:111]
	v_mfma_f32_16x16x32_bf16 v[112:115], v[156:159], v[190:193], v[112:115]
	v_mfma_f32_16x16x32_bf16 v[124:127], v[148:151], v[194:197], v[124:127]
	v_mfma_f32_16x16x32_bf16 v[128:131], v[156:159], v[194:197], v[128:131]
	v_mfma_f32_16x16x32_bf16 v[76:79], v[152:155], v[172:175], v[76:79]
	v_mfma_f32_16x16x32_bf16 v[80:83], v[160:163], v[172:175], v[80:83]
	v_mfma_f32_16x16x32_bf16 v[92:95], v[152:155], v[176:179], v[92:95]
	v_mfma_f32_16x16x32_bf16 v[96:99], v[160:163], v[176:179], v[96:99]
	v_mfma_f32_16x16x32_bf16 v[108:111], v[152:155], v[198:201], v[108:111]
	v_mfma_f32_16x16x32_bf16 v[112:115], v[160:163], v[198:201], v[112:115]
	v_mfma_f32_16x16x32_bf16 v[124:127], v[152:155], v[232:235], v[124:127]
	v_mfma_f32_16x16x32_bf16 v[128:131], v[160:163], v[232:235], v[128:131]
	s_setprio 0
	s_barrier
	s_add_i32 s31, s31, s33
	s_mov_b32 m0, s31
	ds_read_b128 v[164:167], v205 offset:16384
	ds_read_b128 v[168:171], v205 offset:18432
	ds_read_b128 v[172:175], v206 offset:16384
	ds_read_b128 v[176:179], v206 offset:18432
	ds_read_b128 v[190:193], v205 offset:20480
	ds_read_b128 v[194:197], v205 offset:22528
	ds_read_b128 v[198:201], v206 offset:20480
	ds_read_b128 v[232:235], v206 offset:22528
	global_load_lds_dwordx4 v34, s[28:29]
	s_add_i32 m0, s31, 0x2000
	s_add_u32 s34, s28, 0x80000
	s_addc_u32 s35, s29, 0
	s_add_i32 s25, s25, s33
	global_load_lds_dwordx4 v184, s[28:29]
	s_mov_b32 m0, s25
	s_nop 0
	global_load_lds_dwordx4 v34, s[34:35]
	s_add_i32 m0, s25, 0x2000
	s_nop 0
	global_load_lds_dwordx4 v184, s[34:35]
	s_mov_b32 m0, s50
	s_nop 0
	global_load_lds_dwordx4 v188, s[40:41]
	s_mov_b32 m0, s51
	s_nop 0
	global_load_lds_dwordx4 v186, s[40:41]
	s_waitcnt vmcnt(8)
	s_waitcnt lgkmcnt(0)
	s_barrier
	s_setprio 1
	v_mfma_f32_16x16x32_bf16 v[2:5], v[132:135], v[164:167], v[2:5]
	v_mfma_f32_16x16x32_bf16 v[6:9], v[140:143], v[164:167], v[6:9]
	v_mfma_f32_16x16x32_bf16 v[18:21], v[132:135], v[168:171], v[18:21]
	v_mfma_f32_16x16x32_bf16 v[22:25], v[140:143], v[168:171], v[22:25]
	v_mfma_f32_16x16x32_bf16 v[36:39], v[132:135], v[190:193], v[36:39]
	v_mfma_f32_16x16x32_bf16 v[40:43], v[140:143], v[190:193], v[40:43]
	v_mfma_f32_16x16x32_bf16 v[52:55], v[132:135], v[194:197], v[52:55]
	v_mfma_f32_16x16x32_bf16 v[56:59], v[140:143], v[194:197], v[56:59]
	v_mfma_f32_16x16x32_bf16 v[2:5], v[136:139], v[172:175], v[2:5]
	v_mfma_f32_16x16x32_bf16 v[6:9], v[144:147], v[172:175], v[6:9]
	v_mfma_f32_16x16x32_bf16 v[18:21], v[136:139], v[176:179], v[18:21]
	v_mfma_f32_16x16x32_bf16 v[22:25], v[144:147], v[176:179], v[22:25]
	v_mfma_f32_16x16x32_bf16 v[36:39], v[136:139], v[198:201], v[36:39]
	v_mfma_f32_16x16x32_bf16 v[40:43], v[144:147], v[198:201], v[40:43]
	v_mfma_f32_16x16x32_bf16 v[52:55], v[136:139], v[232:235], v[52:55]
	v_mfma_f32_16x16x32_bf16 v[56:59], v[144:147], v[232:235], v[56:59]
	v_mfma_f32_16x16x32_bf16 v[10:13], v[148:151], v[164:167], v[10:13]
	v_mfma_f32_16x16x32_bf16 v[14:17], v[156:159], v[164:167], v[14:17]
	v_mfma_f32_16x16x32_bf16 v[26:29], v[148:151], v[168:171], v[26:29]
	v_mfma_f32_16x16x32_bf16 v[30:33], v[156:159], v[168:171], v[30:33]
	v_mfma_f32_16x16x32_bf16 v[44:47], v[148:151], v[190:193], v[44:47]
	v_mfma_f32_16x16x32_bf16 v[48:51], v[156:159], v[190:193], v[48:51]
	v_mfma_f32_16x16x32_bf16 v[60:63], v[148:151], v[194:197], v[60:63]
	v_mfma_f32_16x16x32_bf16 v[64:67], v[156:159], v[194:197], v[64:67]
	v_mfma_f32_16x16x32_bf16 v[10:13], v[152:155], v[172:175], v[10:13]
	v_mfma_f32_16x16x32_bf16 v[14:17], v[160:163], v[172:175], v[14:17]
	v_mfma_f32_16x16x32_bf16 v[26:29], v[152:155], v[176:179], v[26:29]
	v_mfma_f32_16x16x32_bf16 v[30:33], v[160:163], v[176:179], v[30:33]
	v_mfma_f32_16x16x32_bf16 v[44:47], v[152:155], v[198:201], v[44:47]
	v_mfma_f32_16x16x32_bf16 v[48:51], v[160:163], v[198:201], v[48:51]
	v_mfma_f32_16x16x32_bf16 v[60:63], v[152:155], v[232:235], v[60:63]
	v_mfma_f32_16x16x32_bf16 v[64:67], v[160:163], v[232:235], v[64:67]
	s_setprio 0
	s_barrier
	s_add_i32 s25, 0, 0x18000
	s_add_i32 s31, 0, 0x1c000
	ds_read_b128 v[132:135], v1 offset:32768
	ds_read_b128 v[136:139], v204 offset:32768
	ds_read_b128 v[140:143], v1 offset:34816
	ds_read_b128 v[144:147], v204 offset:34816
	ds_read_b128 v[148:151], v1 offset:49152
	ds_read_b128 v[152:155], v204 offset:49152
	ds_read_b128 v[156:159], v1 offset:51200
	ds_read_b128 v[160:163], v204 offset:51200
	s_add_u32 s34, s40, 0x80000
	s_addc_u32 s35, s41, 0
	s_mov_b32 m0, s52
	ds_read_b128 v[164:167], v205 offset:32768
	ds_read_b128 v[168:171], v205 offset:34816
	ds_read_b128 v[172:175], v206 offset:32768
	ds_read_b128 v[176:179], v206 offset:34816
	ds_read_b128 v[190:193], v205 offset:36864
	ds_read_b128 v[194:197], v205 offset:38912
	ds_read_b128 v[198:201], v206 offset:36864
	ds_read_b128 v[232:235], v206 offset:38912
	global_load_lds_dwordx4 v188, s[34:35]
	s_mov_b32 m0, s53
	s_nop 0
	global_load_lds_dwordx4 v186, s[34:35]
	s_waitcnt vmcnt(8)
	s_waitcnt lgkmcnt(0)
	s_barrier
	s_setprio 1
	v_mfma_f32_16x16x32_bf16 v[68:71], v[132:135], v[164:167], v[68:71]
	v_mfma_f32_16x16x32_bf16 v[72:75], v[140:143], v[164:167], v[72:75]
	v_mfma_f32_16x16x32_bf16 v[84:87], v[132:135], v[168:171], v[84:87]
	v_mfma_f32_16x16x32_bf16 v[88:91], v[140:143], v[168:171], v[88:91]
	v_mfma_f32_16x16x32_bf16 v[100:103], v[132:135], v[190:193], v[100:103]
	v_mfma_f32_16x16x32_bf16 v[104:107], v[140:143], v[190:193], v[104:107]
	v_mfma_f32_16x16x32_bf16 v[116:119], v[132:135], v[194:197], v[116:119]
	v_mfma_f32_16x16x32_bf16 v[120:123], v[140:143], v[194:197], v[120:123]
	v_mfma_f32_16x16x32_bf16 v[68:71], v[136:139], v[172:175], v[68:71]
	v_mfma_f32_16x16x32_bf16 v[72:75], v[144:147], v[172:175], v[72:75]
	v_mfma_f32_16x16x32_bf16 v[84:87], v[136:139], v[176:179], v[84:87]
	v_mfma_f32_16x16x32_bf16 v[88:91], v[144:147], v[176:179], v[88:91]
	v_mfma_f32_16x16x32_bf16 v[100:103], v[136:139], v[198:201], v[100:103]
	v_mfma_f32_16x16x32_bf16 v[104:107], v[144:147], v[198:201], v[104:107]
	v_mfma_f32_16x16x32_bf16 v[116:119], v[136:139], v[232:235], v[116:119]
	v_mfma_f32_16x16x32_bf16 v[120:123], v[144:147], v[232:235], v[120:123]
	v_mfma_f32_16x16x32_bf16 v[76:79], v[148:151], v[164:167], v[76:79]
	v_mfma_f32_16x16x32_bf16 v[80:83], v[156:159], v[164:167], v[80:83]
	v_mfma_f32_16x16x32_bf16 v[92:95], v[148:151], v[168:171], v[92:95]
	v_mfma_f32_16x16x32_bf16 v[96:99], v[156:159], v[168:171], v[96:99]
	v_mfma_f32_16x16x32_bf16 v[108:111], v[148:151], v[190:193], v[108:111]
	v_mfma_f32_16x16x32_bf16 v[112:115], v[156:159], v[190:193], v[112:115]
	v_mfma_f32_16x16x32_bf16 v[124:127], v[148:151], v[194:197], v[124:127]
	v_mfma_f32_16x16x32_bf16 v[128:131], v[156:159], v[194:197], v[128:131]
	v_mfma_f32_16x16x32_bf16 v[76:79], v[152:155], v[172:175], v[76:79]
	v_mfma_f32_16x16x32_bf16 v[80:83], v[160:163], v[172:175], v[80:83]
	v_mfma_f32_16x16x32_bf16 v[92:95], v[152:155], v[176:179], v[92:95]
	v_mfma_f32_16x16x32_bf16 v[96:99], v[160:163], v[176:179], v[96:99]
	v_mfma_f32_16x16x32_bf16 v[108:111], v[152:155], v[198:201], v[108:111]
	v_mfma_f32_16x16x32_bf16 v[112:115], v[160:163], v[198:201], v[112:115]
	v_mfma_f32_16x16x32_bf16 v[124:127], v[152:155], v[232:235], v[124:127]
	v_mfma_f32_16x16x32_bf16 v[128:131], v[160:163], v[232:235], v[128:131]
	s_setprio 0
	s_barrier
	s_add_i32 s25, s25, s33
	s_add_i32 m0, s25, 0xffffff80
	ds_read_b128 v[164:167], v205 offset:49152
	ds_read_b128 v[168:171], v205 offset:51200
	ds_read_b128 v[172:175], v206 offset:49152
	ds_read_b128 v[176:179], v206 offset:51200
	ds_read_b128 v[190:193], v205 offset:53248
	ds_read_b128 v[194:197], v205 offset:55296
	ds_read_b128 v[198:201], v206 offset:53248
	ds_read_b128 v[232:235], v206 offset:55296
	global_load_lds_dwordx4 v34, s[28:29] offset:128
	s_add_i32 m0, s25, 0x1f80
	s_mov_b64 s[98:99], s[28:29]
	s_add_u32 s28, s28, 0x80080
	s_addc_u32 s29, s29, 0
	s_add_i32 s25, s31, s33
	global_load_lds_dwordx4 v184, s[98:99] offset:128
	s_mov_b32 m0, s25
	s_nop 0
	global_load_lds_dwordx4 v34, s[28:29]
	s_add_i32 m0, s25, 0x2000
	s_nop 0
	global_load_lds_dwordx4 v184, s[28:29]
	s_add_i32 m0, s54, 0xffffff80
	s_nop 0
	global_load_lds_dwordx4 v188, s[40:41] offset:128
	s_add_i32 m0, s55, 0xffffff80
	s_nop 0
	global_load_lds_dwordx4 v186, s[40:41] offset:128
	s_waitcnt vmcnt(8)
	s_waitcnt lgkmcnt(0)
	s_barrier
	s_setprio 1
	v_mfma_f32_16x16x32_bf16 v[2:5], v[132:135], v[164:167], v[2:5]
	v_mfma_f32_16x16x32_bf16 v[6:9], v[140:143], v[164:167], v[6:9]
	v_mfma_f32_16x16x32_bf16 v[18:21], v[132:135], v[168:171], v[18:21]
	v_mfma_f32_16x16x32_bf16 v[22:25], v[140:143], v[168:171], v[22:25]
	v_mfma_f32_16x16x32_bf16 v[36:39], v[132:135], v[190:193], v[36:39]
	v_mfma_f32_16x16x32_bf16 v[40:43], v[140:143], v[190:193], v[40:43]
	v_mfma_f32_16x16x32_bf16 v[52:55], v[132:135], v[194:197], v[52:55]
	v_mfma_f32_16x16x32_bf16 v[56:59], v[140:143], v[194:197], v[56:59]
	v_mfma_f32_16x16x32_bf16 v[2:5], v[136:139], v[172:175], v[2:5]
	v_mfma_f32_16x16x32_bf16 v[6:9], v[144:147], v[172:175], v[6:9]
	v_mfma_f32_16x16x32_bf16 v[18:21], v[136:139], v[176:179], v[18:21]
	v_mfma_f32_16x16x32_bf16 v[22:25], v[144:147], v[176:179], v[22:25]
	v_mfma_f32_16x16x32_bf16 v[36:39], v[136:139], v[198:201], v[36:39]
	v_mfma_f32_16x16x32_bf16 v[40:43], v[144:147], v[198:201], v[40:43]
	v_mfma_f32_16x16x32_bf16 v[52:55], v[136:139], v[232:235], v[52:55]
	v_mfma_f32_16x16x32_bf16 v[56:59], v[144:147], v[232:235], v[56:59]
	v_mfma_f32_16x16x32_bf16 v[10:13], v[148:151], v[164:167], v[10:13]
	v_mfma_f32_16x16x32_bf16 v[14:17], v[156:159], v[164:167], v[14:17]
	v_mfma_f32_16x16x32_bf16 v[26:29], v[148:151], v[168:171], v[26:29]
	v_mfma_f32_16x16x32_bf16 v[30:33], v[156:159], v[168:171], v[30:33]
	v_mfma_f32_16x16x32_bf16 v[44:47], v[148:151], v[190:193], v[44:47]
	v_mfma_f32_16x16x32_bf16 v[48:51], v[156:159], v[190:193], v[48:51]
	v_mfma_f32_16x16x32_bf16 v[60:63], v[148:151], v[194:197], v[60:63]
	v_mfma_f32_16x16x32_bf16 v[64:67], v[156:159], v[194:197], v[64:67]
	v_mfma_f32_16x16x32_bf16 v[10:13], v[152:155], v[172:175], v[10:13]
	v_mfma_f32_16x16x32_bf16 v[14:17], v[160:163], v[172:175], v[14:17]
	v_mfma_f32_16x16x32_bf16 v[26:29], v[152:155], v[176:179], v[26:29]
	v_mfma_f32_16x16x32_bf16 v[30:33], v[160:163], v[176:179], v[30:33]
	v_mfma_f32_16x16x32_bf16 v[44:47], v[152:155], v[198:201], v[44:47]
	v_mfma_f32_16x16x32_bf16 v[48:51], v[160:163], v[198:201], v[48:51]
	v_mfma_f32_16x16x32_bf16 v[60:63], v[152:155], v[232:235], v[60:63]
	v_mfma_f32_16x16x32_bf16 v[64:67], v[160:163], v[232:235], v[64:67]
	s_setprio 0
	s_barrier
	s_add_u32 s22, s22, 0x100
	s_addc_u32 s23, s23, 0
	s_add_u32 s21, s21, 0x100
	s_addc_u32 s24, s24, 0
	s_cmp_ge_u32 s30, s9
	s_mov_b32 s25, s30
	s_cbranch_scc0 .LBB0_908

.LBB0_1022:
	s_ashr_i32 s23, s22, 31
	s_lshl_b64 s[12:13], s[22:23], 20
	v_readlane_b32 s20, v254, 52
	v_readlane_b32 s21, v254, 53
	s_add_u32 s40, s20, s12
	s_addc_u32 s41, s21, s13
	s_and_b64 s[12:13], s[38:39], exec
	s_cselect_b32 s12, s41, s9
	s_cselect_b32 s13, s40, s8
	s_ashr_i32 s19, s18, 31
	s_lshl_b64 s[20:21], s[18:19], 20
	v_readlane_b32 s24, v254, 48
	v_readlane_b32 s25, v254, 49
	s_add_u32 s42, s24, s20
	s_addc_u32 s43, s25, s21
	s_and_b64 s[20:21], s[38:39], exec
	s_cselect_b32 s19, s43, s29
	s_cselect_b32 s20, s42, s28
	s_add_u32 s8, s8, 0x80080
	s_addc_u32 s9, s9, 0
	s_add_u32 s21, s28, 0x100
	s_addc_u32 s23, s29, 0
	s_mov_b32 s24, -2
	v_readlane_b32 s35, v255, 20
	v_readlane_b32 s57, v255, 21
	v_readlane_b32 s58, v255, 22
	v_readlane_b32 s59, v255, 23
	s_mov_b64 s[60:61], 0x80
	s_add_u32 s25, s8, 0xfff80080
	s_addc_u32 s28, s9, -1
	s_add_i32 s30, 0, 0x10000
	s_cmp_eq_u32 s24, 28
	s_cselect_b32 s45, s12, s28
	s_cselect_b32 s44, s13, s25
	s_cselect_b32 s29, s19, s23
	s_cselect_b32 s28, s20, s21
	s_add_i32 s25, 0, 0x14000
	ds_read_b128 v[138:141], v1
	ds_read_b128 v[142:145], v150
	ds_read_b128 v[146:149], v1 offset:2048
	ds_read_b128 v[154:157], v150 offset:2048
	ds_read_b128 v[158:161], v1 offset:16384
	ds_read_b128 v[162:165], v150 offset:16384
	ds_read_b128 v[166:169], v1 offset:18432
	ds_read_b128 v[170:173], v150 offset:18432
	s_add_i32 m0, s46, 0xc000
	ds_read_b128 v[174:177], v151
	ds_read_b128 v[184:187], v151 offset:2048
	ds_read_b128 v[188:191], v152
	ds_read_b128 v[192:195], v152 offset:2048
	ds_read_b128 v[196:199], v151 offset:4096
	ds_read_b128 v[200:203], v151 offset:6144
	ds_read_b128 v[204:207], v152 offset:4096
	ds_read_b128 v[208:211], v152 offset:6144
	global_load_lds_dwordx4 v136, s[8:9]
	s_add_i32 m0, s46, 0xe000
	s_nop 0
	global_load_lds_dwordx4 v134, s[8:9]
	s_waitcnt vmcnt(8)
	s_waitcnt lgkmcnt(0)
	s_barrier
	s_setprio 1
	v_mfma_f32_16x16x32_bf16 v[128:131], v[138:141], v[174:177], 0
	v_mfma_f32_16x16x32_bf16 v[124:127], v[146:149], v[174:177], 0
	v_mfma_f32_16x16x32_bf16 v[112:115], v[138:141], v[184:187], 0
	v_mfma_f32_16x16x32_bf16 v[108:111], v[146:149], v[184:187], 0
	v_mfma_f32_16x16x32_bf16 v[96:99], v[138:141], v[196:199], 0
	v_mfma_f32_16x16x32_bf16 v[92:95], v[146:149], v[196:199], 0
	v_mfma_f32_16x16x32_bf16 v[80:83], v[138:141], v[200:203], 0
	v_mfma_f32_16x16x32_bf16 v[76:79], v[146:149], v[200:203], 0
	v_mfma_f32_16x16x32_bf16 v[128:131], v[142:145], v[188:191], v[128:131]
	v_mfma_f32_16x16x32_bf16 v[124:127], v[154:157], v[188:191], v[124:127]
	v_mfma_f32_16x16x32_bf16 v[112:115], v[142:145], v[192:195], v[112:115]
	v_mfma_f32_16x16x32_bf16 v[108:111], v[154:157], v[192:195], v[108:111]
	v_mfma_f32_16x16x32_bf16 v[96:99], v[142:145], v[204:207], v[96:99]
	v_mfma_f32_16x16x32_bf16 v[92:95], v[154:157], v[204:207], v[92:95]
	v_mfma_f32_16x16x32_bf16 v[80:83], v[142:145], v[208:211], v[80:83]
	v_mfma_f32_16x16x32_bf16 v[76:79], v[154:157], v[208:211], v[76:79]
	v_mfma_f32_16x16x32_bf16 v[120:123], v[158:161], v[174:177], 0
	v_mfma_f32_16x16x32_bf16 v[116:119], v[166:169], v[174:177], 0
	v_mfma_f32_16x16x32_bf16 v[104:107], v[158:161], v[184:187], 0
	v_mfma_f32_16x16x32_bf16 v[100:103], v[166:169], v[184:187], 0
	v_mfma_f32_16x16x32_bf16 v[88:91], v[158:161], v[196:199], 0
	v_mfma_f32_16x16x32_bf16 v[84:87], v[166:169], v[196:199], 0
	v_mfma_f32_16x16x32_bf16 v[72:75], v[158:161], v[200:203], 0
	v_mfma_f32_16x16x32_bf16 v[68:71], v[166:169], v[200:203], 0
	v_mfma_f32_16x16x32_bf16 v[120:123], v[162:165], v[188:191], v[120:123]
	v_mfma_f32_16x16x32_bf16 v[116:119], v[170:173], v[188:191], v[116:119]
	v_mfma_f32_16x16x32_bf16 v[104:107], v[162:165], v[192:195], v[104:107]
	v_mfma_f32_16x16x32_bf16 v[100:103], v[170:173], v[192:195], v[100:103]
	v_mfma_f32_16x16x32_bf16 v[88:91], v[162:165], v[204:207], v[88:91]
	v_mfma_f32_16x16x32_bf16 v[84:87], v[170:173], v[204:207], v[84:87]
	v_mfma_f32_16x16x32_bf16 v[72:75], v[162:165], v[208:211], v[72:75]
	v_mfma_f32_16x16x32_bf16 v[68:71], v[170:173], v[208:211], v[68:71]
	s_setprio 0
	s_barrier
	s_add_i32 s30, s30, s33
	s_mov_b32 m0, s30
	ds_read_b128 v[174:177], v151 offset:16384
	ds_read_b128 v[184:187], v151 offset:18432
	ds_read_b128 v[188:191], v152 offset:16384
	ds_read_b128 v[192:195], v152 offset:18432
	ds_read_b128 v[196:199], v151 offset:20480
	ds_read_b128 v[200:203], v151 offset:22528
	ds_read_b128 v[204:207], v152 offset:20480
	ds_read_b128 v[208:211], v152 offset:22528
	global_load_lds_dwordx4 v34, s[28:29]
	s_add_i32 m0, s30, 0x2000
	s_add_u32 s30, s28, 0x80000
	s_addc_u32 s31, s29, 0
	s_add_i32 s25, s25, s33
	global_load_lds_dwordx4 v132, s[28:29]
	s_mov_b32 m0, s25
	s_nop 0
	global_load_lds_dwordx4 v34, s[30:31]
	s_add_i32 m0, s25, 0x2000
	s_nop 0
	global_load_lds_dwordx4 v132, s[30:31]
	s_mov_b32 m0, s46
	s_nop 0
	global_load_lds_dwordx4 v136, s[44:45]
	s_mov_b32 m0, s47
	s_nop 0
	global_load_lds_dwordx4 v134, s[44:45]
	s_waitcnt vmcnt(8)
	s_waitcnt lgkmcnt(0)
	s_barrier
	s_setprio 1
	v_mfma_f32_16x16x32_bf16 v[64:67], v[138:141], v[174:177], 0
	v_mfma_f32_16x16x32_bf16 v[60:63], v[146:149], v[174:177], 0
	v_mfma_f32_16x16x32_bf16 v[48:51], v[138:141], v[184:187], 0
	v_mfma_f32_16x16x32_bf16 v[44:47], v[146:149], v[184:187], 0
	v_mfma_f32_16x16x32_bf16 v[30:33], v[138:141], v[196:199], 0
	v_mfma_f32_16x16x32_bf16 v[26:29], v[146:149], v[196:199], 0
	v_mfma_f32_16x16x32_bf16 v[14:17], v[138:141], v[200:203], 0
	v_mfma_f32_16x16x32_bf16 v[10:13], v[146:149], v[200:203], 0
	v_mfma_f32_16x16x32_bf16 v[64:67], v[142:145], v[188:191], v[64:67]
	v_mfma_f32_16x16x32_bf16 v[60:63], v[154:157], v[188:191], v[60:63]
	v_mfma_f32_16x16x32_bf16 v[48:51], v[142:145], v[192:195], v[48:51]
	v_mfma_f32_16x16x32_bf16 v[44:47], v[154:157], v[192:195], v[44:47]
	v_mfma_f32_16x16x32_bf16 v[30:33], v[142:145], v[204:207], v[30:33]
	v_mfma_f32_16x16x32_bf16 v[26:29], v[154:157], v[204:207], v[26:29]
	v_mfma_f32_16x16x32_bf16 v[14:17], v[142:145], v[208:211], v[14:17]
	v_mfma_f32_16x16x32_bf16 v[10:13], v[154:157], v[208:211], v[10:13]
	v_mfma_f32_16x16x32_bf16 v[56:59], v[158:161], v[174:177], 0
	v_mfma_f32_16x16x32_bf16 v[52:55], v[166:169], v[174:177], 0
	v_mfma_f32_16x16x32_bf16 v[40:43], v[158:161], v[184:187], 0
	v_mfma_f32_16x16x32_bf16 v[36:39], v[166:169], v[184:187], 0
	v_mfma_f32_16x16x32_bf16 v[22:25], v[158:161], v[196:199], 0
	v_mfma_f32_16x16x32_bf16 v[18:21], v[166:169], v[196:199], 0
	v_mfma_f32_16x16x32_bf16 v[6:9], v[158:161], v[200:203], 0
	v_mfma_f32_16x16x32_bf16 v[2:5], v[166:169], v[200:203], 0
	v_mfma_f32_16x16x32_bf16 v[56:59], v[162:165], v[188:191], v[56:59]
	v_mfma_f32_16x16x32_bf16 v[52:55], v[170:173], v[188:191], v[52:55]
	v_mfma_f32_16x16x32_bf16 v[40:43], v[162:165], v[192:195], v[40:43]
	v_mfma_f32_16x16x32_bf16 v[36:39], v[170:173], v[192:195], v[36:39]
	v_mfma_f32_16x16x32_bf16 v[22:25], v[162:165], v[204:207], v[22:25]
	v_mfma_f32_16x16x32_bf16 v[18:21], v[170:173], v[204:207], v[18:21]
	v_mfma_f32_16x16x32_bf16 v[6:9], v[162:165], v[208:211], v[6:9]
	v_mfma_f32_16x16x32_bf16 v[2:5], v[170:173], v[208:211], v[2:5]
	s_setprio 0
	s_barrier
	s_add_i32 s25, 0, 0x18000
	s_add_i32 s34, 0, 0x1c000
	ds_read_b128 v[138:141], v1 offset:32768
	ds_read_b128 v[142:145], v150 offset:32768
	ds_read_b128 v[146:149], v1 offset:34816
	ds_read_b128 v[154:157], v150 offset:34816
	ds_read_b128 v[158:161], v1 offset:49152
	ds_read_b128 v[162:165], v150 offset:49152
	ds_read_b128 v[166:169], v1 offset:51200
	ds_read_b128 v[170:173], v150 offset:51200
	s_add_u32 s30, s44, 0x80000
	s_addc_u32 s31, s45, 0
	s_mov_b32 m0, s48
	ds_read_b128 v[174:177], v151 offset:32768
	ds_read_b128 v[184:187], v151 offset:34816
	ds_read_b128 v[188:191], v152 offset:32768
	ds_read_b128 v[192:195], v152 offset:34816
	ds_read_b128 v[196:199], v151 offset:36864
	ds_read_b128 v[200:203], v151 offset:38912
	ds_read_b128 v[204:207], v152 offset:36864
	ds_read_b128 v[208:211], v152 offset:38912
	global_load_lds_dwordx4 v136, s[30:31]
	s_mov_b32 m0, s49
	s_nop 0
	global_load_lds_dwordx4 v134, s[30:31]
	s_waitcnt vmcnt(8)
	s_waitcnt lgkmcnt(0)
	s_barrier
	s_setprio 1
	v_mfma_f32_16x16x32_bf16 v[128:131], v[138:141], v[174:177], v[128:131]
	v_mfma_f32_16x16x32_bf16 v[124:127], v[146:149], v[174:177], v[124:127]
	v_mfma_f32_16x16x32_bf16 v[112:115], v[138:141], v[184:187], v[112:115]
	v_mfma_f32_16x16x32_bf16 v[108:111], v[146:149], v[184:187], v[108:111]
	v_mfma_f32_16x16x32_bf16 v[96:99], v[138:141], v[196:199], v[96:99]
	v_mfma_f32_16x16x32_bf16 v[92:95], v[146:149], v[196:199], v[92:95]
	v_mfma_f32_16x16x32_bf16 v[80:83], v[138:141], v[200:203], v[80:83]
	v_mfma_f32_16x16x32_bf16 v[76:79], v[146:149], v[200:203], v[76:79]
	v_mfma_f32_16x16x32_bf16 v[128:131], v[142:145], v[188:191], v[128:131]
	v_mfma_f32_16x16x32_bf16 v[124:127], v[154:157], v[188:191], v[124:127]
	v_mfma_f32_16x16x32_bf16 v[112:115], v[142:145], v[192:195], v[112:115]
	v_mfma_f32_16x16x32_bf16 v[108:111], v[154:157], v[192:195], v[108:111]
	v_mfma_f32_16x16x32_bf16 v[96:99], v[142:145], v[204:207], v[96:99]
	v_mfma_f32_16x16x32_bf16 v[92:95], v[154:157], v[204:207], v[92:95]
	v_mfma_f32_16x16x32_bf16 v[80:83], v[142:145], v[208:211], v[80:83]
	v_mfma_f32_16x16x32_bf16 v[76:79], v[154:157], v[208:211], v[76:79]
	v_mfma_f32_16x16x32_bf16 v[120:123], v[158:161], v[174:177], v[120:123]
	v_mfma_f32_16x16x32_bf16 v[116:119], v[166:169], v[174:177], v[116:119]
	v_mfma_f32_16x16x32_bf16 v[104:107], v[158:161], v[184:187], v[104:107]
	v_mfma_f32_16x16x32_bf16 v[100:103], v[166:169], v[184:187], v[100:103]
	v_mfma_f32_16x16x32_bf16 v[88:91], v[158:161], v[196:199], v[88:91]
	v_mfma_f32_16x16x32_bf16 v[84:87], v[166:169], v[196:199], v[84:87]
	v_mfma_f32_16x16x32_bf16 v[72:75], v[158:161], v[200:203], v[72:75]
	v_mfma_f32_16x16x32_bf16 v[68:71], v[166:169], v[200:203], v[68:71]
	v_mfma_f32_16x16x32_bf16 v[120:123], v[162:165], v[188:191], v[120:123]
	v_mfma_f32_16x16x32_bf16 v[116:119], v[170:173], v[188:191], v[116:119]
	v_mfma_f32_16x16x32_bf16 v[104:107], v[162:165], v[192:195], v[104:107]
	v_mfma_f32_16x16x32_bf16 v[100:103], v[170:173], v[192:195], v[100:103]
	v_mfma_f32_16x16x32_bf16 v[88:91], v[162:165], v[204:207], v[88:91]
	v_mfma_f32_16x16x32_bf16 v[84:87], v[170:173], v[204:207], v[84:87]
	v_mfma_f32_16x16x32_bf16 v[72:75], v[162:165], v[208:211], v[72:75]
	v_mfma_f32_16x16x32_bf16 v[68:71], v[170:173], v[208:211], v[68:71]
	s_setprio 0
	s_barrier
	s_add_i32 s25, s25, s33
	s_add_i32 m0, s25, 0xffffff80
	ds_read_b128 v[174:177], v151 offset:49152
	ds_read_b128 v[184:187], v151 offset:51200
	ds_read_b128 v[188:191], v152 offset:49152
	ds_read_b128 v[192:195], v152 offset:51200
	ds_read_b128 v[196:199], v151 offset:53248
	ds_read_b128 v[200:203], v151 offset:55296
	ds_read_b128 v[204:207], v152 offset:53248
	ds_read_b128 v[208:211], v152 offset:55296
	global_load_lds_dwordx4 v34, s[28:29] offset:128
	s_add_i32 m0, s25, 0x1f80
	s_mov_b64 s[98:99], s[28:29]
	s_add_u32 s28, s28, 0x80080
	s_addc_u32 s29, s29, 0
	s_add_i32 s25, s34, s33
	global_load_lds_dwordx4 v132, s[98:99] offset:128
	s_mov_b32 m0, s25
	s_nop 0
	global_load_lds_dwordx4 v34, s[28:29]
	s_add_i32 m0, s25, 0x2000
	s_nop 0
	global_load_lds_dwordx4 v132, s[28:29]
	s_add_i32 m0, s52, 0xffffff80
	s_nop 0
	global_load_lds_dwordx4 v136, s[44:45] offset:128
	s_add_i32 m0, s53, 0xffffff80
	s_nop 0
	global_load_lds_dwordx4 v134, s[44:45] offset:128
	s_waitcnt vmcnt(8)
	s_waitcnt lgkmcnt(0)
	s_barrier
	s_setprio 1
	v_mfma_f32_16x16x32_bf16 v[64:67], v[138:141], v[174:177], v[64:67]
	v_mfma_f32_16x16x32_bf16 v[60:63], v[146:149], v[174:177], v[60:63]
	v_mfma_f32_16x16x32_bf16 v[48:51], v[138:141], v[184:187], v[48:51]
	v_mfma_f32_16x16x32_bf16 v[44:47], v[146:149], v[184:187], v[44:47]
	v_mfma_f32_16x16x32_bf16 v[30:33], v[138:141], v[196:199], v[30:33]
	v_mfma_f32_16x16x32_bf16 v[26:29], v[146:149], v[196:199], v[26:29]
	v_mfma_f32_16x16x32_bf16 v[14:17], v[138:141], v[200:203], v[14:17]
	v_mfma_f32_16x16x32_bf16 v[10:13], v[146:149], v[200:203], v[10:13]
	v_mfma_f32_16x16x32_bf16 v[64:67], v[142:145], v[188:191], v[64:67]
	v_mfma_f32_16x16x32_bf16 v[60:63], v[154:157], v[188:191], v[60:63]
	v_mfma_f32_16x16x32_bf16 v[48:51], v[142:145], v[192:195], v[48:51]
	v_mfma_f32_16x16x32_bf16 v[44:47], v[154:157], v[192:195], v[44:47]
	v_mfma_f32_16x16x32_bf16 v[30:33], v[142:145], v[204:207], v[30:33]
	v_mfma_f32_16x16x32_bf16 v[26:29], v[154:157], v[204:207], v[26:29]
	v_mfma_f32_16x16x32_bf16 v[14:17], v[142:145], v[208:211], v[14:17]
	v_mfma_f32_16x16x32_bf16 v[10:13], v[154:157], v[208:211], v[10:13]
	v_mfma_f32_16x16x32_bf16 v[56:59], v[158:161], v[174:177], v[56:59]
	v_mfma_f32_16x16x32_bf16 v[52:55], v[166:169], v[174:177], v[52:55]
	v_mfma_f32_16x16x32_bf16 v[40:43], v[158:161], v[184:187], v[40:43]
	v_mfma_f32_16x16x32_bf16 v[36:39], v[166:169], v[184:187], v[36:39]
	v_mfma_f32_16x16x32_bf16 v[22:25], v[158:161], v[196:199], v[22:25]
	v_mfma_f32_16x16x32_bf16 v[18:21], v[166:169], v[196:199], v[18:21]
	v_mfma_f32_16x16x32_bf16 v[6:9], v[158:161], v[200:203], v[6:9]
	v_mfma_f32_16x16x32_bf16 v[2:5], v[166:169], v[200:203], v[2:5]
	v_mfma_f32_16x16x32_bf16 v[56:59], v[162:165], v[188:191], v[56:59]
	v_mfma_f32_16x16x32_bf16 v[52:55], v[170:173], v[188:191], v[52:55]
	v_mfma_f32_16x16x32_bf16 v[40:43], v[162:165], v[192:195], v[40:43]
	v_mfma_f32_16x16x32_bf16 v[36:39], v[170:173], v[192:195], v[36:39]
	v_mfma_f32_16x16x32_bf16 v[22:25], v[162:165], v[204:207], v[22:25]
	v_mfma_f32_16x16x32_bf16 v[18:21], v[170:173], v[204:207], v[18:21]
	v_mfma_f32_16x16x32_bf16 v[6:9], v[162:165], v[208:211], v[6:9]
	v_mfma_f32_16x16x32_bf16 v[2:5], v[170:173], v[208:211], v[2:5]
	s_setprio 0
	s_barrier
	s_add_i32 s24, s24, 2
	s_add_u32 s8, s8, 0x100
	s_addc_u32 s9, s9, 0
	s_add_u32 s21, s21, 0x100
	s_addc_u32 s23, s23, 0
	s_cmp_gt_u32 s24, 29
	s_cbranch_scc1 .Lpeel_done_P4
.LBB0_1023:
	s_add_u32 s25, s8, 0xfff80080
	s_addc_u32 s28, s9, -1
	s_add_i32 s30, 0, 0x10000
	s_cmp_eq_u32 s24, 28
	s_cselect_b32 s45, s12, s28
	s_cselect_b32 s44, s13, s25
	s_cselect_b32 s29, s19, s23
	s_cselect_b32 s28, s20, s21
	s_add_i32 s25, 0, 0x14000
	ds_read_b128 v[138:141], v1
	ds_read_b128 v[142:145], v150
	ds_read_b128 v[146:149], v1 offset:2048
	ds_read_b128 v[154:157], v150 offset:2048
	ds_read_b128 v[158:161], v1 offset:16384
	ds_read_b128 v[162:165], v150 offset:16384
	ds_read_b128 v[166:169], v1 offset:18432
	ds_read_b128 v[170:173], v150 offset:18432
	s_add_i32 m0, s46, 0xc000
	ds_read_b128 v[174:177], v151
	ds_read_b128 v[184:187], v151 offset:2048
	ds_read_b128 v[188:191], v152
	ds_read_b128 v[192:195], v152 offset:2048
	ds_read_b128 v[196:199], v151 offset:4096
	ds_read_b128 v[200:203], v151 offset:6144
	ds_read_b128 v[204:207], v152 offset:4096
	ds_read_b128 v[208:211], v152 offset:6144
	global_load_lds_dwordx4 v136, s[8:9]
	s_add_i32 m0, s46, 0xe000
	s_nop 0
	global_load_lds_dwordx4 v134, s[8:9]
	s_waitcnt vmcnt(8)
	s_waitcnt lgkmcnt(0)
	s_barrier
	s_setprio 1
	v_mfma_f32_16x16x32_bf16 v[128:131], v[138:141], v[174:177], v[128:131]
	v_mfma_f32_16x16x32_bf16 v[124:127], v[146:149], v[174:177], v[124:127]
	v_mfma_f32_16x16x32_bf16 v[112:115], v[138:141], v[184:187], v[112:115]
	v_mfma_f32_16x16x32_bf16 v[108:111], v[146:149], v[184:187], v[108:111]
	v_mfma_f32_16x16x32_bf16 v[96:99], v[138:141], v[196:199], v[96:99]
	v_mfma_f32_16x16x32_bf16 v[92:95], v[146:149], v[196:199], v[92:95]
	v_mfma_f32_16x16x32_bf16 v[80:83], v[138:141], v[200:203], v[80:83]
	v_mfma_f32_16x16x32_bf16 v[76:79], v[146:149], v[200:203], v[76:79]
	v_mfma_f32_16x16x32_bf16 v[128:131], v[142:145], v[188:191], v[128:131]
	v_mfma_f32_16x16x32_bf16 v[124:127], v[154:157], v[188:191], v[124:127]
	v_mfma_f32_16x16x32_bf16 v[112:115], v[142:145], v[192:195], v[112:115]
	v_mfma_f32_16x16x32_bf16 v[108:111], v[154:157], v[192:195], v[108:111]
	v_mfma_f32_16x16x32_bf16 v[96:99], v[142:145], v[204:207], v[96:99]
	v_mfma_f32_16x16x32_bf16 v[92:95], v[154:157], v[204:207], v[92:95]
	v_mfma_f32_16x16x32_bf16 v[80:83], v[142:145], v[208:211], v[80:83]
	v_mfma_f32_16x16x32_bf16 v[76:79], v[154:157], v[208:211], v[76:79]
	v_mfma_f32_16x16x32_bf16 v[120:123], v[158:161], v[174:177], v[120:123]
	v_mfma_f32_16x16x32_bf16 v[116:119], v[166:169], v[174:177], v[116:119]
	v_mfma_f32_16x16x32_bf16 v[104:107], v[158:161], v[184:187], v[104:107]
	v_mfma_f32_16x16x32_bf16 v[100:103], v[166:169], v[184:187], v[100:103]
	v_mfma_f32_16x16x32_bf16 v[88:91], v[158:161], v[196:199], v[88:91]
	v_mfma_f32_16x16x32_bf16 v[84:87], v[166:169], v[196:199], v[84:87]
	v_mfma_f32_16x16x32_bf16 v[72:75], v[158:161], v[200:203], v[72:75]
	v_mfma_f32_16x16x32_bf16 v[68:71], v[166:169], v[200:203], v[68:71]
	v_mfma_f32_16x16x32_bf16 v[120:123], v[162:165], v[188:191], v[120:123]
	v_mfma_f32_16x16x32_bf16 v[116:119], v[170:173], v[188:191], v[116:119]
	v_mfma_f32_16x16x32_bf16 v[104:107], v[162:165], v[192:195], v[104:107]
	v_mfma_f32_16x16x32_bf16 v[100:103], v[170:173], v[192:195], v[100:103]
	v_mfma_f32_16x16x32_bf16 v[88:91], v[162:165], v[204:207], v[88:91]
	v_mfma_f32_16x16x32_bf16 v[84:87], v[170:173], v[204:207], v[84:87]
	v_mfma_f32_16x16x32_bf16 v[72:75], v[162:165], v[208:211], v[72:75]
	v_mfma_f32_16x16x32_bf16 v[68:71], v[170:173], v[208:211], v[68:71]
	s_setprio 0
	s_barrier
	s_add_i32 s30, s30, s33
	s_mov_b32 m0, s30
	ds_read_b128 v[174:177], v151 offset:16384
	ds_read_b128 v[184:187], v151 offset:18432
	ds_read_b128 v[188:191], v152 offset:16384
	ds_read_b128 v[192:195], v152 offset:18432
	ds_read_b128 v[196:199], v151 offset:20480
	ds_read_b128 v[200:203], v151 offset:22528
	ds_read_b128 v[204:207], v152 offset:20480
	ds_read_b128 v[208:211], v152 offset:22528
	global_load_lds_dwordx4 v34, s[28:29]
	s_add_i32 m0, s30, 0x2000
	s_add_u32 s30, s28, 0x80000
	s_addc_u32 s31, s29, 0
	s_add_i32 s25, s25, s33
	global_load_lds_dwordx4 v132, s[28:29]
	s_mov_b32 m0, s25
	s_nop 0
	global_load_lds_dwordx4 v34, s[30:31]
	s_add_i32 m0, s25, 0x2000
	s_nop 0
	global_load_lds_dwordx4 v132, s[30:31]
	s_mov_b32 m0, s46
	s_nop 0
	global_load_lds_dwordx4 v136, s[44:45]
	s_mov_b32 m0, s47
	s_nop 0
	global_load_lds_dwordx4 v134, s[44:45]
	s_waitcnt vmcnt(8)
	s_waitcnt lgkmcnt(0)
	s_barrier
	s_setprio 1
	v_mfma_f32_16x16x32_bf16 v[64:67], v[138:141], v[174:177], v[64:67]
	v_mfma_f32_16x16x32_bf16 v[60:63], v[146:149], v[174:177], v[60:63]
	v_mfma_f32_16x16x32_bf16 v[48:51], v[138:141], v[184:187], v[48:51]
	v_mfma_f32_16x16x32_bf16 v[44:47], v[146:149], v[184:187], v[44:47]
	v_mfma_f32_16x16x32_bf16 v[30:33], v[138:141], v[196:199], v[30:33]
	v_mfma_f32_16x16x32_bf16 v[26:29], v[146:149], v[196:199], v[26:29]
	v_mfma_f32_16x16x32_bf16 v[14:17], v[138:141], v[200:203], v[14:17]
	v_mfma_f32_16x16x32_bf16 v[10:13], v[146:149], v[200:203], v[10:13]
	v_mfma_f32_16x16x32_bf16 v[64:67], v[142:145], v[188:191], v[64:67]
	v_mfma_f32_16x16x32_bf16 v[60:63], v[154:157], v[188:191], v[60:63]
	v_mfma_f32_16x16x32_bf16 v[48:51], v[142:145], v[192:195], v[48:51]
	v_mfma_f32_16x16x32_bf16 v[44:47], v[154:157], v[192:195], v[44:47]
	v_mfma_f32_16x16x32_bf16 v[30:33], v[142:145], v[204:207], v[30:33]
	v_mfma_f32_16x16x32_bf16 v[26:29], v[154:157], v[204:207], v[26:29]
	v_mfma_f32_16x16x32_bf16 v[14:17], v[142:145], v[208:211], v[14:17]
	v_mfma_f32_16x16x32_bf16 v[10:13], v[154:157], v[208:211], v[10:13]
	v_mfma_f32_16x16x32_bf16 v[56:59], v[158:161], v[174:177], v[56:59]
	v_mfma_f32_16x16x32_bf16 v[52:55], v[166:169], v[174:177], v[52:55]
	v_mfma_f32_16x16x32_bf16 v[40:43], v[158:161], v[184:187], v[40:43]
	v_mfma_f32_16x16x32_bf16 v[36:39], v[166:169], v[184:187], v[36:39]
	v_mfma_f32_16x16x32_bf16 v[22:25], v[158:161], v[196:199], v[22:25]
	v_mfma_f32_16x16x32_bf16 v[18:21], v[166:169], v[196:199], v[18:21]
	v_mfma_f32_16x16x32_bf16 v[6:9], v[158:161], v[200:203], v[6:9]
	v_mfma_f32_16x16x32_bf16 v[2:5], v[166:169], v[200:203], v[2:5]
	v_mfma_f32_16x16x32_bf16 v[56:59], v[162:165], v[188:191], v[56:59]
	v_mfma_f32_16x16x32_bf16 v[52:55], v[170:173], v[188:191], v[52:55]
	v_mfma_f32_16x16x32_bf16 v[40:43], v[162:165], v[192:195], v[40:43]
	v_mfma_f32_16x16x32_bf16 v[36:39], v[170:173], v[192:195], v[36:39]
	v_mfma_f32_16x16x32_bf16 v[22:25], v[162:165], v[204:207], v[22:25]
	v_mfma_f32_16x16x32_bf16 v[18:21], v[170:173], v[204:207], v[18:21]
	v_mfma_f32_16x16x32_bf16 v[6:9], v[162:165], v[208:211], v[6:9]
	v_mfma_f32_16x16x32_bf16 v[2:5], v[170:173], v[208:211], v[2:5]
	s_setprio 0
	s_barrier
	s_add_i32 s25, 0, 0x18000
	s_add_i32 s34, 0, 0x1c000
	ds_read_b128 v[138:141], v1 offset:32768
	ds_read_b128 v[142:145], v150 offset:32768
	ds_read_b128 v[146:149], v1 offset:34816
	ds_read_b128 v[154:157], v150 offset:34816
	ds_read_b128 v[158:161], v1 offset:49152
	ds_read_b128 v[162:165], v150 offset:49152
	ds_read_b128 v[166:169], v1 offset:51200
	ds_read_b128 v[170:173], v150 offset:51200
	s_add_u32 s30, s44, 0x80000
	s_addc_u32 s31, s45, 0
	s_mov_b32 m0, s48
	ds_read_b128 v[174:177], v151 offset:32768
	ds_read_b128 v[184:187], v151 offset:34816
	ds_read_b128 v[188:191], v152 offset:32768
	ds_read_b128 v[192:195], v152 offset:34816
	ds_read_b128 v[196:199], v151 offset:36864
	ds_read_b128 v[200:203], v151 offset:38912
	ds_read_b128 v[204:207], v152 offset:36864
	ds_read_b128 v[208:211], v152 offset:38912
	global_load_lds_dwordx4 v136, s[30:31]
	s_mov_b32 m0, s49
	s_nop 0
	global_load_lds_dwordx4 v134, s[30:31]
	s_waitcnt vmcnt(8)
	s_waitcnt lgkmcnt(0)
	s_barrier
	s_setprio 1
	v_mfma_f32_16x16x32_bf16 v[128:131], v[138:141], v[174:177], v[128:131]
	v_mfma_f32_16x16x32_bf16 v[124:127], v[146:149], v[174:177], v[124:127]
	v_mfma_f32_16x16x32_bf16 v[112:115], v[138:141], v[184:187], v[112:115]
	v_mfma_f32_16x16x32_bf16 v[108:111], v[146:149], v[184:187], v[108:111]
	v_mfma_f32_16x16x32_bf16 v[96:99], v[138:141], v[196:199], v[96:99]
	v_mfma_f32_16x16x32_bf16 v[92:95], v[146:149], v[196:199], v[92:95]
	v_mfma_f32_16x16x32_bf16 v[80:83], v[138:141], v[200:203], v[80:83]
	v_mfma_f32_16x16x32_bf16 v[76:79], v[146:149], v[200:203], v[76:79]
	v_mfma_f32_16x16x32_bf16 v[128:131], v[142:145], v[188:191], v[128:131]
	v_mfma_f32_16x16x32_bf16 v[124:127], v[154:157], v[188:191], v[124:127]
	v_mfma_f32_16x16x32_bf16 v[112:115], v[142:145], v[192:195], v[112:115]
	v_mfma_f32_16x16x32_bf16 v[108:111], v[154:157], v[192:195], v[108:111]
	v_mfma_f32_16x16x32_bf16 v[96:99], v[142:145], v[204:207], v[96:99]
	v_mfma_f32_16x16x32_bf16 v[92:95], v[154:157], v[204:207], v[92:95]
	v_mfma_f32_16x16x32_bf16 v[80:83], v[142:145], v[208:211], v[80:83]
	v_mfma_f32_16x16x32_bf16 v[76:79], v[154:157], v[208:211], v[76:79]
	v_mfma_f32_16x16x32_bf16 v[120:123], v[158:161], v[174:177], v[120:123]
	v_mfma_f32_16x16x32_bf16 v[116:119], v[166:169], v[174:177], v[116:119]
	v_mfma_f32_16x16x32_bf16 v[104:107], v[158:161], v[184:187], v[104:107]
	v_mfma_f32_16x16x32_bf16 v[100:103], v[166:169], v[184:187], v[100:103]
	v_mfma_f32_16x16x32_bf16 v[88:91], v[158:161], v[196:199], v[88:91]
	v_mfma_f32_16x16x32_bf16 v[84:87], v[166:169], v[196:199], v[84:87]
	v_mfma_f32_16x16x32_bf16 v[72:75], v[158:161], v[200:203], v[72:75]
	v_mfma_f32_16x16x32_bf16 v[68:71], v[166:169], v[200:203], v[68:71]
	v_mfma_f32_16x16x32_bf16 v[120:123], v[162:165], v[188:191], v[120:123]
	v_mfma_f32_16x16x32_bf16 v[116:119], v[170:173], v[188:191], v[116:119]
	v_mfma_f32_16x16x32_bf16 v[104:107], v[162:165], v[192:195], v[104:107]
	v_mfma_f32_16x16x32_bf16 v[100:103], v[170:173], v[192:195], v[100:103]
	v_mfma_f32_16x16x32_bf16 v[88:91], v[162:165], v[204:207], v[88:91]
	v_mfma_f32_16x16x32_bf16 v[84:87], v[170:173], v[204:207], v[84:87]
	v_mfma_f32_16x16x32_bf16 v[72:75], v[162:165], v[208:211], v[72:75]
	v_mfma_f32_16x16x32_bf16 v[68:71], v[170:173], v[208:211], v[68:71]
	s_setprio 0
	s_barrier
	s_add_i32 s25, s25, s33
	s_add_i32 m0, s25, 0xffffff80
	ds_read_b128 v[174:177], v151 offset:49152
	ds_read_b128 v[184:187], v151 offset:51200
	ds_read_b128 v[188:191], v152 offset:49152
	ds_read_b128 v[192:195], v152 offset:51200
	ds_read_b128 v[196:199], v151 offset:53248
	ds_read_b128 v[200:203], v151 offset:55296
	ds_read_b128 v[204:207], v152 offset:53248
	ds_read_b128 v[208:211], v152 offset:55296
	global_load_lds_dwordx4 v34, s[28:29] offset:128
	s_add_i32 m0, s25, 0x1f80
	s_mov_b64 s[98:99], s[28:29]
	s_add_u32 s28, s28, 0x80080
	s_addc_u32 s29, s29, 0
	s_add_i32 s25, s34, s33
	global_load_lds_dwordx4 v132, s[98:99] offset:128
	s_mov_b32 m0, s25
	s_nop 0
	global_load_lds_dwordx4 v34, s[28:29]
	s_add_i32 m0, s25, 0x2000
	s_nop 0
	global_load_lds_dwordx4 v132, s[28:29]
	s_add_i32 m0, s52, 0xffffff80
	s_nop 0
	global_load_lds_dwordx4 v136, s[44:45] offset:128
	s_add_i32 m0, s53, 0xffffff80
	s_nop 0
	global_load_lds_dwordx4 v134, s[44:45] offset:128
	s_waitcnt vmcnt(8)
	s_waitcnt lgkmcnt(0)
	s_barrier
	s_setprio 1
	v_mfma_f32_16x16x32_bf16 v[64:67], v[138:141], v[174:177], v[64:67]
	v_mfma_f32_16x16x32_bf16 v[60:63], v[146:149], v[174:177], v[60:63]
	v_mfma_f32_16x16x32_bf16 v[48:51], v[138:141], v[184:187], v[48:51]
	v_mfma_f32_16x16x32_bf16 v[44:47], v[146:149], v[184:187], v[44:47]
	v_mfma_f32_16x16x32_bf16 v[30:33], v[138:141], v[196:199], v[30:33]
	v_mfma_f32_16x16x32_bf16 v[26:29], v[146:149], v[196:199], v[26:29]
	v_mfma_f32_16x16x32_bf16 v[14:17], v[138:141], v[200:203], v[14:17]
	v_mfma_f32_16x16x32_bf16 v[10:13], v[146:149], v[200:203], v[10:13]
	v_mfma_f32_16x16x32_bf16 v[64:67], v[142:145], v[188:191], v[64:67]
	v_mfma_f32_16x16x32_bf16 v[60:63], v[154:157], v[188:191], v[60:63]
	v_mfma_f32_16x16x32_bf16 v[48:51], v[142:145], v[192:195], v[48:51]
	v_mfma_f32_16x16x32_bf16 v[44:47], v[154:157], v[192:195], v[44:47]
	v_mfma_f32_16x16x32_bf16 v[30:33], v[142:145], v[204:207], v[30:33]
	v_mfma_f32_16x16x32_bf16 v[26:29], v[154:157], v[204:207], v[26:29]
	v_mfma_f32_16x16x32_bf16 v[14:17], v[142:145], v[208:211], v[14:17]
	v_mfma_f32_16x16x32_bf16 v[10:13], v[154:157], v[208:211], v[10:13]
	v_mfma_f32_16x16x32_bf16 v[56:59], v[158:161], v[174:177], v[56:59]
	v_mfma_f32_16x16x32_bf16 v[52:55], v[166:169], v[174:177], v[52:55]
	v_mfma_f32_16x16x32_bf16 v[40:43], v[158:161], v[184:187], v[40:43]
	v_mfma_f32_16x16x32_bf16 v[36:39], v[166:169], v[184:187], v[36:39]
	v_mfma_f32_16x16x32_bf16 v[22:25], v[158:161], v[196:199], v[22:25]
	v_mfma_f32_16x16x32_bf16 v[18:21], v[166:169], v[196:199], v[18:21]
	v_mfma_f32_16x16x32_bf16 v[6:9], v[158:161], v[200:203], v[6:9]
	v_mfma_f32_16x16x32_bf16 v[2:5], v[166:169], v[200:203], v[2:5]
	v_mfma_f32_16x16x32_bf16 v[56:59], v[162:165], v[188:191], v[56:59]
	v_mfma_f32_16x16x32_bf16 v[52:55], v[170:173], v[188:191], v[52:55]
	v_mfma_f32_16x16x32_bf16 v[40:43], v[162:165], v[192:195], v[40:43]
	v_mfma_f32_16x16x32_bf16 v[36:39], v[170:173], v[192:195], v[36:39]
	v_mfma_f32_16x16x32_bf16 v[22:25], v[162:165], v[204:207], v[22:25]
	v_mfma_f32_16x16x32_bf16 v[18:21], v[170:173], v[204:207], v[18:21]
	v_mfma_f32_16x16x32_bf16 v[6:9], v[162:165], v[208:211], v[6:9]
	v_mfma_f32_16x16x32_bf16 v[2:5], v[170:173], v[208:211], v[2:5]
	s_setprio 0
	s_barrier
	s_add_i32 s24, s24, 2
	s_add_u32 s8, s8, 0x100
	s_addc_u32 s9, s9, 0
	s_add_u32 s21, s21, 0x100
	s_addc_u32 s23, s23, 0
	s_cmp_gt_u32 s24, 29
	s_cbranch_scc0 .LBB0_1023

.LBB0_1113:
	s_ashr_i32 s19, s18, 31
	s_lshl_b64 s[20:21], s[18:19], 20
	v_readlane_b32 s22, v254, 38
	v_readlane_b32 s23, v254, 39
	s_add_u32 s22, s22, s20
	s_addc_u32 s23, s23, s21
	s_and_b64 s[20:21], s[38:39], exec
	s_cselect_b32 s13, s23, s9
	s_cselect_b32 s19, s22, s8
	s_ashr_i32 s11, s10, 31
	s_lshl_b64 s[20:21], s[10:11], 20
	v_readlane_b32 s30, v254, 8
	v_readlane_b32 s31, v254, 9
	s_add_u32 s40, s30, s20
	s_addc_u32 s41, s31, s21
	v_mov_b32_e32 v2, v0
	s_and_b64 s[20:21], s[38:39], exec
	s_cselect_b32 s20, s41, s29
	s_cselect_b32 s21, s40, s28
	s_lshl_b32 s11, s24, 8
	v_and_or_b32 v2, v2, 63, s50
	v_or_b32_e32 v2, s11, v2
	v_ashrrev_i32_e32 v3, 31, v2
	v_readlane_b32 s24, v252, 61
	v_lshlrev_b64 v[2:3], 5, v[2:3]
	v_readlane_b32 s25, v252, 62
	s_add_u32 s8, s8, 0x80080
	s_addc_u32 s9, s9, 0
	v_lshl_add_u64 v[2:3], s[24:25], 0, v[2:3]
	global_load_dwordx4 v[116:119], v[2:3], off offset:16
	global_load_dwordx4 v[120:123], v[2:3], off
	s_add_u32 s24, s28, 0x100
	s_addc_u32 s25, s29, 0
	s_mov_b32 s30, -2
	v_readlane_b32 s57, v255, 20
	v_readlane_b32 s58, v255, 21
	v_readlane_b32 s59, v255, 22
	v_readlane_b32 s60, v255, 23
	s_mov_b64 s[62:63], 0x80
	s_add_u32 s28, s8, 0xfff80080
	s_addc_u32 s29, s9, -1
	s_add_i32 s31, 0, 0x10000
	s_cmp_eq_u32 s30, 28
	s_cselect_b32 s43, s13, s29
	s_cselect_b32 s42, s19, s28
	ds_read_b128 v[150:153], v1
	ds_read_b128 v[154:157], v146
	s_cselect_b32 s29, s20, s25
	s_cselect_b32 s28, s21, s24
	s_add_i32 s56, 0, 0x14000
	ds_read_b128 v[158:161], v1 offset:2048
	ds_read_b128 v[162:165], v146 offset:2048
	ds_read_b128 v[166:169], v1 offset:16384
	ds_read_b128 v[170:173], v146 offset:16384
	ds_read_b128 v[174:177], v1 offset:18432
	ds_read_b128 v[184:187], v146 offset:18432
	s_add_i32 m0, s34, 0xc000
	ds_read_b128 v[188:191], v147
	ds_read_b128 v[192:195], v147 offset:2048
	ds_read_b128 v[196:199], v148
	ds_read_b128 v[200:203], v148 offset:2048
	ds_read_b128 v[204:207], v147 offset:4096
	ds_read_b128 v[208:211], v147 offset:6144
	ds_read_b128 v[224:227], v148 offset:4096
	ds_read_b128 v[228:231], v148 offset:6144
	global_load_lds_dwordx4 v144, s[8:9]
	s_add_i32 m0, s34, 0xe000
	s_nop 0
	global_load_lds_dwordx4 v142, s[8:9]
	s_waitcnt vmcnt(8)
	s_waitcnt lgkmcnt(0)
	s_barrier
	s_setprio 1
	v_mfma_f32_16x16x32_bf16 v[132:135], v[150:153], v[188:191], 0
	v_mfma_f32_16x16x32_bf16 v[124:127], v[158:161], v[188:191], 0
	v_mfma_f32_16x16x32_bf16 v[108:111], v[150:153], v[192:195], 0
	v_mfma_f32_16x16x32_bf16 v[100:103], v[158:161], v[192:195], 0
	v_mfma_f32_16x16x32_bf16 v[92:95], v[150:153], v[204:207], 0
	v_mfma_f32_16x16x32_bf16 v[84:87], v[158:161], v[204:207], 0
	v_mfma_f32_16x16x32_bf16 v[76:79], v[150:153], v[208:211], 0
	v_mfma_f32_16x16x32_bf16 v[68:71], v[158:161], v[208:211], 0
	v_mfma_f32_16x16x32_bf16 v[132:135], v[154:157], v[196:199], v[132:135]
	v_mfma_f32_16x16x32_bf16 v[124:127], v[162:165], v[196:199], v[124:127]
	v_mfma_f32_16x16x32_bf16 v[108:111], v[154:157], v[200:203], v[108:111]
	v_mfma_f32_16x16x32_bf16 v[100:103], v[162:165], v[200:203], v[100:103]
	v_mfma_f32_16x16x32_bf16 v[92:95], v[154:157], v[224:227], v[92:95]
	v_mfma_f32_16x16x32_bf16 v[84:87], v[162:165], v[224:227], v[84:87]
	v_mfma_f32_16x16x32_bf16 v[76:79], v[154:157], v[228:231], v[76:79]
	v_mfma_f32_16x16x32_bf16 v[68:71], v[162:165], v[228:231], v[68:71]
	v_mfma_f32_16x16x32_bf16 v[136:139], v[166:169], v[188:191], 0
	v_mfma_f32_16x16x32_bf16 v[128:131], v[174:177], v[188:191], 0
	v_mfma_f32_16x16x32_bf16 v[112:115], v[166:169], v[192:195], 0
	v_mfma_f32_16x16x32_bf16 v[104:107], v[174:177], v[192:195], 0
	v_mfma_f32_16x16x32_bf16 v[96:99], v[166:169], v[204:207], 0
	v_mfma_f32_16x16x32_bf16 v[88:91], v[174:177], v[204:207], 0
	v_mfma_f32_16x16x32_bf16 v[80:83], v[166:169], v[208:211], 0
	v_mfma_f32_16x16x32_bf16 v[72:75], v[174:177], v[208:211], 0
	v_mfma_f32_16x16x32_bf16 v[136:139], v[170:173], v[196:199], v[136:139]
	v_mfma_f32_16x16x32_bf16 v[128:131], v[184:187], v[196:199], v[128:131]
	v_mfma_f32_16x16x32_bf16 v[112:115], v[170:173], v[200:203], v[112:115]
	v_mfma_f32_16x16x32_bf16 v[104:107], v[184:187], v[200:203], v[104:107]
	v_mfma_f32_16x16x32_bf16 v[96:99], v[170:173], v[224:227], v[96:99]
	v_mfma_f32_16x16x32_bf16 v[88:91], v[184:187], v[224:227], v[88:91]
	v_mfma_f32_16x16x32_bf16 v[80:83], v[170:173], v[228:231], v[80:83]
	v_mfma_f32_16x16x32_bf16 v[72:75], v[184:187], v[228:231], v[72:75]
	s_setprio 0
	s_barrier
	s_add_i32 s31, s31, s33
	s_mov_b32 m0, s31
	ds_read_b128 v[188:191], v147 offset:16384
	ds_read_b128 v[192:195], v147 offset:18432
	ds_read_b128 v[196:199], v148 offset:16384
	ds_read_b128 v[200:203], v148 offset:18432
	ds_read_b128 v[204:207], v147 offset:20480
	ds_read_b128 v[208:211], v147 offset:22528
	ds_read_b128 v[224:227], v148 offset:20480
	ds_read_b128 v[228:231], v148 offset:22528
	global_load_lds_dwordx4 v34, s[28:29]
	s_add_i32 m0, s31, 0x2000
	s_add_u32 s54, s28, 0x80000
	s_addc_u32 s55, s29, 0
	s_add_i32 s31, s56, s33
	global_load_lds_dwordx4 v140, s[28:29]
	s_mov_b32 m0, s31
	s_nop 0
	global_load_lds_dwordx4 v34, s[54:55]
	s_add_i32 m0, s31, 0x2000
	s_nop 0
	global_load_lds_dwordx4 v140, s[54:55]
	s_mov_b32 m0, s34
	s_nop 0
	global_load_lds_dwordx4 v144, s[42:43]
	s_mov_b32 m0, s35
	s_nop 0
	global_load_lds_dwordx4 v142, s[42:43]
	s_waitcnt vmcnt(8)
	s_waitcnt lgkmcnt(0)
	s_barrier
	s_setprio 1
	v_mfma_f32_16x16x32_bf16 v[60:63], v[150:153], v[188:191], 0
	v_mfma_f32_16x16x32_bf16 v[52:55], v[158:161], v[188:191], 0
	v_mfma_f32_16x16x32_bf16 v[44:47], v[150:153], v[192:195], 0
	v_mfma_f32_16x16x32_bf16 v[36:39], v[158:161], v[192:195], 0
	v_mfma_f32_16x16x32_bf16 v[26:29], v[150:153], v[204:207], 0
	v_mfma_f32_16x16x32_bf16 v[18:21], v[158:161], v[204:207], 0
	v_mfma_f32_16x16x32_bf16 v[10:13], v[150:153], v[208:211], 0
	v_mfma_f32_16x16x32_bf16 v[6:9], v[158:161], v[208:211], 0
	v_mfma_f32_16x16x32_bf16 v[60:63], v[154:157], v[196:199], v[60:63]
	v_mfma_f32_16x16x32_bf16 v[52:55], v[162:165], v[196:199], v[52:55]
	v_mfma_f32_16x16x32_bf16 v[44:47], v[154:157], v[200:203], v[44:47]
	v_mfma_f32_16x16x32_bf16 v[36:39], v[162:165], v[200:203], v[36:39]
	v_mfma_f32_16x16x32_bf16 v[26:29], v[154:157], v[224:227], v[26:29]
	v_mfma_f32_16x16x32_bf16 v[18:21], v[162:165], v[224:227], v[18:21]
	v_mfma_f32_16x16x32_bf16 v[10:13], v[154:157], v[228:231], v[10:13]
	v_mfma_f32_16x16x32_bf16 v[6:9], v[162:165], v[228:231], v[6:9]
	v_mfma_f32_16x16x32_bf16 v[64:67], v[166:169], v[188:191], 0
	v_mfma_f32_16x16x32_bf16 v[56:59], v[174:177], v[188:191], 0
	v_mfma_f32_16x16x32_bf16 v[48:51], v[166:169], v[192:195], 0
	v_mfma_f32_16x16x32_bf16 v[40:43], v[174:177], v[192:195], 0
	v_mfma_f32_16x16x32_bf16 v[30:33], v[166:169], v[204:207], 0
	v_mfma_f32_16x16x32_bf16 v[22:25], v[174:177], v[204:207], 0
	v_mfma_f32_16x16x32_bf16 v[14:17], v[166:169], v[208:211], 0
	v_mfma_f32_16x16x32_bf16 v[2:5], v[174:177], v[208:211], 0
	v_mfma_f32_16x16x32_bf16 v[64:67], v[170:173], v[196:199], v[64:67]
	v_mfma_f32_16x16x32_bf16 v[56:59], v[184:187], v[196:199], v[56:59]
	v_mfma_f32_16x16x32_bf16 v[48:51], v[170:173], v[200:203], v[48:51]
	v_mfma_f32_16x16x32_bf16 v[40:43], v[184:187], v[200:203], v[40:43]
	v_mfma_f32_16x16x32_bf16 v[30:33], v[170:173], v[224:227], v[30:33]
	v_mfma_f32_16x16x32_bf16 v[22:25], v[184:187], v[224:227], v[22:25]
	v_mfma_f32_16x16x32_bf16 v[14:17], v[170:173], v[228:231], v[14:17]
	v_mfma_f32_16x16x32_bf16 v[2:5], v[184:187], v[228:231], v[2:5]
	s_setprio 0
	s_barrier
	s_add_i32 s31, 0, 0x18000
	ds_read_b128 v[150:153], v1 offset:32768
	ds_read_b128 v[154:157], v146 offset:32768
	s_add_i32 s54, 0, 0x1c000
	ds_read_b128 v[158:161], v1 offset:34816
	ds_read_b128 v[162:165], v146 offset:34816
	ds_read_b128 v[166:169], v1 offset:49152
	ds_read_b128 v[170:173], v146 offset:49152
	ds_read_b128 v[174:177], v1 offset:51200
	ds_read_b128 v[184:187], v146 offset:51200
	s_mov_b64 s[100:101], s[42:43]
	s_add_u32 s42, s42, 0x80000
	s_addc_u32 s43, s43, 0
	s_mov_b32 m0, s44
	ds_read_b128 v[188:191], v147 offset:32768
	ds_read_b128 v[192:195], v147 offset:34816
	ds_read_b128 v[196:199], v148 offset:32768
	ds_read_b128 v[200:203], v148 offset:34816
	ds_read_b128 v[204:207], v147 offset:36864
	ds_read_b128 v[208:211], v147 offset:38912
	ds_read_b128 v[224:227], v148 offset:36864
	ds_read_b128 v[228:231], v148 offset:38912
	global_load_lds_dwordx4 v144, s[42:43]
	s_mov_b32 m0, s45
	s_nop 0
	global_load_lds_dwordx4 v142, s[42:43]
	s_waitcnt vmcnt(8)
	s_waitcnt lgkmcnt(0)
	s_barrier
	s_setprio 1
	v_mfma_f32_16x16x32_bf16 v[132:135], v[150:153], v[188:191], v[132:135]
	v_mfma_f32_16x16x32_bf16 v[124:127], v[158:161], v[188:191], v[124:127]
	v_mfma_f32_16x16x32_bf16 v[108:111], v[150:153], v[192:195], v[108:111]
	v_mfma_f32_16x16x32_bf16 v[100:103], v[158:161], v[192:195], v[100:103]
	v_mfma_f32_16x16x32_bf16 v[92:95], v[150:153], v[204:207], v[92:95]
	v_mfma_f32_16x16x32_bf16 v[84:87], v[158:161], v[204:207], v[84:87]
	v_mfma_f32_16x16x32_bf16 v[76:79], v[150:153], v[208:211], v[76:79]
	v_mfma_f32_16x16x32_bf16 v[68:71], v[158:161], v[208:211], v[68:71]
	v_mfma_f32_16x16x32_bf16 v[132:135], v[154:157], v[196:199], v[132:135]
	v_mfma_f32_16x16x32_bf16 v[124:127], v[162:165], v[196:199], v[124:127]
	v_mfma_f32_16x16x32_bf16 v[108:111], v[154:157], v[200:203], v[108:111]
	v_mfma_f32_16x16x32_bf16 v[100:103], v[162:165], v[200:203], v[100:103]
	v_mfma_f32_16x16x32_bf16 v[92:95], v[154:157], v[224:227], v[92:95]
	v_mfma_f32_16x16x32_bf16 v[84:87], v[162:165], v[224:227], v[84:87]
	v_mfma_f32_16x16x32_bf16 v[76:79], v[154:157], v[228:231], v[76:79]
	v_mfma_f32_16x16x32_bf16 v[68:71], v[162:165], v[228:231], v[68:71]
	v_mfma_f32_16x16x32_bf16 v[136:139], v[166:169], v[188:191], v[136:139]
	v_mfma_f32_16x16x32_bf16 v[128:131], v[174:177], v[188:191], v[128:131]
	v_mfma_f32_16x16x32_bf16 v[112:115], v[166:169], v[192:195], v[112:115]
	v_mfma_f32_16x16x32_bf16 v[104:107], v[174:177], v[192:195], v[104:107]
	v_mfma_f32_16x16x32_bf16 v[96:99], v[166:169], v[204:207], v[96:99]
	v_mfma_f32_16x16x32_bf16 v[88:91], v[174:177], v[204:207], v[88:91]
	v_mfma_f32_16x16x32_bf16 v[80:83], v[166:169], v[208:211], v[80:83]
	v_mfma_f32_16x16x32_bf16 v[72:75], v[174:177], v[208:211], v[72:75]
	v_mfma_f32_16x16x32_bf16 v[136:139], v[170:173], v[196:199], v[136:139]
	v_mfma_f32_16x16x32_bf16 v[128:131], v[184:187], v[196:199], v[128:131]
	v_mfma_f32_16x16x32_bf16 v[112:115], v[170:173], v[200:203], v[112:115]
	v_mfma_f32_16x16x32_bf16 v[104:107], v[184:187], v[200:203], v[104:107]
	v_mfma_f32_16x16x32_bf16 v[96:99], v[170:173], v[224:227], v[96:99]
	v_mfma_f32_16x16x32_bf16 v[88:91], v[184:187], v[224:227], v[88:91]
	v_mfma_f32_16x16x32_bf16 v[80:83], v[170:173], v[228:231], v[80:83]
	v_mfma_f32_16x16x32_bf16 v[72:75], v[184:187], v[228:231], v[72:75]
	s_setprio 0
	s_barrier
	s_add_i32 s31, s31, s33
	s_add_i32 m0, s31, 0xffffff80
	ds_read_b128 v[188:191], v147 offset:49152
	ds_read_b128 v[192:195], v147 offset:51200
	ds_read_b128 v[196:199], v148 offset:49152
	ds_read_b128 v[200:203], v148 offset:51200
	ds_read_b128 v[204:207], v147 offset:53248
	ds_read_b128 v[208:211], v147 offset:55296
	ds_read_b128 v[224:227], v148 offset:53248
	ds_read_b128 v[228:231], v148 offset:55296
	global_load_lds_dwordx4 v34, s[28:29] offset:128
	s_add_i32 m0, s31, 0x1f80
	s_mov_b64 s[98:99], s[28:29]
	s_add_u32 s28, s28, 0x80080
	s_addc_u32 s29, s29, 0
	s_add_i32 s31, s54, s33
	global_load_lds_dwordx4 v140, s[98:99] offset:128
	s_mov_b32 m0, s31
	s_nop 0
	global_load_lds_dwordx4 v34, s[28:29]
	s_add_i32 m0, s31, 0x2000
	s_nop 0
	global_load_lds_dwordx4 v140, s[28:29]
	s_add_i32 m0, s48, 0xffffff80
	s_nop 0
	global_load_lds_dwordx4 v144, s[100:101] offset:128
	s_add_i32 m0, s49, 0xffffff80
	s_nop 0
	global_load_lds_dwordx4 v142, s[100:101] offset:128
	s_waitcnt vmcnt(8)
	s_waitcnt lgkmcnt(0)
	s_barrier
	s_setprio 1
	v_mfma_f32_16x16x32_bf16 v[60:63], v[150:153], v[188:191], v[60:63]
	v_mfma_f32_16x16x32_bf16 v[52:55], v[158:161], v[188:191], v[52:55]
	v_mfma_f32_16x16x32_bf16 v[44:47], v[150:153], v[192:195], v[44:47]
	v_mfma_f32_16x16x32_bf16 v[36:39], v[158:161], v[192:195], v[36:39]
	v_mfma_f32_16x16x32_bf16 v[26:29], v[150:153], v[204:207], v[26:29]
	v_mfma_f32_16x16x32_bf16 v[18:21], v[158:161], v[204:207], v[18:21]
	v_mfma_f32_16x16x32_bf16 v[10:13], v[150:153], v[208:211], v[10:13]
	v_mfma_f32_16x16x32_bf16 v[6:9], v[158:161], v[208:211], v[6:9]
	v_mfma_f32_16x16x32_bf16 v[60:63], v[154:157], v[196:199], v[60:63]
	v_mfma_f32_16x16x32_bf16 v[52:55], v[162:165], v[196:199], v[52:55]
	v_mfma_f32_16x16x32_bf16 v[44:47], v[154:157], v[200:203], v[44:47]
	v_mfma_f32_16x16x32_bf16 v[36:39], v[162:165], v[200:203], v[36:39]
	v_mfma_f32_16x16x32_bf16 v[26:29], v[154:157], v[224:227], v[26:29]
	v_mfma_f32_16x16x32_bf16 v[18:21], v[162:165], v[224:227], v[18:21]
	v_mfma_f32_16x16x32_bf16 v[10:13], v[154:157], v[228:231], v[10:13]
	v_mfma_f32_16x16x32_bf16 v[6:9], v[162:165], v[228:231], v[6:9]
	v_mfma_f32_16x16x32_bf16 v[64:67], v[166:169], v[188:191], v[64:67]
	v_mfma_f32_16x16x32_bf16 v[56:59], v[174:177], v[188:191], v[56:59]
	v_mfma_f32_16x16x32_bf16 v[48:51], v[166:169], v[192:195], v[48:51]
	v_mfma_f32_16x16x32_bf16 v[40:43], v[174:177], v[192:195], v[40:43]
	v_mfma_f32_16x16x32_bf16 v[30:33], v[166:169], v[204:207], v[30:33]
	v_mfma_f32_16x16x32_bf16 v[22:25], v[174:177], v[204:207], v[22:25]
	v_mfma_f32_16x16x32_bf16 v[14:17], v[166:169], v[208:211], v[14:17]
	v_mfma_f32_16x16x32_bf16 v[2:5], v[174:177], v[208:211], v[2:5]
	v_mfma_f32_16x16x32_bf16 v[64:67], v[170:173], v[196:199], v[64:67]
	v_mfma_f32_16x16x32_bf16 v[56:59], v[184:187], v[196:199], v[56:59]
	v_mfma_f32_16x16x32_bf16 v[48:51], v[170:173], v[200:203], v[48:51]
	v_mfma_f32_16x16x32_bf16 v[40:43], v[184:187], v[200:203], v[40:43]
	v_mfma_f32_16x16x32_bf16 v[30:33], v[170:173], v[224:227], v[30:33]
	v_mfma_f32_16x16x32_bf16 v[22:25], v[184:187], v[224:227], v[22:25]
	v_mfma_f32_16x16x32_bf16 v[14:17], v[170:173], v[228:231], v[14:17]
	v_mfma_f32_16x16x32_bf16 v[2:5], v[184:187], v[228:231], v[2:5]
	s_setprio 0
	s_barrier
	s_add_i32 s30, s30, 2
	s_add_u32 s8, s8, 0x100
	s_addc_u32 s9, s9, 0
	s_add_u32 s24, s24, 0x100
	s_addc_u32 s25, s25, 0
	s_cmp_gt_u32 s30, 29
	s_cbranch_scc1 .Lpeel_done_P6
.LBB0_1114:
	s_add_u32 s28, s8, 0xfff80080
	s_addc_u32 s29, s9, -1
	s_add_i32 s31, 0, 0x10000
	s_cmp_eq_u32 s30, 28
	s_cselect_b32 s43, s13, s29
	s_cselect_b32 s42, s19, s28
	ds_read_b128 v[150:153], v1
	ds_read_b128 v[154:157], v146
	s_cselect_b32 s29, s20, s25
	s_cselect_b32 s28, s21, s24
	s_add_i32 s56, 0, 0x14000
	ds_read_b128 v[158:161], v1 offset:2048
	ds_read_b128 v[162:165], v146 offset:2048
	ds_read_b128 v[166:169], v1 offset:16384
	ds_read_b128 v[170:173], v146 offset:16384
	ds_read_b128 v[174:177], v1 offset:18432
	ds_read_b128 v[184:187], v146 offset:18432
	s_add_i32 m0, s34, 0xc000
	ds_read_b128 v[188:191], v147
	ds_read_b128 v[192:195], v147 offset:2048
	ds_read_b128 v[196:199], v148
	ds_read_b128 v[200:203], v148 offset:2048
	ds_read_b128 v[204:207], v147 offset:4096
	ds_read_b128 v[208:211], v147 offset:6144
	ds_read_b128 v[224:227], v148 offset:4096
	ds_read_b128 v[228:231], v148 offset:6144
	global_load_lds_dwordx4 v144, s[8:9]
	s_add_i32 m0, s34, 0xe000
	s_nop 0
	global_load_lds_dwordx4 v142, s[8:9]
	s_waitcnt vmcnt(8)
	s_waitcnt lgkmcnt(0)
	s_barrier
	s_setprio 1
	v_mfma_f32_16x16x32_bf16 v[132:135], v[150:153], v[188:191], v[132:135]
	v_mfma_f32_16x16x32_bf16 v[124:127], v[158:161], v[188:191], v[124:127]
	v_mfma_f32_16x16x32_bf16 v[108:111], v[150:153], v[192:195], v[108:111]
	v_mfma_f32_16x16x32_bf16 v[100:103], v[158:161], v[192:195], v[100:103]
	v_mfma_f32_16x16x32_bf16 v[92:95], v[150:153], v[204:207], v[92:95]
	v_mfma_f32_16x16x32_bf16 v[84:87], v[158:161], v[204:207], v[84:87]
	v_mfma_f32_16x16x32_bf16 v[76:79], v[150:153], v[208:211], v[76:79]
	v_mfma_f32_16x16x32_bf16 v[68:71], v[158:161], v[208:211], v[68:71]
	v_mfma_f32_16x16x32_bf16 v[132:135], v[154:157], v[196:199], v[132:135]
	v_mfma_f32_16x16x32_bf16 v[124:127], v[162:165], v[196:199], v[124:127]
	v_mfma_f32_16x16x32_bf16 v[108:111], v[154:157], v[200:203], v[108:111]
	v_mfma_f32_16x16x32_bf16 v[100:103], v[162:165], v[200:203], v[100:103]
	v_mfma_f32_16x16x32_bf16 v[92:95], v[154:157], v[224:227], v[92:95]
	v_mfma_f32_16x16x32_bf16 v[84:87], v[162:165], v[224:227], v[84:87]
	v_mfma_f32_16x16x32_bf16 v[76:79], v[154:157], v[228:231], v[76:79]
	v_mfma_f32_16x16x32_bf16 v[68:71], v[162:165], v[228:231], v[68:71]
	v_mfma_f32_16x16x32_bf16 v[136:139], v[166:169], v[188:191], v[136:139]
	v_mfma_f32_16x16x32_bf16 v[128:131], v[174:177], v[188:191], v[128:131]
	v_mfma_f32_16x16x32_bf16 v[112:115], v[166:169], v[192:195], v[112:115]
	v_mfma_f32_16x16x32_bf16 v[104:107], v[174:177], v[192:195], v[104:107]
	v_mfma_f32_16x16x32_bf16 v[96:99], v[166:169], v[204:207], v[96:99]
	v_mfma_f32_16x16x32_bf16 v[88:91], v[174:177], v[204:207], v[88:91]
	v_mfma_f32_16x16x32_bf16 v[80:83], v[166:169], v[208:211], v[80:83]
	v_mfma_f32_16x16x32_bf16 v[72:75], v[174:177], v[208:211], v[72:75]
	v_mfma_f32_16x16x32_bf16 v[136:139], v[170:173], v[196:199], v[136:139]
	v_mfma_f32_16x16x32_bf16 v[128:131], v[184:187], v[196:199], v[128:131]
	v_mfma_f32_16x16x32_bf16 v[112:115], v[170:173], v[200:203], v[112:115]
	v_mfma_f32_16x16x32_bf16 v[104:107], v[184:187], v[200:203], v[104:107]
	v_mfma_f32_16x16x32_bf16 v[96:99], v[170:173], v[224:227], v[96:99]
	v_mfma_f32_16x16x32_bf16 v[88:91], v[184:187], v[224:227], v[88:91]
	v_mfma_f32_16x16x32_bf16 v[80:83], v[170:173], v[228:231], v[80:83]
	v_mfma_f32_16x16x32_bf16 v[72:75], v[184:187], v[228:231], v[72:75]
	s_setprio 0
	s_barrier
	s_add_i32 s31, s31, s33
	s_mov_b32 m0, s31
	ds_read_b128 v[188:191], v147 offset:16384
	ds_read_b128 v[192:195], v147 offset:18432
	ds_read_b128 v[196:199], v148 offset:16384
	ds_read_b128 v[200:203], v148 offset:18432
	ds_read_b128 v[204:207], v147 offset:20480
	ds_read_b128 v[208:211], v147 offset:22528
	ds_read_b128 v[224:227], v148 offset:20480
	ds_read_b128 v[228:231], v148 offset:22528
	global_load_lds_dwordx4 v34, s[28:29]
	s_add_i32 m0, s31, 0x2000
	s_add_u32 s54, s28, 0x80000
	s_addc_u32 s55, s29, 0
	s_add_i32 s31, s56, s33
	global_load_lds_dwordx4 v140, s[28:29]
	s_mov_b32 m0, s31
	s_nop 0
	global_load_lds_dwordx4 v34, s[54:55]
	s_add_i32 m0, s31, 0x2000
	s_nop 0
	global_load_lds_dwordx4 v140, s[54:55]
	s_mov_b32 m0, s34
	s_nop 0
	global_load_lds_dwordx4 v144, s[42:43]
	s_mov_b32 m0, s35
	s_nop 0
	global_load_lds_dwordx4 v142, s[42:43]
	s_waitcnt vmcnt(8)
	s_waitcnt lgkmcnt(0)
	s_barrier
	s_setprio 1
	v_mfma_f32_16x16x32_bf16 v[60:63], v[150:153], v[188:191], v[60:63]
	v_mfma_f32_16x16x32_bf16 v[52:55], v[158:161], v[188:191], v[52:55]
	v_mfma_f32_16x16x32_bf16 v[44:47], v[150:153], v[192:195], v[44:47]
	v_mfma_f32_16x16x32_bf16 v[36:39], v[158:161], v[192:195], v[36:39]
	v_mfma_f32_16x16x32_bf16 v[26:29], v[150:153], v[204:207], v[26:29]
	v_mfma_f32_16x16x32_bf16 v[18:21], v[158:161], v[204:207], v[18:21]
	v_mfma_f32_16x16x32_bf16 v[10:13], v[150:153], v[208:211], v[10:13]
	v_mfma_f32_16x16x32_bf16 v[6:9], v[158:161], v[208:211], v[6:9]
	v_mfma_f32_16x16x32_bf16 v[60:63], v[154:157], v[196:199], v[60:63]
	v_mfma_f32_16x16x32_bf16 v[52:55], v[162:165], v[196:199], v[52:55]
	v_mfma_f32_16x16x32_bf16 v[44:47], v[154:157], v[200:203], v[44:47]
	v_mfma_f32_16x16x32_bf16 v[36:39], v[162:165], v[200:203], v[36:39]
	v_mfma_f32_16x16x32_bf16 v[26:29], v[154:157], v[224:227], v[26:29]
	v_mfma_f32_16x16x32_bf16 v[18:21], v[162:165], v[224:227], v[18:21]
	v_mfma_f32_16x16x32_bf16 v[10:13], v[154:157], v[228:231], v[10:13]
	v_mfma_f32_16x16x32_bf16 v[6:9], v[162:165], v[228:231], v[6:9]
	v_mfma_f32_16x16x32_bf16 v[64:67], v[166:169], v[188:191], v[64:67]
	v_mfma_f32_16x16x32_bf16 v[56:59], v[174:177], v[188:191], v[56:59]
	v_mfma_f32_16x16x32_bf16 v[48:51], v[166:169], v[192:195], v[48:51]
	v_mfma_f32_16x16x32_bf16 v[40:43], v[174:177], v[192:195], v[40:43]
	v_mfma_f32_16x16x32_bf16 v[30:33], v[166:169], v[204:207], v[30:33]
	v_mfma_f32_16x16x32_bf16 v[22:25], v[174:177], v[204:207], v[22:25]
	v_mfma_f32_16x16x32_bf16 v[14:17], v[166:169], v[208:211], v[14:17]
	v_mfma_f32_16x16x32_bf16 v[2:5], v[174:177], v[208:211], v[2:5]
	v_mfma_f32_16x16x32_bf16 v[64:67], v[170:173], v[196:199], v[64:67]
	v_mfma_f32_16x16x32_bf16 v[56:59], v[184:187], v[196:199], v[56:59]
	v_mfma_f32_16x16x32_bf16 v[48:51], v[170:173], v[200:203], v[48:51]
	v_mfma_f32_16x16x32_bf16 v[40:43], v[184:187], v[200:203], v[40:43]
	v_mfma_f32_16x16x32_bf16 v[30:33], v[170:173], v[224:227], v[30:33]
	v_mfma_f32_16x16x32_bf16 v[22:25], v[184:187], v[224:227], v[22:25]
	v_mfma_f32_16x16x32_bf16 v[14:17], v[170:173], v[228:231], v[14:17]
	v_mfma_f32_16x16x32_bf16 v[2:5], v[184:187], v[228:231], v[2:5]
	s_setprio 0
	s_barrier
	s_add_i32 s31, 0, 0x18000
	ds_read_b128 v[150:153], v1 offset:32768
	ds_read_b128 v[154:157], v146 offset:32768
	s_add_i32 s54, 0, 0x1c000
	ds_read_b128 v[158:161], v1 offset:34816
	ds_read_b128 v[162:165], v146 offset:34816
	ds_read_b128 v[166:169], v1 offset:49152
	ds_read_b128 v[170:173], v146 offset:49152
	ds_read_b128 v[174:177], v1 offset:51200
	ds_read_b128 v[184:187], v146 offset:51200
	s_mov_b64 s[100:101], s[42:43]
	s_add_u32 s42, s42, 0x80000
	s_addc_u32 s43, s43, 0
	s_mov_b32 m0, s44
	ds_read_b128 v[188:191], v147 offset:32768
	ds_read_b128 v[192:195], v147 offset:34816
	ds_read_b128 v[196:199], v148 offset:32768
	ds_read_b128 v[200:203], v148 offset:34816
	ds_read_b128 v[204:207], v147 offset:36864
	ds_read_b128 v[208:211], v147 offset:38912
	ds_read_b128 v[224:227], v148 offset:36864
	ds_read_b128 v[228:231], v148 offset:38912
	global_load_lds_dwordx4 v144, s[42:43]
	s_mov_b32 m0, s45
	s_nop 0
	global_load_lds_dwordx4 v142, s[42:43]
	s_waitcnt vmcnt(8)
	s_waitcnt lgkmcnt(0)
	s_barrier
	s_setprio 1
	v_mfma_f32_16x16x32_bf16 v[132:135], v[150:153], v[188:191], v[132:135]
	v_mfma_f32_16x16x32_bf16 v[124:127], v[158:161], v[188:191], v[124:127]
	v_mfma_f32_16x16x32_bf16 v[108:111], v[150:153], v[192:195], v[108:111]
	v_mfma_f32_16x16x32_bf16 v[100:103], v[158:161], v[192:195], v[100:103]
	v_mfma_f32_16x16x32_bf16 v[92:95], v[150:153], v[204:207], v[92:95]
	v_mfma_f32_16x16x32_bf16 v[84:87], v[158:161], v[204:207], v[84:87]
	v_mfma_f32_16x16x32_bf16 v[76:79], v[150:153], v[208:211], v[76:79]
	v_mfma_f32_16x16x32_bf16 v[68:71], v[158:161], v[208:211], v[68:71]
	v_mfma_f32_16x16x32_bf16 v[132:135], v[154:157], v[196:199], v[132:135]
	v_mfma_f32_16x16x32_bf16 v[124:127], v[162:165], v[196:199], v[124:127]
	v_mfma_f32_16x16x32_bf16 v[108:111], v[154:157], v[200:203], v[108:111]
	v_mfma_f32_16x16x32_bf16 v[100:103], v[162:165], v[200:203], v[100:103]
	v_mfma_f32_16x16x32_bf16 v[92:95], v[154:157], v[224:227], v[92:95]
	v_mfma_f32_16x16x32_bf16 v[84:87], v[162:165], v[224:227], v[84:87]
	v_mfma_f32_16x16x32_bf16 v[76:79], v[154:157], v[228:231], v[76:79]
	v_mfma_f32_16x16x32_bf16 v[68:71], v[162:165], v[228:231], v[68:71]
	v_mfma_f32_16x16x32_bf16 v[136:139], v[166:169], v[188:191], v[136:139]
	v_mfma_f32_16x16x32_bf16 v[128:131], v[174:177], v[188:191], v[128:131]
	v_mfma_f32_16x16x32_bf16 v[112:115], v[166:169], v[192:195], v[112:115]
	v_mfma_f32_16x16x32_bf16 v[104:107], v[174:177], v[192:195], v[104:107]
	v_mfma_f32_16x16x32_bf16 v[96:99], v[166:169], v[204:207], v[96:99]
	v_mfma_f32_16x16x32_bf16 v[88:91], v[174:177], v[204:207], v[88:91]
	v_mfma_f32_16x16x32_bf16 v[80:83], v[166:169], v[208:211], v[80:83]
	v_mfma_f32_16x16x32_bf16 v[72:75], v[174:177], v[208:211], v[72:75]
	v_mfma_f32_16x16x32_bf16 v[136:139], v[170:173], v[196:199], v[136:139]
	v_mfma_f32_16x16x32_bf16 v[128:131], v[184:187], v[196:199], v[128:131]
	v_mfma_f32_16x16x32_bf16 v[112:115], v[170:173], v[200:203], v[112:115]
	v_mfma_f32_16x16x32_bf16 v[104:107], v[184:187], v[200:203], v[104:107]
	v_mfma_f32_16x16x32_bf16 v[96:99], v[170:173], v[224:227], v[96:99]
	v_mfma_f32_16x16x32_bf16 v[88:91], v[184:187], v[224:227], v[88:91]
	v_mfma_f32_16x16x32_bf16 v[80:83], v[170:173], v[228:231], v[80:83]
	v_mfma_f32_16x16x32_bf16 v[72:75], v[184:187], v[228:231], v[72:75]
	s_setprio 0
	s_barrier
	s_add_i32 s31, s31, s33
	s_add_i32 m0, s31, 0xffffff80
	ds_read_b128 v[188:191], v147 offset:49152
	ds_read_b128 v[192:195], v147 offset:51200
	ds_read_b128 v[196:199], v148 offset:49152
	ds_read_b128 v[200:203], v148 offset:51200
	ds_read_b128 v[204:207], v147 offset:53248
	ds_read_b128 v[208:211], v147 offset:55296
	ds_read_b128 v[224:227], v148 offset:53248
	ds_read_b128 v[228:231], v148 offset:55296
	global_load_lds_dwordx4 v34, s[28:29] offset:128
	s_add_i32 m0, s31, 0x1f80
	s_mov_b64 s[98:99], s[28:29]
	s_add_u32 s28, s28, 0x80080
	s_addc_u32 s29, s29, 0
	s_add_i32 s31, s54, s33
	global_load_lds_dwordx4 v140, s[98:99] offset:128
	s_mov_b32 m0, s31
	s_nop 0
	global_load_lds_dwordx4 v34, s[28:29]
	s_add_i32 m0, s31, 0x2000
	s_nop 0
	global_load_lds_dwordx4 v140, s[28:29]
	s_add_i32 m0, s48, 0xffffff80
	s_nop 0
	global_load_lds_dwordx4 v144, s[100:101] offset:128
	s_add_i32 m0, s49, 0xffffff80
	s_nop 0
	global_load_lds_dwordx4 v142, s[100:101] offset:128
	s_waitcnt vmcnt(8)
	s_waitcnt lgkmcnt(0)
	s_barrier
	s_setprio 1
	v_mfma_f32_16x16x32_bf16 v[60:63], v[150:153], v[188:191], v[60:63]
	v_mfma_f32_16x16x32_bf16 v[52:55], v[158:161], v[188:191], v[52:55]
	v_mfma_f32_16x16x32_bf16 v[44:47], v[150:153], v[192:195], v[44:47]
	v_mfma_f32_16x16x32_bf16 v[36:39], v[158:161], v[192:195], v[36:39]
	v_mfma_f32_16x16x32_bf16 v[26:29], v[150:153], v[204:207], v[26:29]
	v_mfma_f32_16x16x32_bf16 v[18:21], v[158:161], v[204:207], v[18:21]
	v_mfma_f32_16x16x32_bf16 v[10:13], v[150:153], v[208:211], v[10:13]
	v_mfma_f32_16x16x32_bf16 v[6:9], v[158:161], v[208:211], v[6:9]
	v_mfma_f32_16x16x32_bf16 v[60:63], v[154:157], v[196:199], v[60:63]
	v_mfma_f32_16x16x32_bf16 v[52:55], v[162:165], v[196:199], v[52:55]
	v_mfma_f32_16x16x32_bf16 v[44:47], v[154:157], v[200:203], v[44:47]
	v_mfma_f32_16x16x32_bf16 v[36:39], v[162:165], v[200:203], v[36:39]
	v_mfma_f32_16x16x32_bf16 v[26:29], v[154:157], v[224:227], v[26:29]
	v_mfma_f32_16x16x32_bf16 v[18:21], v[162:165], v[224:227], v[18:21]
	v_mfma_f32_16x16x32_bf16 v[10:13], v[154:157], v[228:231], v[10:13]
	v_mfma_f32_16x16x32_bf16 v[6:9], v[162:165], v[228:231], v[6:9]
	v_mfma_f32_16x16x32_bf16 v[64:67], v[166:169], v[188:191], v[64:67]
	v_mfma_f32_16x16x32_bf16 v[56:59], v[174:177], v[188:191], v[56:59]
	v_mfma_f32_16x16x32_bf16 v[48:51], v[166:169], v[192:195], v[48:51]
	v_mfma_f32_16x16x32_bf16 v[40:43], v[174:177], v[192:195], v[40:43]
	v_mfma_f32_16x16x32_bf16 v[30:33], v[166:169], v[204:207], v[30:33]
	v_mfma_f32_16x16x32_bf16 v[22:25], v[174:177], v[204:207], v[22:25]
	v_mfma_f32_16x16x32_bf16 v[14:17], v[166:169], v[208:211], v[14:17]
	v_mfma_f32_16x16x32_bf16 v[2:5], v[174:177], v[208:211], v[2:5]
	v_mfma_f32_16x16x32_bf16 v[64:67], v[170:173], v[196:199], v[64:67]
	v_mfma_f32_16x16x32_bf16 v[56:59], v[184:187], v[196:199], v[56:59]
	v_mfma_f32_16x16x32_bf16 v[48:51], v[170:173], v[200:203], v[48:51]
	v_mfma_f32_16x16x32_bf16 v[40:43], v[184:187], v[200:203], v[40:43]
	v_mfma_f32_16x16x32_bf16 v[30:33], v[170:173], v[224:227], v[30:33]
	v_mfma_f32_16x16x32_bf16 v[22:25], v[184:187], v[224:227], v[22:25]
	v_mfma_f32_16x16x32_bf16 v[14:17], v[170:173], v[228:231], v[14:17]
	v_mfma_f32_16x16x32_bf16 v[2:5], v[184:187], v[228:231], v[2:5]
	s_setprio 0
	s_barrier
	s_add_i32 s30, s30, 2
	s_add_u32 s8, s8, 0x100
	s_addc_u32 s9, s9, 0
	s_add_u32 s24, s24, 0x100
	s_addc_u32 s25, s25, 0
	s_cmp_gt_u32 s30, 29
	s_cbranch_scc0 .LBB0_1114

.LBB0_1194:
	s_add_u32 s8, s8, 0x160080
	s_addc_u32 s9, s9, 0
	s_add_u32 s20, s18, 0x100
	s_addc_u32 s21, s19, 0
	s_mov_b32 s24, -2
	v_readlane_b32 s35, v255, 20
	v_readlane_b32 s40, v255, 21
	v_readlane_b32 s41, v255, 22
	v_readlane_b32 s57, v255, 23
	s_mov_b64 s[58:59], 0x80
	s_add_u32 s18, s8, 0xffea0080
	s_addc_u32 s19, s9, -1
	s_add_i32 s25, 0, 0x10000
	s_cmpk_eq_i32 s24, 0x54
	s_cselect_b32 s23, s45, s19
	s_cselect_b32 s22, s44, s18
	s_cselect_b32 s19, s47, s21
	s_cselect_b32 s18, s46, s20
	s_add_i32 s34, 0, 0x14000
	ds_read_b128 v[138:141], v1
	ds_read_b128 v[142:145], v160
	ds_read_b128 v[146:149], v1 offset:2048
	ds_read_b128 v[150:153], v160 offset:2048
	ds_read_b128 v[154:157], v1 offset:16384
	ds_read_b128 v[164:167], v160 offset:16384
	ds_read_b128 v[168:171], v1 offset:18432
	ds_read_b128 v[172:175], v160 offset:18432
	s_add_i32 m0, s29, 0xc000
	ds_read_b128 v[176:179], v161
	ds_read_b128 v[184:187], v161 offset:2048
	ds_read_b128 v[188:191], v162
	ds_read_b128 v[192:195], v162 offset:2048
	ds_read_b128 v[196:199], v161 offset:4096
	ds_read_b128 v[200:203], v161 offset:6144
	ds_read_b128 v[204:207], v162 offset:4096
	ds_read_b128 v[208:211], v162 offset:6144
	global_load_lds_dwordx4 v136, s[8:9]
	s_add_i32 m0, s29, 0xe000
	s_nop 0
	global_load_lds_dwordx4 v134, s[8:9]
	s_waitcnt vmcnt(8)
	s_waitcnt lgkmcnt(0)
	s_barrier
	s_setprio 1
	v_mfma_f32_16x16x32_bf16 v[128:131], v[138:141], v[176:179], 0
	v_mfma_f32_16x16x32_bf16 v[124:127], v[146:149], v[176:179], 0
	v_mfma_f32_16x16x32_bf16 v[112:115], v[138:141], v[184:187], 0
	v_mfma_f32_16x16x32_bf16 v[108:111], v[146:149], v[184:187], 0
	v_mfma_f32_16x16x32_bf16 v[96:99], v[138:141], v[196:199], 0
	v_mfma_f32_16x16x32_bf16 v[92:95], v[146:149], v[196:199], 0
	v_mfma_f32_16x16x32_bf16 v[80:83], v[138:141], v[200:203], 0
	v_mfma_f32_16x16x32_bf16 v[76:79], v[146:149], v[200:203], 0
	v_mfma_f32_16x16x32_bf16 v[128:131], v[142:145], v[188:191], v[128:131]
	v_mfma_f32_16x16x32_bf16 v[124:127], v[150:153], v[188:191], v[124:127]
	v_mfma_f32_16x16x32_bf16 v[112:115], v[142:145], v[192:195], v[112:115]
	v_mfma_f32_16x16x32_bf16 v[108:111], v[150:153], v[192:195], v[108:111]
	v_mfma_f32_16x16x32_bf16 v[96:99], v[142:145], v[204:207], v[96:99]
	v_mfma_f32_16x16x32_bf16 v[92:95], v[150:153], v[204:207], v[92:95]
	v_mfma_f32_16x16x32_bf16 v[80:83], v[142:145], v[208:211], v[80:83]
	v_mfma_f32_16x16x32_bf16 v[76:79], v[150:153], v[208:211], v[76:79]
	v_mfma_f32_16x16x32_bf16 v[120:123], v[154:157], v[176:179], 0
	v_mfma_f32_16x16x32_bf16 v[116:119], v[168:171], v[176:179], 0
	v_mfma_f32_16x16x32_bf16 v[104:107], v[154:157], v[184:187], 0
	v_mfma_f32_16x16x32_bf16 v[100:103], v[168:171], v[184:187], 0
	v_mfma_f32_16x16x32_bf16 v[88:91], v[154:157], v[196:199], 0
	v_mfma_f32_16x16x32_bf16 v[84:87], v[168:171], v[196:199], 0
	v_mfma_f32_16x16x32_bf16 v[72:75], v[154:157], v[200:203], 0
	v_mfma_f32_16x16x32_bf16 v[68:71], v[168:171], v[200:203], 0
	v_mfma_f32_16x16x32_bf16 v[120:123], v[164:167], v[188:191], v[120:123]
	v_mfma_f32_16x16x32_bf16 v[116:119], v[172:175], v[188:191], v[116:119]
	v_mfma_f32_16x16x32_bf16 v[104:107], v[164:167], v[192:195], v[104:107]
	v_mfma_f32_16x16x32_bf16 v[100:103], v[172:175], v[192:195], v[100:103]
	v_mfma_f32_16x16x32_bf16 v[88:91], v[164:167], v[204:207], v[88:91]
	v_mfma_f32_16x16x32_bf16 v[84:87], v[172:175], v[204:207], v[84:87]
	v_mfma_f32_16x16x32_bf16 v[72:75], v[164:167], v[208:211], v[72:75]
	v_mfma_f32_16x16x32_bf16 v[68:71], v[172:175], v[208:211], v[68:71]
	s_setprio 0
	s_barrier
	s_add_i32 s25, s25, s28
	s_mov_b32 m0, s25
	ds_read_b128 v[176:179], v161 offset:16384
	ds_read_b128 v[184:187], v161 offset:18432
	ds_read_b128 v[188:191], v162 offset:16384
	ds_read_b128 v[192:195], v162 offset:18432
	ds_read_b128 v[196:199], v161 offset:20480
	ds_read_b128 v[200:203], v161 offset:22528
	ds_read_b128 v[204:207], v162 offset:20480
	ds_read_b128 v[208:211], v162 offset:22528
	global_load_lds_dwordx4 v34, s[18:19]
	s_add_i32 m0, s25, 0x2000
	s_add_u32 s30, s18, 0x160000
	s_addc_u32 s31, s19, 0
	s_add_i32 s25, s34, s28
	global_load_lds_dwordx4 v132, s[18:19]
	s_mov_b32 m0, s25
	s_nop 0
	global_load_lds_dwordx4 v34, s[30:31]
	s_add_i32 m0, s25, 0x2000
	s_nop 0
	global_load_lds_dwordx4 v132, s[30:31]
	s_mov_b32 m0, s29
	s_nop 0
	global_load_lds_dwordx4 v136, s[22:23]
	s_mov_b32 m0, s33
	s_nop 0
	global_load_lds_dwordx4 v134, s[22:23]
	s_waitcnt vmcnt(8)
	s_waitcnt lgkmcnt(0)
	s_barrier
	s_setprio 1
	v_mfma_f32_16x16x32_bf16 v[64:67], v[138:141], v[176:179], 0
	v_mfma_f32_16x16x32_bf16 v[60:63], v[146:149], v[176:179], 0
	v_mfma_f32_16x16x32_bf16 v[48:51], v[138:141], v[184:187], 0
	v_mfma_f32_16x16x32_bf16 v[44:47], v[146:149], v[184:187], 0
	v_mfma_f32_16x16x32_bf16 v[30:33], v[138:141], v[196:199], 0
	v_mfma_f32_16x16x32_bf16 v[26:29], v[146:149], v[196:199], 0
	v_mfma_f32_16x16x32_bf16 v[14:17], v[138:141], v[200:203], 0
	v_mfma_f32_16x16x32_bf16 v[10:13], v[146:149], v[200:203], 0
	v_mfma_f32_16x16x32_bf16 v[64:67], v[142:145], v[188:191], v[64:67]
	v_mfma_f32_16x16x32_bf16 v[60:63], v[150:153], v[188:191], v[60:63]
	v_mfma_f32_16x16x32_bf16 v[48:51], v[142:145], v[192:195], v[48:51]
	v_mfma_f32_16x16x32_bf16 v[44:47], v[150:153], v[192:195], v[44:47]
	v_mfma_f32_16x16x32_bf16 v[30:33], v[142:145], v[204:207], v[30:33]
	v_mfma_f32_16x16x32_bf16 v[26:29], v[150:153], v[204:207], v[26:29]
	v_mfma_f32_16x16x32_bf16 v[14:17], v[142:145], v[208:211], v[14:17]
	v_mfma_f32_16x16x32_bf16 v[10:13], v[150:153], v[208:211], v[10:13]
	v_mfma_f32_16x16x32_bf16 v[56:59], v[154:157], v[176:179], 0
	v_mfma_f32_16x16x32_bf16 v[52:55], v[168:171], v[176:179], 0
	v_mfma_f32_16x16x32_bf16 v[40:43], v[154:157], v[184:187], 0
	v_mfma_f32_16x16x32_bf16 v[36:39], v[168:171], v[184:187], 0
	v_mfma_f32_16x16x32_bf16 v[22:25], v[154:157], v[196:199], 0
	v_mfma_f32_16x16x32_bf16 v[18:21], v[168:171], v[196:199], 0
	v_mfma_f32_16x16x32_bf16 v[6:9], v[154:157], v[200:203], 0
	v_mfma_f32_16x16x32_bf16 v[2:5], v[168:171], v[200:203], 0
	v_mfma_f32_16x16x32_bf16 v[56:59], v[164:167], v[188:191], v[56:59]
	v_mfma_f32_16x16x32_bf16 v[52:55], v[172:175], v[188:191], v[52:55]
	v_mfma_f32_16x16x32_bf16 v[40:43], v[164:167], v[192:195], v[40:43]
	v_mfma_f32_16x16x32_bf16 v[36:39], v[172:175], v[192:195], v[36:39]
	v_mfma_f32_16x16x32_bf16 v[22:25], v[164:167], v[204:207], v[22:25]
	v_mfma_f32_16x16x32_bf16 v[18:21], v[172:175], v[204:207], v[18:21]
	v_mfma_f32_16x16x32_bf16 v[6:9], v[164:167], v[208:211], v[6:9]
	v_mfma_f32_16x16x32_bf16 v[2:5], v[172:175], v[208:211], v[2:5]
	s_setprio 0
	s_barrier
	s_add_i32 s25, 0, 0x18000
	s_add_i32 s30, 0, 0x1c000
	ds_read_b128 v[138:141], v1 offset:32768
	ds_read_b128 v[142:145], v160 offset:32768
	ds_read_b128 v[146:149], v1 offset:34816
	ds_read_b128 v[150:153], v160 offset:34816
	ds_read_b128 v[154:157], v1 offset:49152
	ds_read_b128 v[164:167], v160 offset:49152
	ds_read_b128 v[168:171], v1 offset:51200
	ds_read_b128 v[172:175], v160 offset:51200
	s_mov_b64 s[100:101], s[22:23]
	s_add_u32 s22, s22, 0x160000
	s_addc_u32 s23, s23, 0
	s_mov_b32 m0, s48
	ds_read_b128 v[176:179], v161 offset:32768
	ds_read_b128 v[184:187], v161 offset:34816
	ds_read_b128 v[188:191], v162 offset:32768
	ds_read_b128 v[192:195], v162 offset:34816
	ds_read_b128 v[196:199], v161 offset:36864
	ds_read_b128 v[200:203], v161 offset:38912
	ds_read_b128 v[204:207], v162 offset:36864
	ds_read_b128 v[208:211], v162 offset:38912
	global_load_lds_dwordx4 v136, s[22:23]
	s_mov_b32 m0, s49
	s_nop 0
	global_load_lds_dwordx4 v134, s[22:23]
	s_waitcnt vmcnt(8)
	s_waitcnt lgkmcnt(0)
	s_barrier
	s_setprio 1
	v_mfma_f32_16x16x32_bf16 v[128:131], v[138:141], v[176:179], v[128:131]
	v_mfma_f32_16x16x32_bf16 v[124:127], v[146:149], v[176:179], v[124:127]
	v_mfma_f32_16x16x32_bf16 v[112:115], v[138:141], v[184:187], v[112:115]
	v_mfma_f32_16x16x32_bf16 v[108:111], v[146:149], v[184:187], v[108:111]
	v_mfma_f32_16x16x32_bf16 v[96:99], v[138:141], v[196:199], v[96:99]
	v_mfma_f32_16x16x32_bf16 v[92:95], v[146:149], v[196:199], v[92:95]
	v_mfma_f32_16x16x32_bf16 v[80:83], v[138:141], v[200:203], v[80:83]
	v_mfma_f32_16x16x32_bf16 v[76:79], v[146:149], v[200:203], v[76:79]
	v_mfma_f32_16x16x32_bf16 v[128:131], v[142:145], v[188:191], v[128:131]
	v_mfma_f32_16x16x32_bf16 v[124:127], v[150:153], v[188:191], v[124:127]
	v_mfma_f32_16x16x32_bf16 v[112:115], v[142:145], v[192:195], v[112:115]
	v_mfma_f32_16x16x32_bf16 v[108:111], v[150:153], v[192:195], v[108:111]
	v_mfma_f32_16x16x32_bf16 v[96:99], v[142:145], v[204:207], v[96:99]
	v_mfma_f32_16x16x32_bf16 v[92:95], v[150:153], v[204:207], v[92:95]
	v_mfma_f32_16x16x32_bf16 v[80:83], v[142:145], v[208:211], v[80:83]
	v_mfma_f32_16x16x32_bf16 v[76:79], v[150:153], v[208:211], v[76:79]
	v_mfma_f32_16x16x32_bf16 v[120:123], v[154:157], v[176:179], v[120:123]
	v_mfma_f32_16x16x32_bf16 v[116:119], v[168:171], v[176:179], v[116:119]
	v_mfma_f32_16x16x32_bf16 v[104:107], v[154:157], v[184:187], v[104:107]
	v_mfma_f32_16x16x32_bf16 v[100:103], v[168:171], v[184:187], v[100:103]
	v_mfma_f32_16x16x32_bf16 v[88:91], v[154:157], v[196:199], v[88:91]
	v_mfma_f32_16x16x32_bf16 v[84:87], v[168:171], v[196:199], v[84:87]
	v_mfma_f32_16x16x32_bf16 v[72:75], v[154:157], v[200:203], v[72:75]
	v_mfma_f32_16x16x32_bf16 v[68:71], v[168:171], v[200:203], v[68:71]
	v_mfma_f32_16x16x32_bf16 v[120:123], v[164:167], v[188:191], v[120:123]
	v_mfma_f32_16x16x32_bf16 v[116:119], v[172:175], v[188:191], v[116:119]
	v_mfma_f32_16x16x32_bf16 v[104:107], v[164:167], v[192:195], v[104:107]
	v_mfma_f32_16x16x32_bf16 v[100:103], v[172:175], v[192:195], v[100:103]
	v_mfma_f32_16x16x32_bf16 v[88:91], v[164:167], v[204:207], v[88:91]
	v_mfma_f32_16x16x32_bf16 v[84:87], v[172:175], v[204:207], v[84:87]
	v_mfma_f32_16x16x32_bf16 v[72:75], v[164:167], v[208:211], v[72:75]
	v_mfma_f32_16x16x32_bf16 v[68:71], v[172:175], v[208:211], v[68:71]
	s_setprio 0
	s_barrier
	s_add_i32 s22, s25, s28
	s_add_i32 m0, s22, 0xffffff80
	ds_read_b128 v[176:179], v161 offset:49152
	ds_read_b128 v[184:187], v161 offset:51200
	ds_read_b128 v[188:191], v162 offset:49152
	ds_read_b128 v[192:195], v162 offset:51200
	ds_read_b128 v[196:199], v161 offset:53248
	ds_read_b128 v[200:203], v161 offset:55296
	ds_read_b128 v[204:207], v162 offset:53248
	ds_read_b128 v[208:211], v162 offset:55296
	global_load_lds_dwordx4 v34, s[18:19] offset:128
	s_add_i32 m0, s22, 0x1f80
	s_mov_b64 s[98:99], s[18:19]
	s_add_u32 s18, s18, 0x160080
	s_addc_u32 s19, s19, 0
	s_add_i32 s22, s30, s28
	global_load_lds_dwordx4 v132, s[98:99] offset:128
	s_mov_b32 m0, s22
	s_nop 0
	global_load_lds_dwordx4 v34, s[18:19]
	s_add_i32 m0, s22, 0x2000
	s_nop 0
	global_load_lds_dwordx4 v132, s[18:19]
	s_add_i32 m0, s53, 0xffffff80
	s_nop 0
	global_load_lds_dwordx4 v136, s[100:101] offset:128
	s_add_i32 m0, s54, 0xffffff80
	s_nop 0
	global_load_lds_dwordx4 v134, s[100:101] offset:128
	s_waitcnt vmcnt(8)
	s_waitcnt lgkmcnt(0)
	s_barrier
	s_setprio 1
	v_mfma_f32_16x16x32_bf16 v[64:67], v[138:141], v[176:179], v[64:67]
	v_mfma_f32_16x16x32_bf16 v[60:63], v[146:149], v[176:179], v[60:63]
	v_mfma_f32_16x16x32_bf16 v[48:51], v[138:141], v[184:187], v[48:51]
	v_mfma_f32_16x16x32_bf16 v[44:47], v[146:149], v[184:187], v[44:47]
	v_mfma_f32_16x16x32_bf16 v[30:33], v[138:141], v[196:199], v[30:33]
	v_mfma_f32_16x16x32_bf16 v[26:29], v[146:149], v[196:199], v[26:29]
	v_mfma_f32_16x16x32_bf16 v[14:17], v[138:141], v[200:203], v[14:17]
	v_mfma_f32_16x16x32_bf16 v[10:13], v[146:149], v[200:203], v[10:13]
	v_mfma_f32_16x16x32_bf16 v[64:67], v[142:145], v[188:191], v[64:67]
	v_mfma_f32_16x16x32_bf16 v[60:63], v[150:153], v[188:191], v[60:63]
	v_mfma_f32_16x16x32_bf16 v[48:51], v[142:145], v[192:195], v[48:51]
	v_mfma_f32_16x16x32_bf16 v[44:47], v[150:153], v[192:195], v[44:47]
	v_mfma_f32_16x16x32_bf16 v[30:33], v[142:145], v[204:207], v[30:33]
	v_mfma_f32_16x16x32_bf16 v[26:29], v[150:153], v[204:207], v[26:29]
	v_mfma_f32_16x16x32_bf16 v[14:17], v[142:145], v[208:211], v[14:17]
	v_mfma_f32_16x16x32_bf16 v[10:13], v[150:153], v[208:211], v[10:13]
	v_mfma_f32_16x16x32_bf16 v[56:59], v[154:157], v[176:179], v[56:59]
	v_mfma_f32_16x16x32_bf16 v[52:55], v[168:171], v[176:179], v[52:55]
	v_mfma_f32_16x16x32_bf16 v[40:43], v[154:157], v[184:187], v[40:43]
	v_mfma_f32_16x16x32_bf16 v[36:39], v[168:171], v[184:187], v[36:39]
	v_mfma_f32_16x16x32_bf16 v[22:25], v[154:157], v[196:199], v[22:25]
	v_mfma_f32_16x16x32_bf16 v[18:21], v[168:171], v[196:199], v[18:21]
	v_mfma_f32_16x16x32_bf16 v[6:9], v[154:157], v[200:203], v[6:9]
	v_mfma_f32_16x16x32_bf16 v[2:5], v[168:171], v[200:203], v[2:5]
	v_mfma_f32_16x16x32_bf16 v[56:59], v[164:167], v[188:191], v[56:59]
	v_mfma_f32_16x16x32_bf16 v[52:55], v[172:175], v[188:191], v[52:55]
	v_mfma_f32_16x16x32_bf16 v[40:43], v[164:167], v[192:195], v[40:43]
	v_mfma_f32_16x16x32_bf16 v[36:39], v[172:175], v[192:195], v[36:39]
	v_mfma_f32_16x16x32_bf16 v[22:25], v[164:167], v[204:207], v[22:25]
	v_mfma_f32_16x16x32_bf16 v[18:21], v[172:175], v[204:207], v[18:21]
	v_mfma_f32_16x16x32_bf16 v[6:9], v[164:167], v[208:211], v[6:9]
	v_mfma_f32_16x16x32_bf16 v[2:5], v[172:175], v[208:211], v[2:5]
	s_setprio 0
	s_barrier
	s_add_i32 s24, s24, 2
	s_add_u32 s8, s8, 0x100
	s_addc_u32 s9, s9, 0
	s_add_u32 s20, s20, 0x100
	s_addc_u32 s21, s21, 0
	s_cmpk_gt_u32 s24, 0x55
	s_cbranch_scc1 .Lpeel_done_P7
.LBB0_1195:
	s_add_u32 s18, s8, 0xffea0080
	s_addc_u32 s19, s9, -1
	s_add_i32 s25, 0, 0x10000
	s_cmpk_eq_i32 s24, 0x54
	s_cselect_b32 s23, s45, s19
	s_cselect_b32 s22, s44, s18
	s_cselect_b32 s19, s47, s21
	s_cselect_b32 s18, s46, s20
	s_add_i32 s34, 0, 0x14000
	ds_read_b128 v[138:141], v1
	ds_read_b128 v[142:145], v160
	ds_read_b128 v[146:149], v1 offset:2048
	ds_read_b128 v[150:153], v160 offset:2048
	ds_read_b128 v[154:157], v1 offset:16384
	ds_read_b128 v[164:167], v160 offset:16384
	ds_read_b128 v[168:171], v1 offset:18432
	ds_read_b128 v[172:175], v160 offset:18432
	s_add_i32 m0, s29, 0xc000
	ds_read_b128 v[176:179], v161
	ds_read_b128 v[184:187], v161 offset:2048
	ds_read_b128 v[188:191], v162
	ds_read_b128 v[192:195], v162 offset:2048
	ds_read_b128 v[196:199], v161 offset:4096
	ds_read_b128 v[200:203], v161 offset:6144
	ds_read_b128 v[204:207], v162 offset:4096
	ds_read_b128 v[208:211], v162 offset:6144
	global_load_lds_dwordx4 v136, s[8:9]
	s_add_i32 m0, s29, 0xe000
	s_nop 0
	global_load_lds_dwordx4 v134, s[8:9]
	s_waitcnt vmcnt(8)
	s_waitcnt lgkmcnt(0)
	s_barrier
	s_setprio 1
	v_mfma_f32_16x16x32_bf16 v[128:131], v[138:141], v[176:179], v[128:131]
	v_mfma_f32_16x16x32_bf16 v[124:127], v[146:149], v[176:179], v[124:127]
	v_mfma_f32_16x16x32_bf16 v[112:115], v[138:141], v[184:187], v[112:115]
	v_mfma_f32_16x16x32_bf16 v[108:111], v[146:149], v[184:187], v[108:111]
	v_mfma_f32_16x16x32_bf16 v[96:99], v[138:141], v[196:199], v[96:99]
	v_mfma_f32_16x16x32_bf16 v[92:95], v[146:149], v[196:199], v[92:95]
	v_mfma_f32_16x16x32_bf16 v[80:83], v[138:141], v[200:203], v[80:83]
	v_mfma_f32_16x16x32_bf16 v[76:79], v[146:149], v[200:203], v[76:79]
	v_mfma_f32_16x16x32_bf16 v[128:131], v[142:145], v[188:191], v[128:131]
	v_mfma_f32_16x16x32_bf16 v[124:127], v[150:153], v[188:191], v[124:127]
	v_mfma_f32_16x16x32_bf16 v[112:115], v[142:145], v[192:195], v[112:115]
	v_mfma_f32_16x16x32_bf16 v[108:111], v[150:153], v[192:195], v[108:111]
	v_mfma_f32_16x16x32_bf16 v[96:99], v[142:145], v[204:207], v[96:99]
	v_mfma_f32_16x16x32_bf16 v[92:95], v[150:153], v[204:207], v[92:95]
	v_mfma_f32_16x16x32_bf16 v[80:83], v[142:145], v[208:211], v[80:83]
	v_mfma_f32_16x16x32_bf16 v[76:79], v[150:153], v[208:211], v[76:79]
	v_mfma_f32_16x16x32_bf16 v[120:123], v[154:157], v[176:179], v[120:123]
	v_mfma_f32_16x16x32_bf16 v[116:119], v[168:171], v[176:179], v[116:119]
	v_mfma_f32_16x16x32_bf16 v[104:107], v[154:157], v[184:187], v[104:107]
	v_mfma_f32_16x16x32_bf16 v[100:103], v[168:171], v[184:187], v[100:103]
	v_mfma_f32_16x16x32_bf16 v[88:91], v[154:157], v[196:199], v[88:91]
	v_mfma_f32_16x16x32_bf16 v[84:87], v[168:171], v[196:199], v[84:87]
	v_mfma_f32_16x16x32_bf16 v[72:75], v[154:157], v[200:203], v[72:75]
	v_mfma_f32_16x16x32_bf16 v[68:71], v[168:171], v[200:203], v[68:71]
	v_mfma_f32_16x16x32_bf16 v[120:123], v[164:167], v[188:191], v[120:123]
	v_mfma_f32_16x16x32_bf16 v[116:119], v[172:175], v[188:191], v[116:119]
	v_mfma_f32_16x16x32_bf16 v[104:107], v[164:167], v[192:195], v[104:107]
	v_mfma_f32_16x16x32_bf16 v[100:103], v[172:175], v[192:195], v[100:103]
	v_mfma_f32_16x16x32_bf16 v[88:91], v[164:167], v[204:207], v[88:91]
	v_mfma_f32_16x16x32_bf16 v[84:87], v[172:175], v[204:207], v[84:87]
	v_mfma_f32_16x16x32_bf16 v[72:75], v[164:167], v[208:211], v[72:75]
	v_mfma_f32_16x16x32_bf16 v[68:71], v[172:175], v[208:211], v[68:71]
	s_setprio 0
	s_barrier
	s_add_i32 s25, s25, s28
	s_mov_b32 m0, s25
	ds_read_b128 v[176:179], v161 offset:16384
	ds_read_b128 v[184:187], v161 offset:18432
	ds_read_b128 v[188:191], v162 offset:16384
	ds_read_b128 v[192:195], v162 offset:18432
	ds_read_b128 v[196:199], v161 offset:20480
	ds_read_b128 v[200:203], v161 offset:22528
	ds_read_b128 v[204:207], v162 offset:20480
	ds_read_b128 v[208:211], v162 offset:22528
	global_load_lds_dwordx4 v34, s[18:19]
	s_add_i32 m0, s25, 0x2000
	s_add_u32 s30, s18, 0x160000
	s_addc_u32 s31, s19, 0
	s_add_i32 s25, s34, s28
	global_load_lds_dwordx4 v132, s[18:19]
	s_mov_b32 m0, s25
	s_nop 0
	global_load_lds_dwordx4 v34, s[30:31]
	s_add_i32 m0, s25, 0x2000
	s_nop 0
	global_load_lds_dwordx4 v132, s[30:31]
	s_mov_b32 m0, s29
	s_nop 0
	global_load_lds_dwordx4 v136, s[22:23]
	s_mov_b32 m0, s33
	s_nop 0
	global_load_lds_dwordx4 v134, s[22:23]
	s_waitcnt vmcnt(8)
	s_waitcnt lgkmcnt(0)
	s_barrier
	s_setprio 1
	v_mfma_f32_16x16x32_bf16 v[64:67], v[138:141], v[176:179], v[64:67]
	v_mfma_f32_16x16x32_bf16 v[60:63], v[146:149], v[176:179], v[60:63]
	v_mfma_f32_16x16x32_bf16 v[48:51], v[138:141], v[184:187], v[48:51]
	v_mfma_f32_16x16x32_bf16 v[44:47], v[146:149], v[184:187], v[44:47]
	v_mfma_f32_16x16x32_bf16 v[30:33], v[138:141], v[196:199], v[30:33]
	v_mfma_f32_16x16x32_bf16 v[26:29], v[146:149], v[196:199], v[26:29]
	v_mfma_f32_16x16x32_bf16 v[14:17], v[138:141], v[200:203], v[14:17]
	v_mfma_f32_16x16x32_bf16 v[10:13], v[146:149], v[200:203], v[10:13]
	v_mfma_f32_16x16x32_bf16 v[64:67], v[142:145], v[188:191], v[64:67]
	v_mfma_f32_16x16x32_bf16 v[60:63], v[150:153], v[188:191], v[60:63]
	v_mfma_f32_16x16x32_bf16 v[48:51], v[142:145], v[192:195], v[48:51]
	v_mfma_f32_16x16x32_bf16 v[44:47], v[150:153], v[192:195], v[44:47]
	v_mfma_f32_16x16x32_bf16 v[30:33], v[142:145], v[204:207], v[30:33]
	v_mfma_f32_16x16x32_bf16 v[26:29], v[150:153], v[204:207], v[26:29]
	v_mfma_f32_16x16x32_bf16 v[14:17], v[142:145], v[208:211], v[14:17]
	v_mfma_f32_16x16x32_bf16 v[10:13], v[150:153], v[208:211], v[10:13]
	v_mfma_f32_16x16x32_bf16 v[56:59], v[154:157], v[176:179], v[56:59]
	v_mfma_f32_16x16x32_bf16 v[52:55], v[168:171], v[176:179], v[52:55]
	v_mfma_f32_16x16x32_bf16 v[40:43], v[154:157], v[184:187], v[40:43]
	v_mfma_f32_16x16x32_bf16 v[36:39], v[168:171], v[184:187], v[36:39]
	v_mfma_f32_16x16x32_bf16 v[22:25], v[154:157], v[196:199], v[22:25]
	v_mfma_f32_16x16x32_bf16 v[18:21], v[168:171], v[196:199], v[18:21]
	v_mfma_f32_16x16x32_bf16 v[6:9], v[154:157], v[200:203], v[6:9]
	v_mfma_f32_16x16x32_bf16 v[2:5], v[168:171], v[200:203], v[2:5]
	v_mfma_f32_16x16x32_bf16 v[56:59], v[164:167], v[188:191], v[56:59]
	v_mfma_f32_16x16x32_bf16 v[52:55], v[172:175], v[188:191], v[52:55]
	v_mfma_f32_16x16x32_bf16 v[40:43], v[164:167], v[192:195], v[40:43]
	v_mfma_f32_16x16x32_bf16 v[36:39], v[172:175], v[192:195], v[36:39]
	v_mfma_f32_16x16x32_bf16 v[22:25], v[164:167], v[204:207], v[22:25]
	v_mfma_f32_16x16x32_bf16 v[18:21], v[172:175], v[204:207], v[18:21]
	v_mfma_f32_16x16x32_bf16 v[6:9], v[164:167], v[208:211], v[6:9]
	v_mfma_f32_16x16x32_bf16 v[2:5], v[172:175], v[208:211], v[2:5]
	s_setprio 0
	s_barrier
	s_add_i32 s25, 0, 0x18000
	s_add_i32 s30, 0, 0x1c000
	ds_read_b128 v[138:141], v1 offset:32768
	ds_read_b128 v[142:145], v160 offset:32768
	ds_read_b128 v[146:149], v1 offset:34816
	ds_read_b128 v[150:153], v160 offset:34816
	ds_read_b128 v[154:157], v1 offset:49152
	ds_read_b128 v[164:167], v160 offset:49152
	ds_read_b128 v[168:171], v1 offset:51200
	ds_read_b128 v[172:175], v160 offset:51200
	s_mov_b64 s[100:101], s[22:23]
	s_add_u32 s22, s22, 0x160000
	s_addc_u32 s23, s23, 0
	s_mov_b32 m0, s48
	ds_read_b128 v[176:179], v161 offset:32768
	ds_read_b128 v[184:187], v161 offset:34816
	ds_read_b128 v[188:191], v162 offset:32768
	ds_read_b128 v[192:195], v162 offset:34816
	ds_read_b128 v[196:199], v161 offset:36864
	ds_read_b128 v[200:203], v161 offset:38912
	ds_read_b128 v[204:207], v162 offset:36864
	ds_read_b128 v[208:211], v162 offset:38912
	global_load_lds_dwordx4 v136, s[22:23]
	s_mov_b32 m0, s49
	s_nop 0
	global_load_lds_dwordx4 v134, s[22:23]
	s_waitcnt vmcnt(8)
	s_waitcnt lgkmcnt(0)
	s_barrier
	s_setprio 1
	v_mfma_f32_16x16x32_bf16 v[128:131], v[138:141], v[176:179], v[128:131]
	v_mfma_f32_16x16x32_bf16 v[124:127], v[146:149], v[176:179], v[124:127]
	v_mfma_f32_16x16x32_bf16 v[112:115], v[138:141], v[184:187], v[112:115]
	v_mfma_f32_16x16x32_bf16 v[108:111], v[146:149], v[184:187], v[108:111]
	v_mfma_f32_16x16x32_bf16 v[96:99], v[138:141], v[196:199], v[96:99]
	v_mfma_f32_16x16x32_bf16 v[92:95], v[146:149], v[196:199], v[92:95]
	v_mfma_f32_16x16x32_bf16 v[80:83], v[138:141], v[200:203], v[80:83]
	v_mfma_f32_16x16x32_bf16 v[76:79], v[146:149], v[200:203], v[76:79]
	v_mfma_f32_16x16x32_bf16 v[128:131], v[142:145], v[188:191], v[128:131]
	v_mfma_f32_16x16x32_bf16 v[124:127], v[150:153], v[188:191], v[124:127]
	v_mfma_f32_16x16x32_bf16 v[112:115], v[142:145], v[192:195], v[112:115]
	v_mfma_f32_16x16x32_bf16 v[108:111], v[150:153], v[192:195], v[108:111]
	v_mfma_f32_16x16x32_bf16 v[96:99], v[142:145], v[204:207], v[96:99]
	v_mfma_f32_16x16x32_bf16 v[92:95], v[150:153], v[204:207], v[92:95]
	v_mfma_f32_16x16x32_bf16 v[80:83], v[142:145], v[208:211], v[80:83]
	v_mfma_f32_16x16x32_bf16 v[76:79], v[150:153], v[208:211], v[76:79]
	v_mfma_f32_16x16x32_bf16 v[120:123], v[154:157], v[176:179], v[120:123]
	v_mfma_f32_16x16x32_bf16 v[116:119], v[168:171], v[176:179], v[116:119]
	v_mfma_f32_16x16x32_bf16 v[104:107], v[154:157], v[184:187], v[104:107]
	v_mfma_f32_16x16x32_bf16 v[100:103], v[168:171], v[184:187], v[100:103]
	v_mfma_f32_16x16x32_bf16 v[88:91], v[154:157], v[196:199], v[88:91]
	v_mfma_f32_16x16x32_bf16 v[84:87], v[168:171], v[196:199], v[84:87]
	v_mfma_f32_16x16x32_bf16 v[72:75], v[154:157], v[200:203], v[72:75]
	v_mfma_f32_16x16x32_bf16 v[68:71], v[168:171], v[200:203], v[68:71]
	v_mfma_f32_16x16x32_bf16 v[120:123], v[164:167], v[188:191], v[120:123]
	v_mfma_f32_16x16x32_bf16 v[116:119], v[172:175], v[188:191], v[116:119]
	v_mfma_f32_16x16x32_bf16 v[104:107], v[164:167], v[192:195], v[104:107]
	v_mfma_f32_16x16x32_bf16 v[100:103], v[172:175], v[192:195], v[100:103]
	v_mfma_f32_16x16x32_bf16 v[88:91], v[164:167], v[204:207], v[88:91]
	v_mfma_f32_16x16x32_bf16 v[84:87], v[172:175], v[204:207], v[84:87]
	v_mfma_f32_16x16x32_bf16 v[72:75], v[164:167], v[208:211], v[72:75]
	v_mfma_f32_16x16x32_bf16 v[68:71], v[172:175], v[208:211], v[68:71]
	s_setprio 0
	s_barrier
	s_add_i32 s22, s25, s28
	s_add_i32 m0, s22, 0xffffff80
	ds_read_b128 v[176:179], v161 offset:49152
	ds_read_b128 v[184:187], v161 offset:51200
	ds_read_b128 v[188:191], v162 offset:49152
	ds_read_b128 v[192:195], v162 offset:51200
	ds_read_b128 v[196:199], v161 offset:53248
	ds_read_b128 v[200:203], v161 offset:55296
	ds_read_b128 v[204:207], v162 offset:53248
	ds_read_b128 v[208:211], v162 offset:55296
	global_load_lds_dwordx4 v34, s[18:19] offset:128
	s_add_i32 m0, s22, 0x1f80
	s_mov_b64 s[98:99], s[18:19]
	s_add_u32 s18, s18, 0x160080
	s_addc_u32 s19, s19, 0
	s_add_i32 s22, s30, s28
	global_load_lds_dwordx4 v132, s[98:99] offset:128
	s_mov_b32 m0, s22
	s_nop 0
	global_load_lds_dwordx4 v34, s[18:19]
	s_add_i32 m0, s22, 0x2000
	s_nop 0
	global_load_lds_dwordx4 v132, s[18:19]
	s_add_i32 m0, s53, 0xffffff80
	s_nop 0
	global_load_lds_dwordx4 v136, s[100:101] offset:128
	s_add_i32 m0, s54, 0xffffff80
	s_nop 0
	global_load_lds_dwordx4 v134, s[100:101] offset:128
	s_waitcnt vmcnt(8)
	s_waitcnt lgkmcnt(0)
	s_barrier
	s_setprio 1
	v_mfma_f32_16x16x32_bf16 v[64:67], v[138:141], v[176:179], v[64:67]
	v_mfma_f32_16x16x32_bf16 v[60:63], v[146:149], v[176:179], v[60:63]
	v_mfma_f32_16x16x32_bf16 v[48:51], v[138:141], v[184:187], v[48:51]
	v_mfma_f32_16x16x32_bf16 v[44:47], v[146:149], v[184:187], v[44:47]
	v_mfma_f32_16x16x32_bf16 v[30:33], v[138:141], v[196:199], v[30:33]
	v_mfma_f32_16x16x32_bf16 v[26:29], v[146:149], v[196:199], v[26:29]
	v_mfma_f32_16x16x32_bf16 v[14:17], v[138:141], v[200:203], v[14:17]
	v_mfma_f32_16x16x32_bf16 v[10:13], v[146:149], v[200:203], v[10:13]
	v_mfma_f32_16x16x32_bf16 v[64:67], v[142:145], v[188:191], v[64:67]
	v_mfma_f32_16x16x32_bf16 v[60:63], v[150:153], v[188:191], v[60:63]
	v_mfma_f32_16x16x32_bf16 v[48:51], v[142:145], v[192:195], v[48:51]
	v_mfma_f32_16x16x32_bf16 v[44:47], v[150:153], v[192:195], v[44:47]
	v_mfma_f32_16x16x32_bf16 v[30:33], v[142:145], v[204:207], v[30:33]
	v_mfma_f32_16x16x32_bf16 v[26:29], v[150:153], v[204:207], v[26:29]
	v_mfma_f32_16x16x32_bf16 v[14:17], v[142:145], v[208:211], v[14:17]
	v_mfma_f32_16x16x32_bf16 v[10:13], v[150:153], v[208:211], v[10:13]
	v_mfma_f32_16x16x32_bf16 v[56:59], v[154:157], v[176:179], v[56:59]
	v_mfma_f32_16x16x32_bf16 v[52:55], v[168:171], v[176:179], v[52:55]
	v_mfma_f32_16x16x32_bf16 v[40:43], v[154:157], v[184:187], v[40:43]
	v_mfma_f32_16x16x32_bf16 v[36:39], v[168:171], v[184:187], v[36:39]
	v_mfma_f32_16x16x32_bf16 v[22:25], v[154:157], v[196:199], v[22:25]
	v_mfma_f32_16x16x32_bf16 v[18:21], v[168:171], v[196:199], v[18:21]
	v_mfma_f32_16x16x32_bf16 v[6:9], v[154:157], v[200:203], v[6:9]
	v_mfma_f32_16x16x32_bf16 v[2:5], v[168:171], v[200:203], v[2:5]
	v_mfma_f32_16x16x32_bf16 v[56:59], v[164:167], v[188:191], v[56:59]
	v_mfma_f32_16x16x32_bf16 v[52:55], v[172:175], v[188:191], v[52:55]
	v_mfma_f32_16x16x32_bf16 v[40:43], v[164:167], v[192:195], v[40:43]
	v_mfma_f32_16x16x32_bf16 v[36:39], v[172:175], v[192:195], v[36:39]
	v_mfma_f32_16x16x32_bf16 v[22:25], v[164:167], v[204:207], v[22:25]
	v_mfma_f32_16x16x32_bf16 v[18:21], v[172:175], v[204:207], v[18:21]
	v_mfma_f32_16x16x32_bf16 v[6:9], v[164:167], v[208:211], v[6:9]
	v_mfma_f32_16x16x32_bf16 v[2:5], v[172:175], v[208:211], v[2:5]
	s_setprio 0
	s_barrier
	s_add_i32 s24, s24, 2
	s_add_u32 s8, s8, 0x100
	s_addc_u32 s9, s9, 0
	s_add_u32 s20, s20, 0x100
	s_addc_u32 s21, s21, 0
	s_cmpk_gt_u32 s24, 0x55
	s_cbranch_scc0 .LBB0_1195
